# SP2 GEMM loops phase 4: +kstep 64-bit VALU adds folded into LDS-DMA immediate offset (M0 compensated)
# speedup vs baseline: 1.0033x; 1.0033x over previous
; #define PG8_STAGE(bufoff, gbase, voff) do { _Pragma("unroll") for (int _i = 0; _i < 2; ++_i) \
;         __builtin_amdgcn_global_load_lds((const unsigned*)((const char*)(gbase) + (voff)[_i]), (LAS unsigned*)(lds + (bufoff) + ldsw + _i * 8192), 16, 0, 0); } while (0)
; #define PG8_LDA(dst, b, h) do { _Pragma("unroll") for (int m = 0; m < 4; ++m) _Pragma("unroll") for (int k = 0; k < 2; ++k) dst[m][k] = *(const LAS bf16x8*)(lds + PG8_SA(b, h) + aoff + m * 2048 + k * 1024); } while (0)
; #define PG8_LDB(dst, b, h) do { _Pragma("unroll") for (int n = 0; n < 2; ++n) _Pragma("unroll") for (int k = 0; k < 2; ++k) dst[n][k] = *(const LAS bf16x8*)(lds + PG8_SB(b, h) + boff + n * 2048 + k * 1024); } while (0)
; #define PG8_WAIT_V(n) asm volatile("s_waitcnt vmcnt(" #n ")" ::: "memory")
; #define PG8_WAIT_L(n) asm volatile("s_waitcnt lgkmcnt(" #n ")" ::: "memory")
; #define PG8_BAR __builtin_amdgcn_s_barrier()
; #define PG8_SCHED __builtin_amdgcn_sched_barrier(0)
;     ...
;         for (int t = 0; t < nt; t += 2) {
;             const bool last = (t == nt - 2);
;             const char* a1 = cA + (size_t)(t + 1) * kstep;
;             const char* a2 = last ? nA : cA + (size_t)(t + 2) * kstep; const char* b2 = last ? nB : cB + (size_t)(t + 2) * kstep;
;             const char* a3 = a2 + kstep; const char* b3 = b2 + kstep;
;             if constexpr (SP2) {
;             PG8_LDB(B0, 0, 0); PG8_LDB(B1, 0, 1); PG8_SCHED; PG8_LDA(At, 0, 0); PG8_STAGE(PG8_SA(1, 1), a1 + hstepA, voffA);
;             PG8_WAIT_V(8); PG8_WAIT_L(0); PG8_BAR; PG8_MMA(0, 0, At, B0); PG8_MMA(0, 1, At, B1); PG8_BAR; PG8_SCHED;
;             PG8_LDA(At, 0, 1); PG8_STAGE(PG8_SB(0, 0), b2, voffB); PG8_STAGE(PG8_SB(0, 1), b2 + hstepB, voffB); PG8_STAGE(PG8_SA(0, 0), a2, voffA);
;             PG8_WAIT_V(8); PG8_WAIT_L(0); PG8_BAR; PG8_MMA(1, 0, At, B0); PG8_MMA(1, 1, At, B1); PG8_BAR; PG8_SCHED;
.LBB0_165:
	s_add_i32 s62, 0, 0x10000
	v_lshl_add_u64 v[162:163], v[148:149], 0, s[38:39]
	s_cmpk_eq_i32 s38, 0xf00
	v_lshl_add_u64 v[162:163], v[162:163], 0, s[4:5]
	s_cselect_b64 vcc, -1, 0
	s_add_i32 s63, 0, 0x14000
	v_lshl_add_u64 v[178:179], v[154:155], 0, s[38:39]
	v_cndmask_b32_e32 v231, v163, v145, vcc
	v_cndmask_b32_e32 v230, v162, v144, vcc
	ds_read_b128 v[162:165], v246
	ds_read_b128 v[166:169], v246 offset:1024
	ds_read_b128 v[170:173], v246 offset:2048
	ds_read_b128 v[174:177], v246 offset:3072
	v_cndmask_b32_e32 v233, v179, v147, vcc
	v_cndmask_b32_e32 v232, v178, v146, vcc
	ds_read_b128 v[178:181], v247
	ds_read_b128 v[182:185], v247 offset:1024
	ds_read_b128 v[186:189], v247 offset:2048
	ds_read_b128 v[190:193], v247 offset:3072
	v_lshl_add_u64 v[234:235], v[152:153], 0, s[38:39]
	s_add_i32 m0, s3, 0xc000
	ds_read_b128 v[194:197], v160
	ds_read_b128 v[198:201], v160 offset:1024
	ds_read_b128 v[202:205], v160 offset:2048
	ds_read_b128 v[206:209], v160 offset:3072
	ds_read_b128 v[210:213], v160 offset:4096
	ds_read_b128 v[214:217], v160 offset:5120
	ds_read_b128 v[218:221], v160 offset:6144
	ds_read_b128 v[226:229], v160 offset:7168
	global_load_lds_dwordx4 v[234:235], off
	v_lshl_add_u64 v[234:235], v[150:151], 0, s[38:39]
	s_add_i32 m0, s3, 0xe000
	s_nop 0
	global_load_lds_dwordx4 v[234:235], off
	s_waitcnt vmcnt(8)
	s_waitcnt lgkmcnt(0)
	s_barrier
	s_setprio 1
	v_mfma_i32_16x16x64_i8 v[128:131], v[162:165], v[194:197], v[128:131]
	v_mfma_i32_16x16x64_i8 v[124:127], v[170:173], v[194:197], v[124:127]
	v_mfma_i32_16x16x64_i8 v[112:115], v[162:165], v[202:205], v[112:115]
	v_mfma_i32_16x16x64_i8 v[108:111], v[170:173], v[202:205], v[108:111]
	v_mfma_i32_16x16x64_i8 v[96:99], v[162:165], v[210:213], v[96:99]
	v_mfma_i32_16x16x64_i8 v[92:95], v[170:173], v[210:213], v[92:95]
	v_mfma_i32_16x16x64_i8 v[80:83], v[162:165], v[218:221], v[80:83]
	v_mfma_i32_16x16x64_i8 v[76:79], v[170:173], v[218:221], v[76:79]
	v_mfma_i32_16x16x64_i8 v[128:131], v[166:169], v[198:201], v[128:131]
	v_mfma_i32_16x16x64_i8 v[124:127], v[174:177], v[198:201], v[124:127]
	v_mfma_i32_16x16x64_i8 v[112:115], v[166:169], v[206:209], v[112:115]
	v_mfma_i32_16x16x64_i8 v[108:111], v[174:177], v[206:209], v[108:111]
	v_mfma_i32_16x16x64_i8 v[96:99], v[166:169], v[214:217], v[96:99]
	v_mfma_i32_16x16x64_i8 v[92:95], v[174:177], v[214:217], v[92:95]
	v_mfma_i32_16x16x64_i8 v[80:83], v[166:169], v[226:229], v[80:83]
	v_mfma_i32_16x16x64_i8 v[76:79], v[174:177], v[226:229], v[76:79]
	v_mfma_i32_16x16x64_i8 v[120:123], v[178:181], v[194:197], v[120:123]
	v_mfma_i32_16x16x64_i8 v[116:119], v[186:189], v[194:197], v[116:119]
	v_mfma_i32_16x16x64_i8 v[104:107], v[178:181], v[202:205], v[104:107]
	v_mfma_i32_16x16x64_i8 v[100:103], v[186:189], v[202:205], v[100:103]
	v_mfma_i32_16x16x64_i8 v[88:91], v[178:181], v[210:213], v[88:91]
	v_mfma_i32_16x16x64_i8 v[84:87], v[186:189], v[210:213], v[84:87]
	v_mfma_i32_16x16x64_i8 v[72:75], v[178:181], v[218:221], v[72:75]
	v_mfma_i32_16x16x64_i8 v[68:71], v[186:189], v[218:221], v[68:71]
	v_mfma_i32_16x16x64_i8 v[120:123], v[182:185], v[198:201], v[120:123]
	v_mfma_i32_16x16x64_i8 v[116:119], v[190:193], v[198:201], v[116:119]
	v_mfma_i32_16x16x64_i8 v[104:107], v[182:185], v[206:209], v[104:107]
	v_mfma_i32_16x16x64_i8 v[100:103], v[190:193], v[206:209], v[100:103]
	v_mfma_i32_16x16x64_i8 v[88:91], v[182:185], v[214:217], v[88:91]
	v_mfma_i32_16x16x64_i8 v[84:87], v[190:193], v[214:217], v[84:87]
	v_mfma_i32_16x16x64_i8 v[72:75], v[182:185], v[226:229], v[72:75]
	v_mfma_i32_16x16x64_i8 v[68:71], v[190:193], v[226:229], v[68:71]
	s_setprio 0
	s_barrier
	s_add_i32 s62, s62, s2
	v_lshl_add_u64 v[234:235], v[232:233], 0, v[2:3]
	s_mov_b32 m0, s62
	ds_read_b128 v[194:197], v160 offset:16384
	ds_read_b128 v[198:201], v160 offset:17408
	ds_read_b128 v[202:205], v160 offset:18432
	ds_read_b128 v[206:209], v160 offset:19456
	ds_read_b128 v[210:213], v160 offset:20480
	ds_read_b128 v[214:217], v160 offset:21504
	ds_read_b128 v[218:221], v160 offset:22528
	ds_read_b128 v[226:229], v160 offset:23552
	global_load_lds_dwordx4 v[234:235], off
	v_lshl_add_u64 v[236:237], v[232:233], 0, v[134:135]
	s_add_i32 m0, s62, 0x2000
	v_lshl_add_u64 v[232:233], v[232:233], 0, v[138:139]
	s_add_i32 s62, s63, s2
	global_load_lds_dwordx4 v[236:237], off
	v_lshl_add_u64 v[238:239], v[232:233], 0, v[2:3]
	s_mov_b32 m0, s62
	v_lshl_add_u64 v[232:233], v[232:233], 0, v[134:135]
	global_load_lds_dwordx4 v[238:239], off
	s_add_i32 m0, s62, 0x2000
	v_lshl_add_u64 v[240:241], v[230:231], 0, v[0:1]
	global_load_lds_dwordx4 v[232:233], off
	s_mov_b32 m0, s3
	v_lshl_add_u64 v[242:243], v[230:231], 0, v[132:133]
	global_load_lds_dwordx4 v[240:241], off
	s_mov_b32 m0, s8
	s_nop 0
	global_load_lds_dwordx4 v[242:243], off
	s_waitcnt vmcnt(8)
	s_waitcnt lgkmcnt(0)
	s_barrier
; #define PG8_STAGE(bufoff, gbase, voff) do { _Pragma("unroll") for (int _i = 0; _i < 2; ++_i) \
;         __builtin_amdgcn_global_load_lds((const unsigned*)((const char*)(gbase) + (voff)[_i]), (LAS unsigned*)(lds + (bufoff) + ldsw + _i * 8192), 16, 0, 0); } while (0)
; #define PG8_LDA(dst, b, h) do { _Pragma("unroll") for (int m = 0; m < 4; ++m) _Pragma("unroll") for (int k = 0; k < 2; ++k) dst[m][k] = *(const LAS bf16x8*)(lds + PG8_SA(b, h) + aoff + m * 2048 + k * 1024); } while (0)
; #define PG8_LDB(dst, b, h) do { _Pragma("unroll") for (int n = 0; n < 2; ++n) _Pragma("unroll") for (int k = 0; k < 2; ++k) dst[n][k] = *(const LAS bf16x8*)(lds + PG8_SB(b, h) + boff + n * 2048 + k * 1024); } while (0)
; #define PG8_WAIT_V(n) asm volatile("s_waitcnt vmcnt(" #n ")" ::: "memory")
; #define PG8_WAIT_L(n) asm volatile("s_waitcnt lgkmcnt(" #n ")" ::: "memory")
; #define PG8_BAR __builtin_amdgcn_s_barrier()
; #define PG8_SCHED __builtin_amdgcn_sched_barrier(0)
;     ...
;             PG8_WAIT_V(8); PG8_WAIT_L(0); PG8_BAR; PG8_MMA(1, 0, At, B0); PG8_MMA(1, 1, At, B1); PG8_BAR; PG8_SCHED;
;             PG8_LDB(B0, 1, 0); PG8_LDB(B1, 1, 1); PG8_SCHED; PG8_LDA(At, 1, 0); PG8_STAGE(PG8_SA(0, 1), a2 + hstepA, voffA);
;             PG8_WAIT_V(8); PG8_WAIT_L(0); PG8_BAR; PG8_MMA(0, 0, At, B0); PG8_MMA(0, 1, At, B1); PG8_BAR; PG8_SCHED;
;             PG8_LDA(At, 1, 1); PG8_STAGE(PG8_SB(1, 0), b3, voffB); PG8_STAGE(PG8_SB(1, 1), b3 + hstepB, voffB); PG8_STAGE(PG8_SA(1, 0), a3, voffA);
	s_setprio 1
	v_mfma_i32_16x16x64_i8 v[64:67], v[162:165], v[194:197], v[64:67]
	v_mfma_i32_16x16x64_i8 v[60:63], v[170:173], v[194:197], v[60:63]
	v_mfma_i32_16x16x64_i8 v[48:51], v[162:165], v[202:205], v[48:51]
	v_mfma_i32_16x16x64_i8 v[44:47], v[170:173], v[202:205], v[44:47]
	v_mfma_i32_16x16x64_i8 v[32:35], v[162:165], v[210:213], v[32:35]
	v_mfma_i32_16x16x64_i8 v[28:31], v[170:173], v[210:213], v[28:31]
	v_mfma_i32_16x16x64_i8 v[16:19], v[162:165], v[218:221], v[16:19]
	v_mfma_i32_16x16x64_i8 v[12:15], v[170:173], v[218:221], v[12:15]
	v_mfma_i32_16x16x64_i8 v[64:67], v[166:169], v[198:201], v[64:67]
	v_mfma_i32_16x16x64_i8 v[60:63], v[174:177], v[198:201], v[60:63]
	v_mfma_i32_16x16x64_i8 v[48:51], v[166:169], v[206:209], v[48:51]
	v_mfma_i32_16x16x64_i8 v[44:47], v[174:177], v[206:209], v[44:47]
	v_mfma_i32_16x16x64_i8 v[32:35], v[166:169], v[214:217], v[32:35]
	v_mfma_i32_16x16x64_i8 v[28:31], v[174:177], v[214:217], v[28:31]
	v_mfma_i32_16x16x64_i8 v[16:19], v[166:169], v[226:229], v[16:19]
	v_mfma_i32_16x16x64_i8 v[12:15], v[174:177], v[226:229], v[12:15]
	v_mfma_i32_16x16x64_i8 v[56:59], v[178:181], v[194:197], v[56:59]
	v_mfma_i32_16x16x64_i8 v[52:55], v[186:189], v[194:197], v[52:55]
	v_mfma_i32_16x16x64_i8 v[40:43], v[178:181], v[202:205], v[40:43]
	v_mfma_i32_16x16x64_i8 v[36:39], v[186:189], v[202:205], v[36:39]
	v_mfma_i32_16x16x64_i8 v[24:27], v[178:181], v[210:213], v[24:27]
	v_mfma_i32_16x16x64_i8 v[20:23], v[186:189], v[210:213], v[20:23]
	v_mfma_i32_16x16x64_i8 v[8:11], v[178:181], v[218:221], v[8:11]
	v_mfma_i32_16x16x64_i8 v[4:7], v[186:189], v[218:221], v[4:7]
	v_mfma_i32_16x16x64_i8 v[56:59], v[182:185], v[198:201], v[56:59]
	v_mfma_i32_16x16x64_i8 v[52:55], v[190:193], v[198:201], v[52:55]
	v_mfma_i32_16x16x64_i8 v[40:43], v[182:185], v[206:209], v[40:43]
	v_mfma_i32_16x16x64_i8 v[36:39], v[190:193], v[206:209], v[36:39]
	v_mfma_i32_16x16x64_i8 v[24:27], v[182:185], v[214:217], v[24:27]
	v_mfma_i32_16x16x64_i8 v[20:23], v[190:193], v[214:217], v[20:23]
	v_mfma_i32_16x16x64_i8 v[8:11], v[182:185], v[226:229], v[8:11]
	v_mfma_i32_16x16x64_i8 v[4:7], v[190:193], v[226:229], v[4:7]
	s_setprio 0
	s_barrier
	s_add_i32 s62, 0, 0x18000
	s_add_i32 s63, 0, 0x1c000
	ds_read_b128 v[162:165], v248
	ds_read_b128 v[166:169], v248 offset:1024
	ds_read_b128 v[170:173], v248 offset:2048
	ds_read_b128 v[174:177], v248 offset:3072
	ds_read_b128 v[178:181], v249
	ds_read_b128 v[182:185], v249 offset:1024
	ds_read_b128 v[186:189], v249 offset:2048
	ds_read_b128 v[190:193], v249 offset:3072
	v_lshl_add_u64 v[230:231], v[230:231], 0, v[136:137]
	s_mov_b32 m0, s9
	v_lshl_add_u64 v[244:245], v[230:231], 0, v[0:1]
	ds_read_b128 v[194:197], v160 offset:32768
	ds_read_b128 v[198:201], v160 offset:33792
	ds_read_b128 v[202:205], v160 offset:34816
	ds_read_b128 v[206:209], v160 offset:35840
	ds_read_b128 v[210:213], v160 offset:36864
	ds_read_b128 v[214:217], v160 offset:37888
	ds_read_b128 v[218:221], v160 offset:38912
	ds_read_b128 v[226:229], v160 offset:39936
	global_load_lds_dwordx4 v[244:245], off
	v_lshl_add_u64 v[230:231], v[230:231], 0, v[132:133]
	s_mov_b32 m0, s15
	s_nop 0
	global_load_lds_dwordx4 v[230:231], off
	s_waitcnt vmcnt(8)
	s_waitcnt lgkmcnt(0)
	s_barrier
	s_setprio 1
	v_mfma_i32_16x16x64_i8 v[128:131], v[162:165], v[194:197], v[128:131]
	v_mfma_i32_16x16x64_i8 v[124:127], v[170:173], v[194:197], v[124:127]
	v_mfma_i32_16x16x64_i8 v[112:115], v[162:165], v[202:205], v[112:115]
	v_mfma_i32_16x16x64_i8 v[108:111], v[170:173], v[202:205], v[108:111]
	v_mfma_i32_16x16x64_i8 v[96:99], v[162:165], v[210:213], v[96:99]
	v_mfma_i32_16x16x64_i8 v[92:95], v[170:173], v[210:213], v[92:95]
	v_mfma_i32_16x16x64_i8 v[80:83], v[162:165], v[218:221], v[80:83]
	v_mfma_i32_16x16x64_i8 v[76:79], v[170:173], v[218:221], v[76:79]
	v_mfma_i32_16x16x64_i8 v[128:131], v[166:169], v[198:201], v[128:131]
	v_mfma_i32_16x16x64_i8 v[124:127], v[174:177], v[198:201], v[124:127]
	v_mfma_i32_16x16x64_i8 v[112:115], v[166:169], v[206:209], v[112:115]
	v_mfma_i32_16x16x64_i8 v[108:111], v[174:177], v[206:209], v[108:111]
	v_mfma_i32_16x16x64_i8 v[96:99], v[166:169], v[214:217], v[96:99]
	v_mfma_i32_16x16x64_i8 v[92:95], v[174:177], v[214:217], v[92:95]
	v_mfma_i32_16x16x64_i8 v[80:83], v[166:169], v[226:229], v[80:83]
	v_mfma_i32_16x16x64_i8 v[76:79], v[174:177], v[226:229], v[76:79]
	v_mfma_i32_16x16x64_i8 v[120:123], v[178:181], v[194:197], v[120:123]
	v_mfma_i32_16x16x64_i8 v[116:119], v[186:189], v[194:197], v[116:119]
	v_mfma_i32_16x16x64_i8 v[104:107], v[178:181], v[202:205], v[104:107]
	v_mfma_i32_16x16x64_i8 v[100:103], v[186:189], v[202:205], v[100:103]
	v_mfma_i32_16x16x64_i8 v[88:91], v[178:181], v[210:213], v[88:91]
	v_mfma_i32_16x16x64_i8 v[84:87], v[186:189], v[210:213], v[84:87]
	v_mfma_i32_16x16x64_i8 v[72:75], v[178:181], v[218:221], v[72:75]
	v_mfma_i32_16x16x64_i8 v[68:71], v[186:189], v[218:221], v[68:71]
	v_mfma_i32_16x16x64_i8 v[120:123], v[182:185], v[198:201], v[120:123]
	v_mfma_i32_16x16x64_i8 v[116:119], v[190:193], v[198:201], v[116:119]
	v_mfma_i32_16x16x64_i8 v[104:107], v[182:185], v[206:209], v[104:107]
	v_mfma_i32_16x16x64_i8 v[100:103], v[190:193], v[206:209], v[100:103]
	v_mfma_i32_16x16x64_i8 v[88:91], v[182:185], v[214:217], v[88:91]
	v_mfma_i32_16x16x64_i8 v[84:87], v[190:193], v[214:217], v[84:87]
	v_mfma_i32_16x16x64_i8 v[72:75], v[182:185], v[226:229], v[72:75]
	v_mfma_i32_16x16x64_i8 v[68:71], v[190:193], v[226:229], v[68:71]
	s_setprio 0
	s_barrier
; #define PG8_STAGE(bufoff, gbase, voff) do { _Pragma("unroll") for (int _i = 0; _i < 2; ++_i) \
;         __builtin_amdgcn_global_load_lds((const unsigned*)((const char*)(gbase) + (voff)[_i]), (LAS unsigned*)(lds + (bufoff) + ldsw + _i * 8192), 16, 0, 0); } while (0)
; #define PG8_LDA(dst, b, h) do { _Pragma("unroll") for (int m = 0; m < 4; ++m) _Pragma("unroll") for (int k = 0; k < 2; ++k) dst[m][k] = *(const LAS bf16x8*)(lds + PG8_SA(b, h) + aoff + m * 2048 + k * 1024); } while (0)
; #define PG8_WAIT_V(n) asm volatile("s_waitcnt vmcnt(" #n ")" ::: "memory")
; #define PG8_WAIT_L(n) asm volatile("s_waitcnt lgkmcnt(" #n ")" ::: "memory")
; #define PG8_BAR __builtin_amdgcn_s_barrier()
; #define PG8_SCHED __builtin_amdgcn_sched_barrier(0)
;     ...
;             PG8_LDA(At, 1, 1); PG8_STAGE(PG8_SB(1, 0), b3, voffB); PG8_STAGE(PG8_SB(1, 1), b3 + hstepB, voffB); PG8_STAGE(PG8_SA(1, 0), a3, voffA);
;             PG8_WAIT_V(8); PG8_WAIT_L(0); PG8_BAR; PG8_MMA(1, 0, At, B0); PG8_MMA(1, 1, At, B1); PG8_BAR; PG8_SCHED;
	s_add_i32 s62, s62, s2
	s_add_i32 m0, s62, 0xffffff80
	ds_read_b128 v[194:197], v160 offset:49152
	ds_read_b128 v[198:201], v160 offset:50176
	ds_read_b128 v[202:205], v160 offset:51200
	ds_read_b128 v[206:209], v160 offset:52224
	ds_read_b128 v[210:213], v160 offset:53248
	ds_read_b128 v[214:217], v160 offset:54272
	ds_read_b128 v[218:221], v160 offset:55296
	ds_read_b128 v[226:229], v160 offset:56320
	global_load_lds_dwordx4 v[234:235], off offset:128
	s_add_i32 m0, s62, 0x1f80
	s_add_i32 s62, s63, s2
	global_load_lds_dwordx4 v[236:237], off offset:128
	s_add_i32 m0, s62, 0xffffff80
	s_nop 0
	global_load_lds_dwordx4 v[238:239], off offset:128
	s_add_i32 m0, s62, 0x1f80
	s_nop 0
	global_load_lds_dwordx4 v[232:233], off offset:128
	s_add_i32 m0, s47, 0xffffff80
	s_nop 0
	global_load_lds_dwordx4 v[240:241], off offset:128
	s_add_i32 m0, s48, 0xffffff80
	s_nop 0
	global_load_lds_dwordx4 v[242:243], off offset:128
	s_waitcnt vmcnt(8)
	s_waitcnt lgkmcnt(0)
	s_barrier
	s_setprio 1
	v_mfma_i32_16x16x64_i8 v[64:67], v[162:165], v[194:197], v[64:67]
	v_mfma_i32_16x16x64_i8 v[60:63], v[170:173], v[194:197], v[60:63]
	v_mfma_i32_16x16x64_i8 v[48:51], v[162:165], v[202:205], v[48:51]
	v_mfma_i32_16x16x64_i8 v[44:47], v[170:173], v[202:205], v[44:47]
	v_mfma_i32_16x16x64_i8 v[32:35], v[162:165], v[210:213], v[32:35]
	v_mfma_i32_16x16x64_i8 v[28:31], v[170:173], v[210:213], v[28:31]
	v_mfma_i32_16x16x64_i8 v[16:19], v[162:165], v[218:221], v[16:19]
	v_mfma_i32_16x16x64_i8 v[12:15], v[170:173], v[218:221], v[12:15]
	v_mfma_i32_16x16x64_i8 v[64:67], v[166:169], v[198:201], v[64:67]
	v_mfma_i32_16x16x64_i8 v[60:63], v[174:177], v[198:201], v[60:63]
	v_mfma_i32_16x16x64_i8 v[48:51], v[166:169], v[206:209], v[48:51]
	v_mfma_i32_16x16x64_i8 v[44:47], v[174:177], v[206:209], v[44:47]
	v_mfma_i32_16x16x64_i8 v[32:35], v[166:169], v[214:217], v[32:35]
	v_mfma_i32_16x16x64_i8 v[28:31], v[174:177], v[214:217], v[28:31]
	v_mfma_i32_16x16x64_i8 v[16:19], v[166:169], v[226:229], v[16:19]
	v_mfma_i32_16x16x64_i8 v[12:15], v[174:177], v[226:229], v[12:15]
	v_mfma_i32_16x16x64_i8 v[56:59], v[178:181], v[194:197], v[56:59]
	v_mfma_i32_16x16x64_i8 v[52:55], v[186:189], v[194:197], v[52:55]
	v_mfma_i32_16x16x64_i8 v[40:43], v[178:181], v[202:205], v[40:43]
	v_mfma_i32_16x16x64_i8 v[36:39], v[186:189], v[202:205], v[36:39]
	v_mfma_i32_16x16x64_i8 v[24:27], v[178:181], v[210:213], v[24:27]
	v_mfma_i32_16x16x64_i8 v[20:23], v[186:189], v[210:213], v[20:23]
	v_mfma_i32_16x16x64_i8 v[8:11], v[178:181], v[218:221], v[8:11]
	v_mfma_i32_16x16x64_i8 v[4:7], v[186:189], v[218:221], v[4:7]
	v_mfma_i32_16x16x64_i8 v[56:59], v[182:185], v[198:201], v[56:59]
	v_mfma_i32_16x16x64_i8 v[52:55], v[190:193], v[198:201], v[52:55]
	v_mfma_i32_16x16x64_i8 v[40:43], v[182:185], v[206:209], v[40:43]
	v_mfma_i32_16x16x64_i8 v[36:39], v[190:193], v[206:209], v[36:39]
	v_mfma_i32_16x16x64_i8 v[24:27], v[182:185], v[214:217], v[24:27]
	v_mfma_i32_16x16x64_i8 v[20:23], v[190:193], v[214:217], v[20:23]
	v_mfma_i32_16x16x64_i8 v[8:11], v[182:185], v[226:229], v[8:11]
	v_mfma_i32_16x16x64_i8 v[4:7], v[190:193], v[226:229], v[4:7]
	s_setprio 0
	s_barrier
	s_add_i32 s60, s60, 2
	s_add_u32 s38, s38, 0x100
	s_addc_u32 s39, s39, 0
	s_cmp_gt_u32 s60, 29
	s_cbranch_scc0 .LBB0_165
	s_and_b64 vcc, exec, s[42:43]
	s_cbranch_vccz .LBB0_168
	s_barrier

; #define PG8_STAGE(bufoff, gbase, voff) do { _Pragma("unroll") for (int _i = 0; _i < 2; ++_i) \
;         __builtin_amdgcn_global_load_lds((const unsigned*)((const char*)(gbase) + (voff)[_i]), (LAS unsigned*)(lds + (bufoff) + ldsw + _i * 8192), 16, 0, 0); } while (0)
; #define PG8_LDA(dst, b, h) do { _Pragma("unroll") for (int m = 0; m < 4; ++m) _Pragma("unroll") for (int k = 0; k < 2; ++k) dst[m][k] = *(const LAS bf16x8*)(lds + PG8_SA(b, h) + aoff + m * 2048 + k * 1024); } while (0)
; #define PG8_LDB(dst, b, h) do { _Pragma("unroll") for (int n = 0; n < 2; ++n) _Pragma("unroll") for (int k = 0; k < 2; ++k) dst[n][k] = *(const LAS bf16x8*)(lds + PG8_SB(b, h) + boff + n * 2048 + k * 1024); } while (0)
; #define PG8_WAIT_V(n) asm volatile("s_waitcnt vmcnt(" #n ")" ::: "memory")
; #define PG8_WAIT_L(n) asm volatile("s_waitcnt lgkmcnt(" #n ")" ::: "memory")
; #define PG8_BAR __builtin_amdgcn_s_barrier()
; #define PG8_SCHED __builtin_amdgcn_sched_barrier(0)
;     ...
;         for (int t = 0; t < nt; t += 2) {
;             const bool last = (t == nt - 2);
;             const char* a1 = cA + (size_t)(t + 1) * kstep;
;             const char* a2 = last ? nA : cA + (size_t)(t + 2) * kstep; const char* b2 = last ? nB : cB + (size_t)(t + 2) * kstep;
;             const char* a3 = a2 + kstep; const char* b3 = b2 + kstep;
;             if constexpr (SP2) {
;             PG8_LDB(B0, 0, 0); PG8_LDB(B1, 0, 1); PG8_SCHED; PG8_LDA(At, 0, 0); PG8_STAGE(PG8_SA(1, 1), a1 + hstepA, voffA);
;             PG8_WAIT_V(8); PG8_WAIT_L(0); PG8_BAR; PG8_MMA(0, 0, At, B0); PG8_MMA(0, 1, At, B1); PG8_BAR; PG8_SCHED;
;             PG8_LDA(At, 0, 1); PG8_STAGE(PG8_SB(0, 0), b2, voffB); PG8_STAGE(PG8_SB(0, 1), b2 + hstepB, voffB); PG8_STAGE(PG8_SA(0, 0), a2, voffA);
;             PG8_WAIT_V(8); PG8_WAIT_L(0); PG8_BAR; PG8_MMA(1, 0, At, B0); PG8_MMA(1, 1, At, B1); PG8_BAR; PG8_SCHED;
; __global__ void __launch_bounds__(NWAVES * 64, 2) fwd(Args args) {
;     ...
;             { pg8::Gemm g{(bf16_t*)(ws + WS_CQN), (bf16_t*)(ws + WS_WQ), MG, NQ, 512, 512, 512, 0, 0}; pg8::StaticOrder S; S.init(MG, NQ, G, bx);
;               pg8::EpiBf16<0> E{(bf16_t*)(ws + WS_Q), NQ, 1.0f / 64.0f};
;               pg8::gemm_phase<pg8::EpiBf16<0>, pg8::StaticOrder, true, true, 1>(lds + RING_OFF, g, S, E, tid); }
.LBB0_440:
	s_add_i32 s63, 0, 0x10000
	v_lshl_add_u64 v[4:5], v[180:181], 0, s[38:39]
	s_cmpk_eq_i32 s38, 0x300
	v_lshl_add_u64 v[4:5], v[4:5], 0, s[4:5]
	s_cselect_b64 vcc, -1, 0
	s_add_i32 s64, 0, 0x14000
	v_lshl_add_u64 v[6:7], v[186:187], 0, s[38:39]
	v_cndmask_b32_e32 v188, v4, v176, vcc
	v_cndmask_b32_e32 v189, v5, v177, vcc
	ds_read_b128 v[28:31], v204
	ds_read_b128 v[32:35], v204 offset:1024
	ds_read_b128 v[20:23], v204 offset:2048
	ds_read_b128 v[24:27], v204 offset:3072
	v_cndmask_b32_e32 v199, v7, v179, vcc
	v_cndmask_b32_e32 v198, v6, v178, vcc
	ds_read_b128 v[12:15], v205
	ds_read_b128 v[16:19], v205 offset:1024
	ds_read_b128 v[4:7], v205 offset:2048
	ds_read_b128 v[8:11], v205 offset:3072
	v_lshl_add_u64 v[200:201], v[184:185], 0, s[38:39]
	s_add_i32 m0, s15, 0xc000
	ds_read_b128 v[190:193], v212
	ds_read_b128 v[194:197], v212 offset:1024
	ds_read_b128 v[226:229], v212 offset:2048
	ds_read_b128 v[230:233], v212 offset:3072
	ds_read_b128 v[234:237], v212 offset:4096
	ds_read_b128 v[238:241], v212 offset:5120
	ds_read_b128 v[242:245], v212 offset:6144
	ds_read_b128 v[246:249], v212 offset:7168
	global_load_lds_dwordx4 v[200:201], off
	v_lshl_add_u64 v[200:201], v[182:183], 0, s[38:39]
	s_add_i32 m0, s15, 0xe000
	s_nop 0
	global_load_lds_dwordx4 v[200:201], off
	s_waitcnt vmcnt(8)
	s_waitcnt lgkmcnt(0)
	s_barrier
	s_setprio 1
	v_mfma_f32_16x16x128_f8f6f4 v[160:163], v[28:35], v[190:197], v[160:163]
	v_mfma_f32_16x16x128_f8f6f4 v[156:159], v[20:27], v[190:197], v[156:159]
	v_mfma_f32_16x16x128_f8f6f4 v[148:151], v[28:35], v[226:233], v[148:151]
	v_mfma_f32_16x16x128_f8f6f4 v[140:143], v[20:27], v[226:233], v[140:143]
	v_mfma_f32_16x16x128_f8f6f4 v[132:135], v[28:35], v[234:241], v[132:135]
	v_mfma_f32_16x16x128_f8f6f4 v[124:127], v[20:27], v[234:241], v[124:127]
	v_mfma_f32_16x16x128_f8f6f4 v[116:119], v[28:35], v[242:249], v[116:119]
	v_mfma_f32_16x16x128_f8f6f4 v[108:111], v[20:27], v[242:249], v[108:111]
	v_mfma_f32_16x16x128_f8f6f4 v[152:155], v[12:19], v[190:197], v[152:155]
	v_mfma_f32_16x16x128_f8f6f4 v[144:147], v[4:11], v[190:197], v[144:147]
	v_mfma_f32_16x16x128_f8f6f4 v[136:139], v[12:19], v[226:233], v[136:139]
	v_mfma_f32_16x16x128_f8f6f4 v[128:131], v[4:11], v[226:233], v[128:131]
	v_mfma_f32_16x16x128_f8f6f4 v[120:123], v[12:19], v[234:241], v[120:123]
	v_mfma_f32_16x16x128_f8f6f4 v[112:115], v[4:11], v[234:241], v[112:115]
	v_mfma_f32_16x16x128_f8f6f4 v[104:107], v[12:19], v[242:249], v[104:107]
	v_mfma_f32_16x16x128_f8f6f4 v[100:103], v[4:11], v[242:249], v[100:103]
	s_setprio 0
	s_barrier
	s_add_i32 s63, s63, s8
	v_lshl_add_u64 v[190:191], v[198:199], 0, v[2:3]
	s_mov_b32 m0, s63
	ds_read_b128 v[226:229], v212 offset:16384
	ds_read_b128 v[230:233], v212 offset:17408
	ds_read_b128 v[234:237], v212 offset:18432
	ds_read_b128 v[238:241], v212 offset:19456
	ds_read_b128 v[242:245], v212 offset:20480
	ds_read_b128 v[246:249], v212 offset:21504
	ds_read_b128 v[214:217], v212 offset:22528
	ds_read_b128 v[218:221], v212 offset:23552
	global_load_lds_dwordx4 v[190:191], off
	v_lshl_add_u64 v[192:193], v[198:199], 0, v[166:167]
	s_add_i32 m0, s63, 0x2000
	v_lshl_add_u64 v[196:197], v[198:199], 0, v[164:165]
	s_add_i32 s63, s64, s8
	global_load_lds_dwordx4 v[192:193], off
	v_lshl_add_u64 v[194:195], v[196:197], 0, v[2:3]
	s_mov_b32 m0, s63
	v_lshl_add_u64 v[196:197], v[196:197], 0, v[166:167]
	global_load_lds_dwordx4 v[194:195], off
	s_add_i32 m0, s63, 0x2000
	v_lshl_add_u64 v[198:199], v[188:189], 0, v[170:171]
	global_load_lds_dwordx4 v[196:197], off
	s_mov_b32 m0, s15
	v_lshl_add_u64 v[200:201], v[188:189], 0, v[168:169]
	global_load_lds_dwordx4 v[198:199], off
	s_mov_b32 m0, s33
	s_nop 0
	global_load_lds_dwordx4 v[200:201], off
	s_waitcnt vmcnt(8)
	s_waitcnt lgkmcnt(0)
	s_barrier
	s_setprio 1
	v_mfma_f32_16x16x128_f8f6f4 v[96:99], v[28:35], v[226:233], v[96:99]
	v_mfma_f32_16x16x128_f8f6f4 v[92:95], v[20:27], v[226:233], v[92:95]
	v_mfma_f32_16x16x128_f8f6f4 v[84:87], v[28:35], v[234:241], v[84:87]
	v_mfma_f32_16x16x128_f8f6f4 v[76:79], v[20:27], v[234:241], v[76:79]
	v_mfma_f32_16x16x128_f8f6f4 v[68:71], v[28:35], v[242:249], v[68:71]
	v_mfma_f32_16x16x128_f8f6f4 v[60:63], v[20:27], v[242:249], v[60:63]
	v_mfma_f32_16x16x128_f8f6f4 v[52:55], v[28:35], v[214:221], v[52:55]
	v_mfma_f32_16x16x128_f8f6f4 v[44:47], v[20:27], v[214:221], v[44:47]
	v_mfma_f32_16x16x128_f8f6f4 v[88:91], v[12:19], v[226:233], v[88:91]
	v_mfma_f32_16x16x128_f8f6f4 v[80:83], v[4:11], v[226:233], v[80:83]
	v_mfma_f32_16x16x128_f8f6f4 v[72:75], v[12:19], v[234:241], v[72:75]
	v_mfma_f32_16x16x128_f8f6f4 v[64:67], v[4:11], v[234:241], v[64:67]
	v_mfma_f32_16x16x128_f8f6f4 v[56:59], v[12:19], v[242:249], v[56:59]
	v_mfma_f32_16x16x128_f8f6f4 v[48:51], v[4:11], v[242:249], v[48:51]
	v_mfma_f32_16x16x128_f8f6f4 v[40:43], v[12:19], v[214:221], v[40:43]
	v_mfma_f32_16x16x128_f8f6f4 v[36:39], v[4:11], v[214:221], v[36:39]
	s_setprio 0
	s_barrier
; #define PG8_STAGE(bufoff, gbase, voff) do { _Pragma("unroll") for (int _i = 0; _i < 2; ++_i) \
;         __builtin_amdgcn_global_load_lds((const unsigned*)((const char*)(gbase) + (voff)[_i]), (LAS unsigned*)(lds + (bufoff) + ldsw + _i * 8192), 16, 0, 0); } while (0)
; #define PG8_LDA(dst, b, h) do { _Pragma("unroll") for (int m = 0; m < 4; ++m) _Pragma("unroll") for (int k = 0; k < 2; ++k) dst[m][k] = *(const LAS bf16x8*)(lds + PG8_SA(b, h) + aoff + m * 2048 + k * 1024); } while (0)
; #define PG8_LDB(dst, b, h) do { _Pragma("unroll") for (int n = 0; n < 2; ++n) _Pragma("unroll") for (int k = 0; k < 2; ++k) dst[n][k] = *(const LAS bf16x8*)(lds + PG8_SB(b, h) + boff + n * 2048 + k * 1024); } while (0)
; #define PG8_WAIT_V(n) asm volatile("s_waitcnt vmcnt(" #n ")" ::: "memory")
; #define PG8_WAIT_L(n) asm volatile("s_waitcnt lgkmcnt(" #n ")" ::: "memory")
; #define PG8_BAR __builtin_amdgcn_s_barrier()
; #define PG8_SCHED __builtin_amdgcn_sched_barrier(0)
;     ...
;             PG8_WAIT_V(8); PG8_WAIT_L(0); PG8_BAR; PG8_MMA(1, 0, At, B0); PG8_MMA(1, 1, At, B1); PG8_BAR; PG8_SCHED;
;             PG8_LDB(B0, 1, 0); PG8_LDB(B1, 1, 1); PG8_SCHED; PG8_LDA(At, 1, 0); PG8_STAGE(PG8_SA(0, 1), a2 + hstepA, voffA);
;             PG8_WAIT_V(8); PG8_WAIT_L(0); PG8_BAR; PG8_MMA(0, 0, At, B0); PG8_MMA(0, 1, At, B1); PG8_BAR; PG8_SCHED;
;             PG8_LDA(At, 1, 1); PG8_STAGE(PG8_SB(1, 0), b3, voffB); PG8_STAGE(PG8_SB(1, 1), b3 + hstepB, voffB); PG8_STAGE(PG8_SA(1, 0), a3, voffA);
;             PG8_WAIT_V(8); PG8_WAIT_L(0); PG8_BAR; PG8_MMA(1, 0, At, B0); PG8_MMA(1, 1, At, B1); PG8_BAR; PG8_SCHED;
	s_add_i32 s63, 0, 0x18000
	s_add_i32 s64, 0, 0x1c000
	ds_read_b128 v[4:7], v206
	ds_read_b128 v[8:11], v206 offset:1024
	ds_read_b128 v[12:15], v206 offset:2048
	ds_read_b128 v[16:19], v206 offset:3072
	ds_read_b128 v[20:23], v207
	ds_read_b128 v[24:27], v207 offset:1024
	ds_read_b128 v[28:31], v207 offset:2048
	ds_read_b128 v[32:35], v207 offset:3072
	v_lshl_add_u64 v[188:189], v[188:189], 0, v[0:1]
	s_mov_b32 m0, s44
	v_lshl_add_u64 v[202:203], v[188:189], 0, v[170:171]
	ds_read_b128 v[214:217], v212 offset:32768
	ds_read_b128 v[218:221], v212 offset:33792
	ds_read_b128 v[226:229], v212 offset:34816
	ds_read_b128 v[230:233], v212 offset:35840
	ds_read_b128 v[234:237], v212 offset:36864
	ds_read_b128 v[238:241], v212 offset:37888
	ds_read_b128 v[242:245], v212 offset:38912
	ds_read_b128 v[246:249], v212 offset:39936
	global_load_lds_dwordx4 v[202:203], off
	v_lshl_add_u64 v[188:189], v[188:189], 0, v[168:169]
	s_mov_b32 m0, s45
	s_nop 0
	global_load_lds_dwordx4 v[188:189], off
	s_waitcnt vmcnt(8)
	s_waitcnt lgkmcnt(0)
	s_barrier
	s_setprio 1
	v_mfma_f32_16x16x128_f8f6f4 v[160:163], v[4:11], v[214:221], v[160:163]
	v_mfma_f32_16x16x128_f8f6f4 v[156:159], v[12:19], v[214:221], v[156:159]
	v_mfma_f32_16x16x128_f8f6f4 v[148:151], v[4:11], v[226:233], v[148:151]
	v_mfma_f32_16x16x128_f8f6f4 v[140:143], v[12:19], v[226:233], v[140:143]
	v_mfma_f32_16x16x128_f8f6f4 v[132:135], v[4:11], v[234:241], v[132:135]
	v_mfma_f32_16x16x128_f8f6f4 v[124:127], v[12:19], v[234:241], v[124:127]
	v_mfma_f32_16x16x128_f8f6f4 v[116:119], v[4:11], v[242:249], v[116:119]
	v_mfma_f32_16x16x128_f8f6f4 v[108:111], v[12:19], v[242:249], v[108:111]
	v_mfma_f32_16x16x128_f8f6f4 v[152:155], v[20:27], v[214:221], v[152:155]
	v_mfma_f32_16x16x128_f8f6f4 v[144:147], v[28:35], v[214:221], v[144:147]
	v_mfma_f32_16x16x128_f8f6f4 v[136:139], v[20:27], v[226:233], v[136:139]
	v_mfma_f32_16x16x128_f8f6f4 v[128:131], v[28:35], v[226:233], v[128:131]
	v_mfma_f32_16x16x128_f8f6f4 v[120:123], v[20:27], v[234:241], v[120:123]
	v_mfma_f32_16x16x128_f8f6f4 v[112:115], v[28:35], v[234:241], v[112:115]
	v_mfma_f32_16x16x128_f8f6f4 v[104:107], v[20:27], v[242:249], v[104:107]
	v_mfma_f32_16x16x128_f8f6f4 v[100:103], v[28:35], v[242:249], v[100:103]
	s_setprio 0
	s_barrier
	s_add_i32 s63, s63, s8
	s_add_i32 m0, s63, 0xffffff80
	ds_read_b128 v[214:217], v212 offset:49152
	ds_read_b128 v[218:221], v212 offset:50176
	ds_read_b128 v[226:229], v212 offset:51200
	ds_read_b128 v[230:233], v212 offset:52224
	ds_read_b128 v[234:237], v212 offset:53248
	ds_read_b128 v[238:241], v212 offset:54272
	ds_read_b128 v[242:245], v212 offset:55296
	ds_read_b128 v[246:249], v212 offset:56320
	global_load_lds_dwordx4 v[190:191], off offset:128
	s_add_i32 m0, s63, 0x1f80
	s_add_i32 s63, s64, s8
	global_load_lds_dwordx4 v[192:193], off offset:128
	s_add_i32 m0, s63, 0xffffff80
	s_nop 0
	global_load_lds_dwordx4 v[194:195], off offset:128
	s_add_i32 m0, s63, 0x1f80
	s_nop 0
	global_load_lds_dwordx4 v[196:197], off offset:128
	s_add_i32 m0, s46, 0xffffff80
	s_nop 0
	global_load_lds_dwordx4 v[198:199], off offset:128
	s_add_i32 m0, s47, 0xffffff80
	s_nop 0
	global_load_lds_dwordx4 v[200:201], off offset:128
	s_waitcnt vmcnt(8)
	s_waitcnt lgkmcnt(0)
	s_barrier
	s_setprio 1
	v_mfma_f32_16x16x128_f8f6f4 v[96:99], v[4:11], v[214:221], v[96:99]
	v_mfma_f32_16x16x128_f8f6f4 v[92:95], v[12:19], v[214:221], v[92:95]
	v_mfma_f32_16x16x128_f8f6f4 v[84:87], v[4:11], v[226:233], v[84:87]
	v_mfma_f32_16x16x128_f8f6f4 v[76:79], v[12:19], v[226:233], v[76:79]
	v_mfma_f32_16x16x128_f8f6f4 v[68:71], v[4:11], v[234:241], v[68:71]
	v_mfma_f32_16x16x128_f8f6f4 v[60:63], v[12:19], v[234:241], v[60:63]
	v_mfma_f32_16x16x128_f8f6f4 v[52:55], v[4:11], v[242:249], v[52:55]
	v_mfma_f32_16x16x128_f8f6f4 v[44:47], v[12:19], v[242:249], v[44:47]
	v_mfma_f32_16x16x128_f8f6f4 v[88:91], v[20:27], v[214:221], v[88:91]
	v_mfma_f32_16x16x128_f8f6f4 v[80:83], v[28:35], v[214:221], v[80:83]
	v_mfma_f32_16x16x128_f8f6f4 v[72:75], v[20:27], v[226:233], v[72:75]
	v_mfma_f32_16x16x128_f8f6f4 v[64:67], v[28:35], v[226:233], v[64:67]
	v_mfma_f32_16x16x128_f8f6f4 v[56:59], v[20:27], v[234:241], v[56:59]
	v_mfma_f32_16x16x128_f8f6f4 v[48:51], v[28:35], v[234:241], v[48:51]
	v_mfma_f32_16x16x128_f8f6f4 v[40:43], v[20:27], v[242:249], v[40:43]
	v_mfma_f32_16x16x128_f8f6f4 v[36:39], v[28:35], v[242:249], v[36:39]
	s_setprio 0
	s_barrier
	s_add_i32 s62, s62, 2
	s_add_u32 s38, s38, 0x100
	s_addc_u32 s39, s39, 0
	s_cmp_gt_u32 s62, 5
	s_cbranch_scc0 .LBB0_440
	s_and_b64 vcc, exec, s[42:43]
	s_cbranch_vccz .LBB0_443
	s_barrier

; #define PG8_STAGE(bufoff, gbase, voff) do { _Pragma("unroll") for (int _i = 0; _i < 2; ++_i) \
;         __builtin_amdgcn_global_load_lds((const unsigned*)((const char*)(gbase) + (voff)[_i]), (LAS unsigned*)(lds + (bufoff) + ldsw + _i * 8192), 16, 0, 0); } while (0)
; #define PG8_LDA(dst, b, h) do { _Pragma("unroll") for (int m = 0; m < 4; ++m) _Pragma("unroll") for (int k = 0; k < 2; ++k) dst[m][k] = *(const LAS bf16x8*)(lds + PG8_SA(b, h) + aoff + m * 2048 + k * 1024); } while (0)
; #define PG8_LDB(dst, b, h) do { _Pragma("unroll") for (int n = 0; n < 2; ++n) _Pragma("unroll") for (int k = 0; k < 2; ++k) dst[n][k] = *(const LAS bf16x8*)(lds + PG8_SB(b, h) + boff + n * 2048 + k * 1024); } while (0)
; #define PG8_WAIT_V(n) asm volatile("s_waitcnt vmcnt(" #n ")" ::: "memory")
; #define PG8_WAIT_L(n) asm volatile("s_waitcnt lgkmcnt(" #n ")" ::: "memory")
; #define PG8_BAR __builtin_amdgcn_s_barrier()
; #define PG8_SCHED __builtin_amdgcn_sched_barrier(0)
;     ...
;         for (int t = 0; t < nt; t += 2) {
;             const bool last = (t == nt - 2);
;             const char* a1 = cA + (size_t)(t + 1) * kstep;
;             const char* a2 = last ? nA : cA + (size_t)(t + 2) * kstep; const char* b2 = last ? nB : cB + (size_t)(t + 2) * kstep;
;             const char* a3 = a2 + kstep; const char* b3 = b2 + kstep;
;             if constexpr (SP2) {
;             PG8_LDB(B0, 0, 0); PG8_LDB(B1, 0, 1); PG8_SCHED; PG8_LDA(At, 0, 0); PG8_STAGE(PG8_SA(1, 1), a1 + hstepA, voffA);
;             PG8_WAIT_V(8); PG8_WAIT_L(0); PG8_BAR; PG8_MMA(0, 0, At, B0); PG8_MMA(0, 1, At, B1); PG8_BAR; PG8_SCHED;
;             PG8_LDA(At, 0, 1); PG8_STAGE(PG8_SB(0, 0), b2, voffB); PG8_STAGE(PG8_SB(0, 1), b2 + hstepB, voffB); PG8_STAGE(PG8_SA(0, 0), a2, voffA);
;             PG8_WAIT_V(8); PG8_WAIT_L(0); PG8_BAR; PG8_MMA(1, 0, At, B0); PG8_MMA(1, 1, At, B1); PG8_BAR; PG8_SCHED;
.LBB0_783:
	s_add_i32 s39, 0, 0x10000
	s_cmpk_eq_i32 s28, 0xf00
	v_lshl_add_u64 v[160:161], v[148:149], 0, s[28:29]
	s_cselect_b64 vcc, -1, 0
	s_add_i32 s75, 0, 0x14000
	v_lshl_add_u64 v[160:161], v[160:161], 0, s[4:5]
	v_lshl_add_u64 v[176:177], v[154:155], 0, s[28:29]
	v_cndmask_b32_e32 v231, v161, v145, vcc
	v_cndmask_b32_e32 v230, v160, v144, vcc
	ds_read_b128 v[160:163], v246
	ds_read_b128 v[164:167], v246 offset:1024
	ds_read_b128 v[168:171], v246 offset:2048
	ds_read_b128 v[172:175], v246 offset:3072
	v_cndmask_b32_e32 v233, v177, v147, vcc
	v_cndmask_b32_e32 v232, v176, v146, vcc
	ds_read_b128 v[176:179], v247
	ds_read_b128 v[180:183], v247 offset:1024
	ds_read_b128 v[184:187], v247 offset:2048
	ds_read_b128 v[188:191], v247 offset:3072
	v_lshl_add_u64 v[234:235], v[152:153], 0, s[28:29]
	s_add_i32 m0, s33, 0xc000
	ds_read_b128 v[192:195], v159
	ds_read_b128 v[196:199], v159 offset:1024
	ds_read_b128 v[200:203], v159 offset:2048
	ds_read_b128 v[204:207], v159 offset:3072
	ds_read_b128 v[210:213], v159 offset:4096
	ds_read_b128 v[214:217], v159 offset:5120
	ds_read_b128 v[218:221], v159 offset:6144
	ds_read_b128 v[226:229], v159 offset:7168
	global_load_lds_dwordx4 v[234:235], off
	v_lshl_add_u64 v[234:235], v[150:151], 0, s[28:29]
	s_add_i32 m0, s33, 0xe000
	s_nop 0
	global_load_lds_dwordx4 v[234:235], off
	s_waitcnt vmcnt(8)
	s_waitcnt lgkmcnt(0)
	s_barrier
	s_setprio 1
	v_mfma_i32_16x16x64_i8 v[128:131], v[160:163], v[192:195], v[128:131]
	v_mfma_i32_16x16x64_i8 v[124:127], v[168:171], v[192:195], v[124:127]
	v_mfma_i32_16x16x64_i8 v[112:115], v[160:163], v[200:203], v[112:115]
	v_mfma_i32_16x16x64_i8 v[108:111], v[168:171], v[200:203], v[108:111]
	v_mfma_i32_16x16x64_i8 v[96:99], v[160:163], v[210:213], v[96:99]
	v_mfma_i32_16x16x64_i8 v[92:95], v[168:171], v[210:213], v[92:95]
	v_mfma_i32_16x16x64_i8 v[80:83], v[160:163], v[218:221], v[80:83]
	v_mfma_i32_16x16x64_i8 v[76:79], v[168:171], v[218:221], v[76:79]
	v_mfma_i32_16x16x64_i8 v[128:131], v[164:167], v[196:199], v[128:131]
	v_mfma_i32_16x16x64_i8 v[124:127], v[172:175], v[196:199], v[124:127]
	v_mfma_i32_16x16x64_i8 v[112:115], v[164:167], v[204:207], v[112:115]
	v_mfma_i32_16x16x64_i8 v[108:111], v[172:175], v[204:207], v[108:111]
	v_mfma_i32_16x16x64_i8 v[96:99], v[164:167], v[214:217], v[96:99]
	v_mfma_i32_16x16x64_i8 v[92:95], v[172:175], v[214:217], v[92:95]
	v_mfma_i32_16x16x64_i8 v[80:83], v[164:167], v[226:229], v[80:83]
	v_mfma_i32_16x16x64_i8 v[76:79], v[172:175], v[226:229], v[76:79]
	v_mfma_i32_16x16x64_i8 v[120:123], v[176:179], v[192:195], v[120:123]
	v_mfma_i32_16x16x64_i8 v[116:119], v[184:187], v[192:195], v[116:119]
	v_mfma_i32_16x16x64_i8 v[104:107], v[176:179], v[200:203], v[104:107]
	v_mfma_i32_16x16x64_i8 v[100:103], v[184:187], v[200:203], v[100:103]
	v_mfma_i32_16x16x64_i8 v[88:91], v[176:179], v[210:213], v[88:91]
	v_mfma_i32_16x16x64_i8 v[84:87], v[184:187], v[210:213], v[84:87]
	v_mfma_i32_16x16x64_i8 v[72:75], v[176:179], v[218:221], v[72:75]
	v_mfma_i32_16x16x64_i8 v[68:71], v[184:187], v[218:221], v[68:71]
	v_mfma_i32_16x16x64_i8 v[120:123], v[180:183], v[196:199], v[120:123]
	v_mfma_i32_16x16x64_i8 v[116:119], v[188:191], v[196:199], v[116:119]
	v_mfma_i32_16x16x64_i8 v[104:107], v[180:183], v[204:207], v[104:107]
	v_mfma_i32_16x16x64_i8 v[100:103], v[188:191], v[204:207], v[100:103]
	v_mfma_i32_16x16x64_i8 v[88:91], v[180:183], v[214:217], v[88:91]
	v_mfma_i32_16x16x64_i8 v[84:87], v[188:191], v[214:217], v[84:87]
	v_mfma_i32_16x16x64_i8 v[72:75], v[180:183], v[226:229], v[72:75]
	v_mfma_i32_16x16x64_i8 v[68:71], v[188:191], v[226:229], v[68:71]
	s_setprio 0
	s_barrier
	s_add_i32 s39, s39, s15
	v_lshl_add_u64 v[234:235], v[232:233], 0, v[2:3]
	s_mov_b32 m0, s39
	ds_read_b128 v[192:195], v159 offset:16384
	ds_read_b128 v[196:199], v159 offset:17408
	ds_read_b128 v[200:203], v159 offset:18432
	ds_read_b128 v[204:207], v159 offset:19456
	ds_read_b128 v[210:213], v159 offset:20480
	ds_read_b128 v[214:217], v159 offset:21504
	ds_read_b128 v[218:221], v159 offset:22528
	ds_read_b128 v[226:229], v159 offset:23552
	global_load_lds_dwordx4 v[234:235], off
	v_lshl_add_u64 v[236:237], v[232:233], 0, v[134:135]
	s_add_i32 m0, s39, 0x2000
	v_lshl_add_u64 v[232:233], v[232:233], 0, v[138:139]
	s_add_i32 s39, s75, s15
	global_load_lds_dwordx4 v[236:237], off
	v_lshl_add_u64 v[238:239], v[232:233], 0, v[2:3]
	s_mov_b32 m0, s39
	v_lshl_add_u64 v[232:233], v[232:233], 0, v[134:135]
	global_load_lds_dwordx4 v[238:239], off
	s_add_i32 m0, s39, 0x2000
	v_lshl_add_u64 v[240:241], v[230:231], 0, v[0:1]
	global_load_lds_dwordx4 v[232:233], off
	s_mov_b32 m0, s33
	v_lshl_add_u64 v[242:243], v[230:231], 0, v[132:133]
	global_load_lds_dwordx4 v[240:241], off
	s_mov_b32 m0, s57
	s_nop 0
	global_load_lds_dwordx4 v[242:243], off
	s_waitcnt vmcnt(8)
	s_waitcnt lgkmcnt(0)
	s_barrier
; #define PG8_STAGE(bufoff, gbase, voff) do { _Pragma("unroll") for (int _i = 0; _i < 2; ++_i) \
;         __builtin_amdgcn_global_load_lds((const unsigned*)((const char*)(gbase) + (voff)[_i]), (LAS unsigned*)(lds + (bufoff) + ldsw + _i * 8192), 16, 0, 0); } while (0)
; #define PG8_LDA(dst, b, h) do { _Pragma("unroll") for (int m = 0; m < 4; ++m) _Pragma("unroll") for (int k = 0; k < 2; ++k) dst[m][k] = *(const LAS bf16x8*)(lds + PG8_SA(b, h) + aoff + m * 2048 + k * 1024); } while (0)
; #define PG8_LDB(dst, b, h) do { _Pragma("unroll") for (int n = 0; n < 2; ++n) _Pragma("unroll") for (int k = 0; k < 2; ++k) dst[n][k] = *(const LAS bf16x8*)(lds + PG8_SB(b, h) + boff + n * 2048 + k * 1024); } while (0)
; #define PG8_WAIT_V(n) asm volatile("s_waitcnt vmcnt(" #n ")" ::: "memory")
; #define PG8_WAIT_L(n) asm volatile("s_waitcnt lgkmcnt(" #n ")" ::: "memory")
; #define PG8_BAR __builtin_amdgcn_s_barrier()
; #define PG8_SCHED __builtin_amdgcn_sched_barrier(0)
;     ...
;             PG8_WAIT_V(8); PG8_WAIT_L(0); PG8_BAR; PG8_MMA(1, 0, At, B0); PG8_MMA(1, 1, At, B1); PG8_BAR; PG8_SCHED;
;             PG8_LDB(B0, 1, 0); PG8_LDB(B1, 1, 1); PG8_SCHED; PG8_LDA(At, 1, 0); PG8_STAGE(PG8_SA(0, 1), a2 + hstepA, voffA);
;             PG8_WAIT_V(8); PG8_WAIT_L(0); PG8_BAR; PG8_MMA(0, 0, At, B0); PG8_MMA(0, 1, At, B1); PG8_BAR; PG8_SCHED;
;             PG8_LDA(At, 1, 1); PG8_STAGE(PG8_SB(1, 0), b3, voffB); PG8_STAGE(PG8_SB(1, 1), b3 + hstepB, voffB); PG8_STAGE(PG8_SA(1, 0), a3, voffA);
	s_setprio 1
	v_mfma_i32_16x16x64_i8 v[64:67], v[160:163], v[192:195], v[64:67]
	v_mfma_i32_16x16x64_i8 v[60:63], v[168:171], v[192:195], v[60:63]
	v_mfma_i32_16x16x64_i8 v[48:51], v[160:163], v[200:203], v[48:51]
	v_mfma_i32_16x16x64_i8 v[44:47], v[168:171], v[200:203], v[44:47]
	v_mfma_i32_16x16x64_i8 v[32:35], v[160:163], v[210:213], v[32:35]
	v_mfma_i32_16x16x64_i8 v[28:31], v[168:171], v[210:213], v[28:31]
	v_mfma_i32_16x16x64_i8 v[16:19], v[160:163], v[218:221], v[16:19]
	v_mfma_i32_16x16x64_i8 v[12:15], v[168:171], v[218:221], v[12:15]
	v_mfma_i32_16x16x64_i8 v[64:67], v[164:167], v[196:199], v[64:67]
	v_mfma_i32_16x16x64_i8 v[60:63], v[172:175], v[196:199], v[60:63]
	v_mfma_i32_16x16x64_i8 v[48:51], v[164:167], v[204:207], v[48:51]
	v_mfma_i32_16x16x64_i8 v[44:47], v[172:175], v[204:207], v[44:47]
	v_mfma_i32_16x16x64_i8 v[32:35], v[164:167], v[214:217], v[32:35]
	v_mfma_i32_16x16x64_i8 v[28:31], v[172:175], v[214:217], v[28:31]
	v_mfma_i32_16x16x64_i8 v[16:19], v[164:167], v[226:229], v[16:19]
	v_mfma_i32_16x16x64_i8 v[12:15], v[172:175], v[226:229], v[12:15]
	v_mfma_i32_16x16x64_i8 v[56:59], v[176:179], v[192:195], v[56:59]
	v_mfma_i32_16x16x64_i8 v[52:55], v[184:187], v[192:195], v[52:55]
	v_mfma_i32_16x16x64_i8 v[40:43], v[176:179], v[200:203], v[40:43]
	v_mfma_i32_16x16x64_i8 v[36:39], v[184:187], v[200:203], v[36:39]
	v_mfma_i32_16x16x64_i8 v[24:27], v[176:179], v[210:213], v[24:27]
	v_mfma_i32_16x16x64_i8 v[20:23], v[184:187], v[210:213], v[20:23]
	v_mfma_i32_16x16x64_i8 v[8:11], v[176:179], v[218:221], v[8:11]
	v_mfma_i32_16x16x64_i8 v[4:7], v[184:187], v[218:221], v[4:7]
	v_mfma_i32_16x16x64_i8 v[56:59], v[180:183], v[196:199], v[56:59]
	v_mfma_i32_16x16x64_i8 v[52:55], v[188:191], v[196:199], v[52:55]
	v_mfma_i32_16x16x64_i8 v[40:43], v[180:183], v[204:207], v[40:43]
	v_mfma_i32_16x16x64_i8 v[36:39], v[188:191], v[204:207], v[36:39]
	v_mfma_i32_16x16x64_i8 v[24:27], v[180:183], v[214:217], v[24:27]
	v_mfma_i32_16x16x64_i8 v[20:23], v[188:191], v[214:217], v[20:23]
	v_mfma_i32_16x16x64_i8 v[8:11], v[180:183], v[226:229], v[8:11]
	v_mfma_i32_16x16x64_i8 v[4:7], v[188:191], v[226:229], v[4:7]
	s_setprio 0
	s_barrier
	s_add_i32 s39, 0, 0x18000
	s_add_i32 s75, 0, 0x1c000
	ds_read_b128 v[160:163], v248
	ds_read_b128 v[164:167], v248 offset:1024
	ds_read_b128 v[168:171], v248 offset:2048
	ds_read_b128 v[172:175], v248 offset:3072
	ds_read_b128 v[176:179], v249
	ds_read_b128 v[180:183], v249 offset:1024
	ds_read_b128 v[184:187], v249 offset:2048
	ds_read_b128 v[188:191], v249 offset:3072
	v_lshl_add_u64 v[230:231], v[230:231], 0, v[136:137]
	s_mov_b32 m0, s62
	v_lshl_add_u64 v[244:245], v[230:231], 0, v[0:1]
	ds_read_b128 v[192:195], v159 offset:32768
	ds_read_b128 v[196:199], v159 offset:33792
	ds_read_b128 v[200:203], v159 offset:34816
	ds_read_b128 v[204:207], v159 offset:35840
	ds_read_b128 v[210:213], v159 offset:36864
	ds_read_b128 v[214:217], v159 offset:37888
	ds_read_b128 v[218:221], v159 offset:38912
	ds_read_b128 v[226:229], v159 offset:39936
	global_load_lds_dwordx4 v[244:245], off
	v_lshl_add_u64 v[230:231], v[230:231], 0, v[132:133]
	s_mov_b32 m0, s63
	s_nop 0
	global_load_lds_dwordx4 v[230:231], off
	s_waitcnt vmcnt(8)
	s_waitcnt lgkmcnt(0)
	s_barrier
	s_setprio 1
	v_mfma_i32_16x16x64_i8 v[128:131], v[160:163], v[192:195], v[128:131]
	v_mfma_i32_16x16x64_i8 v[124:127], v[168:171], v[192:195], v[124:127]
	v_mfma_i32_16x16x64_i8 v[112:115], v[160:163], v[200:203], v[112:115]
	v_mfma_i32_16x16x64_i8 v[108:111], v[168:171], v[200:203], v[108:111]
	v_mfma_i32_16x16x64_i8 v[96:99], v[160:163], v[210:213], v[96:99]
	v_mfma_i32_16x16x64_i8 v[92:95], v[168:171], v[210:213], v[92:95]
	v_mfma_i32_16x16x64_i8 v[80:83], v[160:163], v[218:221], v[80:83]
	v_mfma_i32_16x16x64_i8 v[76:79], v[168:171], v[218:221], v[76:79]
	v_mfma_i32_16x16x64_i8 v[128:131], v[164:167], v[196:199], v[128:131]
	v_mfma_i32_16x16x64_i8 v[124:127], v[172:175], v[196:199], v[124:127]
	v_mfma_i32_16x16x64_i8 v[112:115], v[164:167], v[204:207], v[112:115]
	v_mfma_i32_16x16x64_i8 v[108:111], v[172:175], v[204:207], v[108:111]
	v_mfma_i32_16x16x64_i8 v[96:99], v[164:167], v[214:217], v[96:99]
	v_mfma_i32_16x16x64_i8 v[92:95], v[172:175], v[214:217], v[92:95]
	v_mfma_i32_16x16x64_i8 v[80:83], v[164:167], v[226:229], v[80:83]
	v_mfma_i32_16x16x64_i8 v[76:79], v[172:175], v[226:229], v[76:79]
	v_mfma_i32_16x16x64_i8 v[120:123], v[176:179], v[192:195], v[120:123]
	v_mfma_i32_16x16x64_i8 v[116:119], v[184:187], v[192:195], v[116:119]
	v_mfma_i32_16x16x64_i8 v[104:107], v[176:179], v[200:203], v[104:107]
	v_mfma_i32_16x16x64_i8 v[100:103], v[184:187], v[200:203], v[100:103]
	v_mfma_i32_16x16x64_i8 v[88:91], v[176:179], v[210:213], v[88:91]
	v_mfma_i32_16x16x64_i8 v[84:87], v[184:187], v[210:213], v[84:87]
	v_mfma_i32_16x16x64_i8 v[72:75], v[176:179], v[218:221], v[72:75]
	v_mfma_i32_16x16x64_i8 v[68:71], v[184:187], v[218:221], v[68:71]
	v_mfma_i32_16x16x64_i8 v[120:123], v[180:183], v[196:199], v[120:123]
	v_mfma_i32_16x16x64_i8 v[116:119], v[188:191], v[196:199], v[116:119]
	v_mfma_i32_16x16x64_i8 v[104:107], v[180:183], v[204:207], v[104:107]
	v_mfma_i32_16x16x64_i8 v[100:103], v[188:191], v[204:207], v[100:103]
	v_mfma_i32_16x16x64_i8 v[88:91], v[180:183], v[214:217], v[88:91]
	v_mfma_i32_16x16x64_i8 v[84:87], v[188:191], v[214:217], v[84:87]
	v_mfma_i32_16x16x64_i8 v[72:75], v[180:183], v[226:229], v[72:75]
	v_mfma_i32_16x16x64_i8 v[68:71], v[188:191], v[226:229], v[68:71]
	s_setprio 0
	s_barrier
; #define PG8_STAGE(bufoff, gbase, voff) do { _Pragma("unroll") for (int _i = 0; _i < 2; ++_i) \
;         __builtin_amdgcn_global_load_lds((const unsigned*)((const char*)(gbase) + (voff)[_i]), (LAS unsigned*)(lds + (bufoff) + ldsw + _i * 8192), 16, 0, 0); } while (0)
; #define PG8_LDA(dst, b, h) do { _Pragma("unroll") for (int m = 0; m < 4; ++m) _Pragma("unroll") for (int k = 0; k < 2; ++k) dst[m][k] = *(const LAS bf16x8*)(lds + PG8_SA(b, h) + aoff + m * 2048 + k * 1024); } while (0)
; #define PG8_WAIT_V(n) asm volatile("s_waitcnt vmcnt(" #n ")" ::: "memory")
; #define PG8_WAIT_L(n) asm volatile("s_waitcnt lgkmcnt(" #n ")" ::: "memory")
; #define PG8_BAR __builtin_amdgcn_s_barrier()
; #define PG8_SCHED __builtin_amdgcn_sched_barrier(0)
;     ...
;             PG8_LDA(At, 1, 1); PG8_STAGE(PG8_SB(1, 0), b3, voffB); PG8_STAGE(PG8_SB(1, 1), b3 + hstepB, voffB); PG8_STAGE(PG8_SA(1, 0), a3, voffA);
;             PG8_WAIT_V(8); PG8_WAIT_L(0); PG8_BAR; PG8_MMA(1, 0, At, B0); PG8_MMA(1, 1, At, B1); PG8_BAR; PG8_SCHED;
	s_add_i32 s39, s39, s15
	s_add_i32 m0, s39, 0xffffff80
	ds_read_b128 v[192:195], v159 offset:49152
	ds_read_b128 v[196:199], v159 offset:50176
	ds_read_b128 v[200:203], v159 offset:51200
	ds_read_b128 v[204:207], v159 offset:52224
	ds_read_b128 v[210:213], v159 offset:53248
	ds_read_b128 v[214:217], v159 offset:54272
	ds_read_b128 v[218:221], v159 offset:55296
	ds_read_b128 v[226:229], v159 offset:56320
	global_load_lds_dwordx4 v[234:235], off offset:128
	s_add_i32 m0, s39, 0x1f80
	s_add_i32 s39, s75, s15
	global_load_lds_dwordx4 v[236:237], off offset:128
	s_add_i32 m0, s39, 0xffffff80
	s_nop 0
	global_load_lds_dwordx4 v[238:239], off offset:128
	s_add_i32 m0, s39, 0x1f80
	s_nop 0
	global_load_lds_dwordx4 v[232:233], off offset:128
	s_add_i32 m0, s64, 0xffffff80
	s_nop 0
	global_load_lds_dwordx4 v[240:241], off offset:128
	s_add_i32 m0, s65, 0xffffff80
	s_nop 0
	global_load_lds_dwordx4 v[242:243], off offset:128
	s_waitcnt vmcnt(8)
	s_waitcnt lgkmcnt(0)
	s_barrier
	s_setprio 1
	v_mfma_i32_16x16x64_i8 v[64:67], v[160:163], v[192:195], v[64:67]
	v_mfma_i32_16x16x64_i8 v[60:63], v[168:171], v[192:195], v[60:63]
	v_mfma_i32_16x16x64_i8 v[48:51], v[160:163], v[200:203], v[48:51]
	v_mfma_i32_16x16x64_i8 v[44:47], v[168:171], v[200:203], v[44:47]
	v_mfma_i32_16x16x64_i8 v[32:35], v[160:163], v[210:213], v[32:35]
	v_mfma_i32_16x16x64_i8 v[28:31], v[168:171], v[210:213], v[28:31]
	v_mfma_i32_16x16x64_i8 v[16:19], v[160:163], v[218:221], v[16:19]
	v_mfma_i32_16x16x64_i8 v[12:15], v[168:171], v[218:221], v[12:15]
	v_mfma_i32_16x16x64_i8 v[64:67], v[164:167], v[196:199], v[64:67]
	v_mfma_i32_16x16x64_i8 v[60:63], v[172:175], v[196:199], v[60:63]
	v_mfma_i32_16x16x64_i8 v[48:51], v[164:167], v[204:207], v[48:51]
	v_mfma_i32_16x16x64_i8 v[44:47], v[172:175], v[204:207], v[44:47]
	v_mfma_i32_16x16x64_i8 v[32:35], v[164:167], v[214:217], v[32:35]
	v_mfma_i32_16x16x64_i8 v[28:31], v[172:175], v[214:217], v[28:31]
	v_mfma_i32_16x16x64_i8 v[16:19], v[164:167], v[226:229], v[16:19]
	v_mfma_i32_16x16x64_i8 v[12:15], v[172:175], v[226:229], v[12:15]
	v_mfma_i32_16x16x64_i8 v[56:59], v[176:179], v[192:195], v[56:59]
	v_mfma_i32_16x16x64_i8 v[52:55], v[184:187], v[192:195], v[52:55]
	v_mfma_i32_16x16x64_i8 v[40:43], v[176:179], v[200:203], v[40:43]
	v_mfma_i32_16x16x64_i8 v[36:39], v[184:187], v[200:203], v[36:39]
	v_mfma_i32_16x16x64_i8 v[24:27], v[176:179], v[210:213], v[24:27]
	v_mfma_i32_16x16x64_i8 v[20:23], v[184:187], v[210:213], v[20:23]
	v_mfma_i32_16x16x64_i8 v[8:11], v[176:179], v[218:221], v[8:11]
	v_mfma_i32_16x16x64_i8 v[4:7], v[184:187], v[218:221], v[4:7]
	v_mfma_i32_16x16x64_i8 v[56:59], v[180:183], v[196:199], v[56:59]
	v_mfma_i32_16x16x64_i8 v[52:55], v[188:191], v[196:199], v[52:55]
	v_mfma_i32_16x16x64_i8 v[40:43], v[180:183], v[204:207], v[40:43]
	v_mfma_i32_16x16x64_i8 v[36:39], v[188:191], v[204:207], v[36:39]
	v_mfma_i32_16x16x64_i8 v[24:27], v[180:183], v[214:217], v[24:27]
	v_mfma_i32_16x16x64_i8 v[20:23], v[188:191], v[214:217], v[20:23]
	v_mfma_i32_16x16x64_i8 v[8:11], v[180:183], v[226:229], v[8:11]
	v_mfma_i32_16x16x64_i8 v[4:7], v[188:191], v[226:229], v[4:7]
	s_setprio 0
	s_barrier
	s_add_i32 s38, s38, 2
	s_add_u32 s28, s28, 0x100
	s_addc_u32 s29, s29, 0
	s_cmp_gt_u32 s38, 29
	s_cbranch_scc0 .LBB0_783
	s_and_b64 vcc, exec, s[60:61]
	s_cbranch_vccz .LBB0_786
	s_barrier

; #define PG8_STAGE(bufoff, gbase, voff) do { _Pragma("unroll") for (int _i = 0; _i < 2; ++_i) \
;         __builtin_amdgcn_global_load_lds((const unsigned*)((const char*)(gbase) + (voff)[_i]), (LAS unsigned*)(lds + (bufoff) + ldsw + _i * 8192), 16, 0, 0); } while (0)
; #define PG8_LDA(dst, b, h) do { _Pragma("unroll") for (int m = 0; m < 4; ++m) _Pragma("unroll") for (int k = 0; k < 2; ++k) dst[m][k] = *(const LAS bf16x8*)(lds + PG8_SA(b, h) + aoff + m * 2048 + k * 1024); } while (0)
; #define PG8_LDB(dst, b, h) do { _Pragma("unroll") for (int n = 0; n < 2; ++n) _Pragma("unroll") for (int k = 0; k < 2; ++k) dst[n][k] = *(const LAS bf16x8*)(lds + PG8_SB(b, h) + boff + n * 2048 + k * 1024); } while (0)
; #define PG8_WAIT_V(n) asm volatile("s_waitcnt vmcnt(" #n ")" ::: "memory")
; #define PG8_WAIT_L(n) asm volatile("s_waitcnt lgkmcnt(" #n ")" ::: "memory")
; #define PG8_BAR __builtin_amdgcn_s_barrier()
;     ...
;         for (int t = 0; t < nt; t += 2) {
;             const bool last = (t == nt - 2);
;             const char* a1 = cA + (size_t)(t + 1) * kstep;
;             const char* a2 = last ? nA : cA + (size_t)(t + 2) * kstep; const char* b2 = last ? nB : cB + (size_t)(t + 2) * kstep;
;             const char* a3 = a2 + kstep; const char* b3 = b2 + kstep;
;             if constexpr (SP2) {
;             PG8_LDB(B0, 0, 0); PG8_LDB(B1, 0, 1); PG8_SCHED; PG8_LDA(At, 0, 0); PG8_STAGE(PG8_SA(1, 1), a1 + hstepA, voffA);
;             PG8_WAIT_V(8); PG8_WAIT_L(0); PG8_BAR; PG8_MMA(0, 0, At, B0); PG8_MMA(0, 1, At, B1); PG8_BAR; PG8_SCHED;
;             PG8_LDA(At, 0, 1); PG8_STAGE(PG8_SB(0, 0), b2, voffB); PG8_STAGE(PG8_SB(0, 1), b2 + hstepB, voffB); PG8_STAGE(PG8_SA(0, 0), a2, voffA);
;             PG8_WAIT_V(8); PG8_WAIT_L(0); PG8_BAR; PG8_MMA(1, 0, At, B0); PG8_MMA(1, 1, At, B1); PG8_BAR; PG8_SCHED;
; __global__ void __launch_bounds__(NWAVES * 64, 2) fwd(Args args) {
;     ...
;             pg8::Gemm g{(bf16_t*)(ws + WS_O), (bf16_t*)(ws + WS_WMP), MG, D, D / 2, D / 2, D / 2, 0, 0}; pg8::StaticOrder S; S.init(MG, D, G, bx, 1);
;             pg8::EpiGate<true, true> E{(bf16_t*)(ws + WS_XN), D, (const bf16_t*)(ws + WS_Z) + ZC_GATE + D, NZ, (const bf16_t*)(ws + WS_XC), D, 1.0f / (64.0f * att::OSCALE), MERGED_QS, nullptr};
;             pg8::gemm_phase<pg8::EpiGate<true, true>, pg8::StaticOrder, true, true, 1>(lds + RING_OFF, g, S, E, tid);
.LBB0_818:
	s_add_i32 s43, 0, 0x10000
	v_lshl_add_u64 v[4:5], v[180:181], 0, s[28:29]
	s_cmpk_eq_i32 s28, 0xf00
	v_lshl_add_u64 v[4:5], v[4:5], 0, s[4:5]
	s_cselect_b64 vcc, -1, 0
	s_add_i32 s75, 0, 0x14000
	v_lshl_add_u64 v[6:7], v[186:187], 0, s[28:29]
	v_cndmask_b32_e32 v188, v4, v176, vcc
	v_cndmask_b32_e32 v189, v5, v177, vcc
	ds_read_b128 v[28:31], v213
	ds_read_b128 v[32:35], v213 offset:1024
	ds_read_b128 v[20:23], v213 offset:2048
	ds_read_b128 v[24:27], v213 offset:3072
	v_cndmask_b32_e32 v207, v7, v179, vcc
	v_cndmask_b32_e32 v206, v6, v178, vcc
	ds_read_b128 v[12:15], v250
	ds_read_b128 v[16:19], v250 offset:1024
	ds_read_b128 v[4:7], v250 offset:2048
	ds_read_b128 v[8:11], v250 offset:3072
	v_lshl_add_u64 v[234:235], v[184:185], 0, s[28:29]
	s_add_i32 m0, s57, 0xc000
	ds_read_b128 v[190:193], v212
	ds_read_b128 v[194:197], v212 offset:1024
	ds_read_b128 v[198:201], v212 offset:2048
	ds_read_b128 v[202:205], v212 offset:3072
	ds_read_b128 v[214:217], v212 offset:4096
	ds_read_b128 v[218:221], v212 offset:5120
	ds_read_b128 v[226:229], v212 offset:6144
	ds_read_b128 v[230:233], v212 offset:7168
	global_load_lds_dwordx4 v[234:235], off
	v_lshl_add_u64 v[234:235], v[182:183], 0, s[28:29]
	s_add_i32 m0, s57, 0xe000
	s_nop 0
	global_load_lds_dwordx4 v[234:235], off
	s_waitcnt vmcnt(8)
	s_waitcnt lgkmcnt(0)
	s_barrier
	s_setprio 1
	v_mfma_f32_16x16x128_f8f6f4 v[160:163], v[28:35], v[190:197], v[160:163]
	v_mfma_f32_16x16x128_f8f6f4 v[156:159], v[20:27], v[190:197], v[156:159]
	v_mfma_f32_16x16x128_f8f6f4 v[144:147], v[28:35], v[198:205], v[144:147]
	v_mfma_f32_16x16x128_f8f6f4 v[140:143], v[20:27], v[198:205], v[140:143]
	v_mfma_f32_16x16x128_f8f6f4 v[128:131], v[28:35], v[214:221], v[128:131]
	v_mfma_f32_16x16x128_f8f6f4 v[124:127], v[20:27], v[214:221], v[124:127]
	v_mfma_f32_16x16x128_f8f6f4 v[112:115], v[28:35], v[226:233], v[112:115]
	v_mfma_f32_16x16x128_f8f6f4 v[108:111], v[20:27], v[226:233], v[108:111]
	v_mfma_f32_16x16x128_f8f6f4 v[152:155], v[12:19], v[190:197], v[152:155]
	v_mfma_f32_16x16x128_f8f6f4 v[148:151], v[4:11], v[190:197], v[148:151]
	v_mfma_f32_16x16x128_f8f6f4 v[136:139], v[12:19], v[198:205], v[136:139]
	v_mfma_f32_16x16x128_f8f6f4 v[132:135], v[4:11], v[198:205], v[132:135]
	v_mfma_f32_16x16x128_f8f6f4 v[120:123], v[12:19], v[214:221], v[120:123]
	v_mfma_f32_16x16x128_f8f6f4 v[116:119], v[4:11], v[214:221], v[116:119]
	v_mfma_f32_16x16x128_f8f6f4 v[104:107], v[12:19], v[226:233], v[104:107]
	v_mfma_f32_16x16x128_f8f6f4 v[100:103], v[4:11], v[226:233], v[100:103]
	s_setprio 0
	s_barrier
	s_add_i32 s43, s43, s33
	v_lshl_add_u64 v[190:191], v[206:207], 0, v[2:3]
	s_mov_b32 m0, s43
	ds_read_b128 v[214:217], v212 offset:16384
	ds_read_b128 v[218:221], v212 offset:17408
	ds_read_b128 v[226:229], v212 offset:18432
	ds_read_b128 v[230:233], v212 offset:19456
	ds_read_b128 v[234:237], v212 offset:20480
	ds_read_b128 v[238:241], v212 offset:21504
	ds_read_b128 v[242:245], v212 offset:22528
	ds_read_b128 v[246:249], v212 offset:23552
	global_load_lds_dwordx4 v[190:191], off
	v_lshl_add_u64 v[192:193], v[206:207], 0, v[166:167]
	s_add_i32 m0, s43, 0x2000
	v_lshl_add_u64 v[196:197], v[206:207], 0, v[170:171]
	s_add_i32 s43, s75, s33
	global_load_lds_dwordx4 v[192:193], off
	v_lshl_add_u64 v[194:195], v[196:197], 0, v[2:3]
	s_mov_b32 m0, s43
	v_lshl_add_u64 v[196:197], v[196:197], 0, v[166:167]
	global_load_lds_dwordx4 v[194:195], off
	s_add_i32 m0, s43, 0x2000
	v_lshl_add_u64 v[198:199], v[188:189], 0, v[0:1]
	global_load_lds_dwordx4 v[196:197], off
	s_mov_b32 m0, s57
	v_lshl_add_u64 v[200:201], v[188:189], 0, v[164:165]
	global_load_lds_dwordx4 v[198:199], off
	s_mov_b32 m0, s62
	s_nop 0
	global_load_lds_dwordx4 v[200:201], off
	s_waitcnt vmcnt(8)
	s_waitcnt lgkmcnt(0)
	s_barrier
	s_setprio 1
	v_mfma_f32_16x16x128_f8f6f4 v[96:99], v[28:35], v[214:221], v[96:99]
	v_mfma_f32_16x16x128_f8f6f4 v[92:95], v[20:27], v[214:221], v[92:95]
	v_mfma_f32_16x16x128_f8f6f4 v[80:83], v[28:35], v[226:233], v[80:83]
	v_mfma_f32_16x16x128_f8f6f4 v[76:79], v[20:27], v[226:233], v[76:79]
	v_mfma_f32_16x16x128_f8f6f4 v[64:67], v[28:35], v[234:241], v[64:67]
	v_mfma_f32_16x16x128_f8f6f4 v[60:63], v[20:27], v[234:241], v[60:63]
	v_mfma_f32_16x16x128_f8f6f4 v[48:51], v[28:35], v[242:249], v[48:51]
	v_mfma_f32_16x16x128_f8f6f4 v[44:47], v[20:27], v[242:249], v[44:47]
	v_mfma_f32_16x16x128_f8f6f4 v[88:91], v[12:19], v[214:221], v[88:91]
	v_mfma_f32_16x16x128_f8f6f4 v[84:87], v[4:11], v[214:221], v[84:87]
	v_mfma_f32_16x16x128_f8f6f4 v[72:75], v[12:19], v[226:233], v[72:75]
	v_mfma_f32_16x16x128_f8f6f4 v[68:71], v[4:11], v[226:233], v[68:71]
	v_mfma_f32_16x16x128_f8f6f4 v[56:59], v[12:19], v[234:241], v[56:59]
	v_mfma_f32_16x16x128_f8f6f4 v[52:55], v[4:11], v[234:241], v[52:55]
	v_mfma_f32_16x16x128_f8f6f4 v[40:43], v[12:19], v[242:249], v[40:43]
	v_mfma_f32_16x16x128_f8f6f4 v[36:39], v[4:11], v[242:249], v[36:39]
	s_setprio 0
	s_barrier
; #define PG8_STAGE(bufoff, gbase, voff) do { _Pragma("unroll") for (int _i = 0; _i < 2; ++_i) \
;         __builtin_amdgcn_global_load_lds((const unsigned*)((const char*)(gbase) + (voff)[_i]), (LAS unsigned*)(lds + (bufoff) + ldsw + _i * 8192), 16, 0, 0); } while (0)
; #define PG8_LDA(dst, b, h) do { _Pragma("unroll") for (int m = 0; m < 4; ++m) _Pragma("unroll") for (int k = 0; k < 2; ++k) dst[m][k] = *(const LAS bf16x8*)(lds + PG8_SA(b, h) + aoff + m * 2048 + k * 1024); } while (0)
; #define PG8_LDB(dst, b, h) do { _Pragma("unroll") for (int n = 0; n < 2; ++n) _Pragma("unroll") for (int k = 0; k < 2; ++k) dst[n][k] = *(const LAS bf16x8*)(lds + PG8_SB(b, h) + boff + n * 2048 + k * 1024); } while (0)
; #define PG8_WAIT_V(n) asm volatile("s_waitcnt vmcnt(" #n ")" ::: "memory")
; #define PG8_WAIT_L(n) asm volatile("s_waitcnt lgkmcnt(" #n ")" ::: "memory")
; #define PG8_BAR __builtin_amdgcn_s_barrier()
; #define PG8_SCHED __builtin_amdgcn_sched_barrier(0)
;     ...
;             PG8_WAIT_V(8); PG8_WAIT_L(0); PG8_BAR; PG8_MMA(1, 0, At, B0); PG8_MMA(1, 1, At, B1); PG8_BAR; PG8_SCHED;
;             PG8_LDB(B0, 1, 0); PG8_LDB(B1, 1, 1); PG8_SCHED; PG8_LDA(At, 1, 0); PG8_STAGE(PG8_SA(0, 1), a2 + hstepA, voffA);
;             PG8_WAIT_V(8); PG8_WAIT_L(0); PG8_BAR; PG8_MMA(0, 0, At, B0); PG8_MMA(0, 1, At, B1); PG8_BAR; PG8_SCHED;
;             PG8_LDA(At, 1, 1); PG8_STAGE(PG8_SB(1, 0), b3, voffB); PG8_STAGE(PG8_SB(1, 1), b3 + hstepB, voffB); PG8_STAGE(PG8_SA(1, 0), a3, voffA);
;             PG8_WAIT_V(8); PG8_WAIT_L(0); PG8_BAR; PG8_MMA(1, 0, At, B0); PG8_MMA(1, 1, At, B1); PG8_BAR; PG8_SCHED;
	s_add_i32 s43, 0, 0x18000
	s_add_i32 s75, 0, 0x1c000
	v_add_u32_e32 v32, s75, v210
	ds_read_b128 v[4:7], v251
	ds_read_b128 v[8:11], v251 offset:1024
	ds_read_b128 v[12:15], v251 offset:2048
	ds_read_b128 v[16:19], v251 offset:3072
	ds_read_b128 v[20:23], v32
	ds_read_b128 v[24:27], v32 offset:1024
	ds_read_b128 v[28:31], v32 offset:2048
	ds_read_b128 v[32:35], v32 offset:3072
	v_lshl_add_u64 v[188:189], v[188:189], 0, v[168:169]
	s_mov_b32 m0, s63
	v_lshl_add_u64 v[202:203], v[188:189], 0, v[0:1]
	ds_read_b128 v[214:217], v212 offset:32768
	ds_read_b128 v[218:221], v212 offset:33792
	ds_read_b128 v[226:229], v212 offset:34816
	ds_read_b128 v[230:233], v212 offset:35840
	ds_read_b128 v[234:237], v212 offset:36864
	ds_read_b128 v[238:241], v212 offset:37888
	ds_read_b128 v[242:245], v212 offset:38912
	ds_read_b128 v[246:249], v212 offset:39936
	global_load_lds_dwordx4 v[202:203], off
	v_lshl_add_u64 v[188:189], v[188:189], 0, v[164:165]
	s_mov_b32 m0, s64
	s_nop 0
	global_load_lds_dwordx4 v[188:189], off
	s_waitcnt vmcnt(8)
	s_waitcnt lgkmcnt(0)
	s_barrier
	s_setprio 1
	v_mfma_f32_16x16x128_f8f6f4 v[160:163], v[4:11], v[214:221], v[160:163]
	v_mfma_f32_16x16x128_f8f6f4 v[156:159], v[12:19], v[214:221], v[156:159]
	v_mfma_f32_16x16x128_f8f6f4 v[144:147], v[4:11], v[226:233], v[144:147]
	v_mfma_f32_16x16x128_f8f6f4 v[140:143], v[12:19], v[226:233], v[140:143]
	v_mfma_f32_16x16x128_f8f6f4 v[128:131], v[4:11], v[234:241], v[128:131]
	v_mfma_f32_16x16x128_f8f6f4 v[124:127], v[12:19], v[234:241], v[124:127]
	v_mfma_f32_16x16x128_f8f6f4 v[112:115], v[4:11], v[242:249], v[112:115]
	v_mfma_f32_16x16x128_f8f6f4 v[108:111], v[12:19], v[242:249], v[108:111]
	v_mfma_f32_16x16x128_f8f6f4 v[152:155], v[20:27], v[214:221], v[152:155]
	v_mfma_f32_16x16x128_f8f6f4 v[148:151], v[28:35], v[214:221], v[148:151]
	v_mfma_f32_16x16x128_f8f6f4 v[136:139], v[20:27], v[226:233], v[136:139]
	v_mfma_f32_16x16x128_f8f6f4 v[132:135], v[28:35], v[226:233], v[132:135]
	v_mfma_f32_16x16x128_f8f6f4 v[120:123], v[20:27], v[234:241], v[120:123]
	v_mfma_f32_16x16x128_f8f6f4 v[116:119], v[28:35], v[234:241], v[116:119]
	v_mfma_f32_16x16x128_f8f6f4 v[104:107], v[20:27], v[242:249], v[104:107]
	v_mfma_f32_16x16x128_f8f6f4 v[100:103], v[28:35], v[242:249], v[100:103]
	s_setprio 0
	s_barrier
	s_add_i32 s43, s43, s33
	s_add_i32 m0, s43, 0xffffff80
	ds_read_b128 v[214:217], v212 offset:49152
	ds_read_b128 v[218:221], v212 offset:50176
	ds_read_b128 v[226:229], v212 offset:51200
	ds_read_b128 v[230:233], v212 offset:52224
	ds_read_b128 v[234:237], v212 offset:53248
	ds_read_b128 v[238:241], v212 offset:54272
	ds_read_b128 v[242:245], v212 offset:55296
	ds_read_b128 v[246:249], v212 offset:56320
	global_load_lds_dwordx4 v[190:191], off offset:128
	s_add_i32 m0, s43, 0x1f80
	s_add_i32 s43, s75, s33
	global_load_lds_dwordx4 v[192:193], off offset:128
	s_add_i32 m0, s43, 0xffffff80
	s_nop 0
	global_load_lds_dwordx4 v[194:195], off offset:128
	s_add_i32 m0, s43, 0x1f80
	s_nop 0
	global_load_lds_dwordx4 v[196:197], off offset:128
	s_add_i32 m0, s65, 0xffffff80
	s_nop 0
	global_load_lds_dwordx4 v[198:199], off offset:128
	s_add_i32 m0, s66, 0xffffff80
	s_nop 0
	global_load_lds_dwordx4 v[200:201], off offset:128
	s_waitcnt vmcnt(8)
	s_waitcnt lgkmcnt(0)
	s_barrier
	s_setprio 1
	v_mfma_f32_16x16x128_f8f6f4 v[96:99], v[4:11], v[214:221], v[96:99]
	v_mfma_f32_16x16x128_f8f6f4 v[92:95], v[12:19], v[214:221], v[92:95]
	v_mfma_f32_16x16x128_f8f6f4 v[80:83], v[4:11], v[226:233], v[80:83]
	v_mfma_f32_16x16x128_f8f6f4 v[76:79], v[12:19], v[226:233], v[76:79]
	v_mfma_f32_16x16x128_f8f6f4 v[64:67], v[4:11], v[234:241], v[64:67]
	v_mfma_f32_16x16x128_f8f6f4 v[60:63], v[12:19], v[234:241], v[60:63]
	v_mfma_f32_16x16x128_f8f6f4 v[48:51], v[4:11], v[242:249], v[48:51]
	v_mfma_f32_16x16x128_f8f6f4 v[44:47], v[12:19], v[242:249], v[44:47]
	v_mfma_f32_16x16x128_f8f6f4 v[88:91], v[20:27], v[214:221], v[88:91]
	v_mfma_f32_16x16x128_f8f6f4 v[84:87], v[28:35], v[214:221], v[84:87]
	v_mfma_f32_16x16x128_f8f6f4 v[72:75], v[20:27], v[226:233], v[72:75]
	v_mfma_f32_16x16x128_f8f6f4 v[68:71], v[28:35], v[226:233], v[68:71]
	v_mfma_f32_16x16x128_f8f6f4 v[56:59], v[20:27], v[234:241], v[56:59]
	v_mfma_f32_16x16x128_f8f6f4 v[52:55], v[28:35], v[234:241], v[52:55]
	v_mfma_f32_16x16x128_f8f6f4 v[40:43], v[20:27], v[242:249], v[40:43]
	v_mfma_f32_16x16x128_f8f6f4 v[36:39], v[28:35], v[242:249], v[36:39]
	s_setprio 0
	s_barrier
	s_add_i32 s42, s42, 2
	s_add_u32 s28, s28, 0x100
	s_addc_u32 s29, s29, 0
	s_cmp_gt_u32 s42, 29
	s_cbranch_scc0 .LBB0_818
	s_and_b64 vcc, exec, s[60:61]
	s_cbranch_vccz .LBB0_821
	s_barrier

; #define PG8_STAGE(bufoff, gbase, voff) do { _Pragma("unroll") for (int _i = 0; _i < 2; ++_i) \
;         __builtin_amdgcn_global_load_lds((const unsigned*)((const char*)(gbase) + (voff)[_i]), (LAS unsigned*)(lds + (bufoff) + ldsw + _i * 8192), 16, 0, 0); } while (0)
; #define PG8_LDA(dst, b, h) do { _Pragma("unroll") for (int m = 0; m < 4; ++m) _Pragma("unroll") for (int k = 0; k < 2; ++k) dst[m][k] = *(const LAS bf16x8*)(lds + PG8_SA(b, h) + aoff + m * 2048 + k * 1024); } while (0)
; #define PG8_LDB(dst, b, h) do { _Pragma("unroll") for (int n = 0; n < 2; ++n) _Pragma("unroll") for (int k = 0; k < 2; ++k) dst[n][k] = *(const LAS bf16x8*)(lds + PG8_SB(b, h) + boff + n * 2048 + k * 1024); } while (0)
; #define PG8_WAIT_V(n) asm volatile("s_waitcnt vmcnt(" #n ")" ::: "memory")
; #define PG8_WAIT_L(n) asm volatile("s_waitcnt lgkmcnt(" #n ")" ::: "memory")
; #define PG8_BAR __builtin_amdgcn_s_barrier()
; #define PG8_SCHED __builtin_amdgcn_sched_barrier(0)
;     ...
;         for (int t = 0; t < nt; t += 2) {
;             const bool last = (t == nt - 2);
;             const char* a1 = cA + (size_t)(t + 1) * kstep;
;             const char* a2 = last ? nA : cA + (size_t)(t + 2) * kstep; const char* b2 = last ? nB : cB + (size_t)(t + 2) * kstep;
;             const char* a3 = a2 + kstep; const char* b3 = b2 + kstep;
;             if constexpr (SP2) {
;             PG8_LDB(B0, 0, 0); PG8_LDB(B1, 0, 1); PG8_SCHED; PG8_LDA(At, 0, 0); PG8_STAGE(PG8_SA(1, 1), a1 + hstepA, voffA);
;             PG8_WAIT_V(8); PG8_WAIT_L(0); PG8_BAR; PG8_MMA(0, 0, At, B0); PG8_MMA(0, 1, At, B1); PG8_BAR; PG8_SCHED;
;             PG8_LDA(At, 0, 1); PG8_STAGE(PG8_SB(0, 0), b2, voffB); PG8_STAGE(PG8_SB(0, 1), b2 + hstepB, voffB); PG8_STAGE(PG8_SA(0, 0), a2, voffA);
;             PG8_WAIT_V(8); PG8_WAIT_L(0); PG8_BAR; PG8_MMA(1, 0, At, B0); PG8_MMA(1, 1, At, B1); PG8_BAR; PG8_SCHED;
.LBB0_912:
	s_add_i32 s59, 0, 0x10000
	v_lshl_add_u64 v[162:163], v[148:149], 0, s[38:39]
	s_cmpk_eq_i32 s38, 0xf00
	v_lshl_add_u64 v[162:163], v[162:163], 0, s[4:5]
	s_cselect_b64 vcc, -1, 0
	s_add_i32 s75, 0, 0x14000
	v_lshl_add_u64 v[178:179], v[154:155], 0, s[38:39]
	v_cndmask_b32_e32 v231, v163, v145, vcc
	v_cndmask_b32_e32 v230, v162, v144, vcc
	ds_read_b128 v[162:165], v246
	ds_read_b128 v[166:169], v246 offset:1024
	ds_read_b128 v[170:173], v246 offset:2048
	ds_read_b128 v[174:177], v246 offset:3072
	v_cndmask_b32_e32 v233, v179, v147, vcc
	v_cndmask_b32_e32 v232, v178, v146, vcc
	ds_read_b128 v[178:181], v247
	ds_read_b128 v[182:185], v247 offset:1024
	ds_read_b128 v[186:189], v247 offset:2048
	ds_read_b128 v[190:193], v247 offset:3072
	v_lshl_add_u64 v[234:235], v[152:153], 0, s[38:39]
	s_add_i32 m0, s60, 0xc000
	ds_read_b128 v[194:197], v160
	ds_read_b128 v[198:201], v160 offset:1024
	ds_read_b128 v[202:205], v160 offset:2048
	ds_read_b128 v[206:209], v160 offset:3072
	ds_read_b128 v[210:213], v160 offset:4096
	ds_read_b128 v[214:217], v160 offset:5120
	ds_read_b128 v[218:221], v160 offset:6144
	ds_read_b128 v[226:229], v160 offset:7168
	global_load_lds_dwordx4 v[234:235], off
	v_lshl_add_u64 v[234:235], v[150:151], 0, s[38:39]
	s_add_i32 m0, s60, 0xe000
	s_nop 0
	global_load_lds_dwordx4 v[234:235], off
	s_waitcnt vmcnt(8)
	s_waitcnt lgkmcnt(0)
	s_barrier
	s_setprio 1
	v_mfma_i32_16x16x64_i8 v[128:131], v[162:165], v[194:197], v[128:131]
	v_mfma_i32_16x16x64_i8 v[124:127], v[170:173], v[194:197], v[124:127]
	v_mfma_i32_16x16x64_i8 v[120:123], v[162:165], v[202:205], v[120:123]
	v_mfma_i32_16x16x64_i8 v[116:119], v[170:173], v[202:205], v[116:119]
	v_mfma_i32_16x16x64_i8 v[112:115], v[162:165], v[210:213], v[112:115]
	v_mfma_i32_16x16x64_i8 v[108:111], v[170:173], v[210:213], v[108:111]
	v_mfma_i32_16x16x64_i8 v[104:107], v[162:165], v[218:221], v[104:107]
	v_mfma_i32_16x16x64_i8 v[100:103], v[170:173], v[218:221], v[100:103]
	v_mfma_i32_16x16x64_i8 v[128:131], v[166:169], v[198:201], v[128:131]
	v_mfma_i32_16x16x64_i8 v[124:127], v[174:177], v[198:201], v[124:127]
	v_mfma_i32_16x16x64_i8 v[120:123], v[166:169], v[206:209], v[120:123]
	v_mfma_i32_16x16x64_i8 v[116:119], v[174:177], v[206:209], v[116:119]
	v_mfma_i32_16x16x64_i8 v[112:115], v[166:169], v[214:217], v[112:115]
	v_mfma_i32_16x16x64_i8 v[108:111], v[174:177], v[214:217], v[108:111]
	v_mfma_i32_16x16x64_i8 v[104:107], v[166:169], v[226:229], v[104:107]
	v_mfma_i32_16x16x64_i8 v[100:103], v[174:177], v[226:229], v[100:103]
	v_mfma_i32_16x16x64_i8 v[96:99], v[178:181], v[194:197], v[96:99]
	v_mfma_i32_16x16x64_i8 v[92:95], v[186:189], v[194:197], v[92:95]
	v_mfma_i32_16x16x64_i8 v[88:91], v[178:181], v[202:205], v[88:91]
	v_mfma_i32_16x16x64_i8 v[84:87], v[186:189], v[202:205], v[84:87]
	v_mfma_i32_16x16x64_i8 v[80:83], v[178:181], v[210:213], v[80:83]
	v_mfma_i32_16x16x64_i8 v[76:79], v[186:189], v[210:213], v[76:79]
	v_mfma_i32_16x16x64_i8 v[72:75], v[178:181], v[218:221], v[72:75]
	v_mfma_i32_16x16x64_i8 v[68:71], v[186:189], v[218:221], v[68:71]
	v_mfma_i32_16x16x64_i8 v[96:99], v[182:185], v[198:201], v[96:99]
	v_mfma_i32_16x16x64_i8 v[92:95], v[190:193], v[198:201], v[92:95]
	v_mfma_i32_16x16x64_i8 v[88:91], v[182:185], v[206:209], v[88:91]
	v_mfma_i32_16x16x64_i8 v[84:87], v[190:193], v[206:209], v[84:87]
	v_mfma_i32_16x16x64_i8 v[80:83], v[182:185], v[214:217], v[80:83]
	v_mfma_i32_16x16x64_i8 v[76:79], v[190:193], v[214:217], v[76:79]
	v_mfma_i32_16x16x64_i8 v[72:75], v[182:185], v[226:229], v[72:75]
	v_mfma_i32_16x16x64_i8 v[68:71], v[190:193], v[226:229], v[68:71]
	s_setprio 0
	s_barrier
	s_add_i32 s59, s59, s57
	v_lshl_add_u64 v[234:235], v[232:233], 0, v[2:3]
	s_mov_b32 m0, s59
	ds_read_b128 v[194:197], v160 offset:16384
	ds_read_b128 v[198:201], v160 offset:17408
	ds_read_b128 v[202:205], v160 offset:18432
	ds_read_b128 v[206:209], v160 offset:19456
	ds_read_b128 v[210:213], v160 offset:20480
	ds_read_b128 v[214:217], v160 offset:21504
	ds_read_b128 v[218:221], v160 offset:22528
	ds_read_b128 v[226:229], v160 offset:23552
	global_load_lds_dwordx4 v[234:235], off
	v_lshl_add_u64 v[236:237], v[232:233], 0, v[134:135]
	s_add_i32 m0, s59, 0x2000
	v_lshl_add_u64 v[232:233], v[232:233], 0, v[138:139]
	s_add_i32 s59, s75, s57
	global_load_lds_dwordx4 v[236:237], off
	v_lshl_add_u64 v[238:239], v[232:233], 0, v[2:3]
	s_mov_b32 m0, s59
	v_lshl_add_u64 v[232:233], v[232:233], 0, v[134:135]
	global_load_lds_dwordx4 v[238:239], off
	s_add_i32 m0, s59, 0x2000
	v_lshl_add_u64 v[240:241], v[230:231], 0, v[0:1]
	global_load_lds_dwordx4 v[232:233], off
	s_mov_b32 m0, s60
	v_lshl_add_u64 v[242:243], v[230:231], 0, v[132:133]
	global_load_lds_dwordx4 v[240:241], off
	s_mov_b32 m0, s61
	s_nop 0
	global_load_lds_dwordx4 v[242:243], off
	s_waitcnt vmcnt(8)
	s_waitcnt lgkmcnt(0)
	s_barrier
; #define PG8_STAGE(bufoff, gbase, voff) do { _Pragma("unroll") for (int _i = 0; _i < 2; ++_i) \
;         __builtin_amdgcn_global_load_lds((const unsigned*)((const char*)(gbase) + (voff)[_i]), (LAS unsigned*)(lds + (bufoff) + ldsw + _i * 8192), 16, 0, 0); } while (0)
; #define PG8_LDA(dst, b, h) do { _Pragma("unroll") for (int m = 0; m < 4; ++m) _Pragma("unroll") for (int k = 0; k < 2; ++k) dst[m][k] = *(const LAS bf16x8*)(lds + PG8_SA(b, h) + aoff + m * 2048 + k * 1024); } while (0)
; #define PG8_LDB(dst, b, h) do { _Pragma("unroll") for (int n = 0; n < 2; ++n) _Pragma("unroll") for (int k = 0; k < 2; ++k) dst[n][k] = *(const LAS bf16x8*)(lds + PG8_SB(b, h) + boff + n * 2048 + k * 1024); } while (0)
; #define PG8_WAIT_V(n) asm volatile("s_waitcnt vmcnt(" #n ")" ::: "memory")
; #define PG8_WAIT_L(n) asm volatile("s_waitcnt lgkmcnt(" #n ")" ::: "memory")
; #define PG8_BAR __builtin_amdgcn_s_barrier()
; #define PG8_SCHED __builtin_amdgcn_sched_barrier(0)
;     ...
;             PG8_WAIT_V(8); PG8_WAIT_L(0); PG8_BAR; PG8_MMA(1, 0, At, B0); PG8_MMA(1, 1, At, B1); PG8_BAR; PG8_SCHED;
;             PG8_LDB(B0, 1, 0); PG8_LDB(B1, 1, 1); PG8_SCHED; PG8_LDA(At, 1, 0); PG8_STAGE(PG8_SA(0, 1), a2 + hstepA, voffA);
;             PG8_WAIT_V(8); PG8_WAIT_L(0); PG8_BAR; PG8_MMA(0, 0, At, B0); PG8_MMA(0, 1, At, B1); PG8_BAR; PG8_SCHED;
;             PG8_LDA(At, 1, 1); PG8_STAGE(PG8_SB(1, 0), b3, voffB); PG8_STAGE(PG8_SB(1, 1), b3 + hstepB, voffB); PG8_STAGE(PG8_SA(1, 0), a3, voffA);
	s_setprio 1
	v_mfma_i32_16x16x64_i8 v[64:67], v[162:165], v[194:197], v[64:67]
	v_mfma_i32_16x16x64_i8 v[60:63], v[170:173], v[194:197], v[60:63]
	v_mfma_i32_16x16x64_i8 v[56:59], v[162:165], v[202:205], v[56:59]
	v_mfma_i32_16x16x64_i8 v[52:55], v[170:173], v[202:205], v[52:55]
	v_mfma_i32_16x16x64_i8 v[48:51], v[162:165], v[210:213], v[48:51]
	v_mfma_i32_16x16x64_i8 v[44:47], v[170:173], v[210:213], v[44:47]
	v_mfma_i32_16x16x64_i8 v[40:43], v[162:165], v[218:221], v[40:43]
	v_mfma_i32_16x16x64_i8 v[36:39], v[170:173], v[218:221], v[36:39]
	v_mfma_i32_16x16x64_i8 v[64:67], v[166:169], v[198:201], v[64:67]
	v_mfma_i32_16x16x64_i8 v[60:63], v[174:177], v[198:201], v[60:63]
	v_mfma_i32_16x16x64_i8 v[56:59], v[166:169], v[206:209], v[56:59]
	v_mfma_i32_16x16x64_i8 v[52:55], v[174:177], v[206:209], v[52:55]
	v_mfma_i32_16x16x64_i8 v[48:51], v[166:169], v[214:217], v[48:51]
	v_mfma_i32_16x16x64_i8 v[44:47], v[174:177], v[214:217], v[44:47]
	v_mfma_i32_16x16x64_i8 v[40:43], v[166:169], v[226:229], v[40:43]
	v_mfma_i32_16x16x64_i8 v[36:39], v[174:177], v[226:229], v[36:39]
	v_mfma_i32_16x16x64_i8 v[32:35], v[178:181], v[194:197], v[32:35]
	v_mfma_i32_16x16x64_i8 v[28:31], v[186:189], v[194:197], v[28:31]
	v_mfma_i32_16x16x64_i8 v[24:27], v[178:181], v[202:205], v[24:27]
	v_mfma_i32_16x16x64_i8 v[20:23], v[186:189], v[202:205], v[20:23]
	v_mfma_i32_16x16x64_i8 v[16:19], v[178:181], v[210:213], v[16:19]
	v_mfma_i32_16x16x64_i8 v[12:15], v[186:189], v[210:213], v[12:15]
	v_mfma_i32_16x16x64_i8 v[8:11], v[178:181], v[218:221], v[8:11]
	v_mfma_i32_16x16x64_i8 v[4:7], v[186:189], v[218:221], v[4:7]
	v_mfma_i32_16x16x64_i8 v[32:35], v[182:185], v[198:201], v[32:35]
	v_mfma_i32_16x16x64_i8 v[28:31], v[190:193], v[198:201], v[28:31]
	v_mfma_i32_16x16x64_i8 v[24:27], v[182:185], v[206:209], v[24:27]
	v_mfma_i32_16x16x64_i8 v[20:23], v[190:193], v[206:209], v[20:23]
	v_mfma_i32_16x16x64_i8 v[16:19], v[182:185], v[214:217], v[16:19]
	v_mfma_i32_16x16x64_i8 v[12:15], v[190:193], v[214:217], v[12:15]
	v_mfma_i32_16x16x64_i8 v[8:11], v[182:185], v[226:229], v[8:11]
	v_mfma_i32_16x16x64_i8 v[4:7], v[190:193], v[226:229], v[4:7]
	s_setprio 0
	s_barrier
	s_add_i32 s59, 0, 0x18000
	s_add_i32 s75, 0, 0x1c000
	ds_read_b128 v[162:165], v248
	ds_read_b128 v[166:169], v248 offset:1024
	ds_read_b128 v[170:173], v248 offset:2048
	ds_read_b128 v[174:177], v248 offset:3072
	ds_read_b128 v[178:181], v249
	ds_read_b128 v[182:185], v249 offset:1024
	ds_read_b128 v[186:189], v249 offset:2048
	ds_read_b128 v[190:193], v249 offset:3072
	v_lshl_add_u64 v[230:231], v[230:231], 0, v[136:137]
	s_mov_b32 m0, s62
	v_lshl_add_u64 v[244:245], v[230:231], 0, v[0:1]
	ds_read_b128 v[194:197], v160 offset:32768
	ds_read_b128 v[198:201], v160 offset:33792
	ds_read_b128 v[202:205], v160 offset:34816
	ds_read_b128 v[206:209], v160 offset:35840
	ds_read_b128 v[210:213], v160 offset:36864
	ds_read_b128 v[214:217], v160 offset:37888
	ds_read_b128 v[218:221], v160 offset:38912
	ds_read_b128 v[226:229], v160 offset:39936
	global_load_lds_dwordx4 v[244:245], off
	v_lshl_add_u64 v[230:231], v[230:231], 0, v[132:133]
	s_mov_b32 m0, s63
	s_nop 0
	global_load_lds_dwordx4 v[230:231], off
	s_waitcnt vmcnt(8)
	s_waitcnt lgkmcnt(0)
	s_barrier
	s_setprio 1
	v_mfma_i32_16x16x64_i8 v[128:131], v[162:165], v[194:197], v[128:131]
	v_mfma_i32_16x16x64_i8 v[124:127], v[170:173], v[194:197], v[124:127]
	v_mfma_i32_16x16x64_i8 v[120:123], v[162:165], v[202:205], v[120:123]
	v_mfma_i32_16x16x64_i8 v[116:119], v[170:173], v[202:205], v[116:119]
	v_mfma_i32_16x16x64_i8 v[112:115], v[162:165], v[210:213], v[112:115]
	v_mfma_i32_16x16x64_i8 v[108:111], v[170:173], v[210:213], v[108:111]
	v_mfma_i32_16x16x64_i8 v[104:107], v[162:165], v[218:221], v[104:107]
	v_mfma_i32_16x16x64_i8 v[100:103], v[170:173], v[218:221], v[100:103]
	v_mfma_i32_16x16x64_i8 v[128:131], v[166:169], v[198:201], v[128:131]
	v_mfma_i32_16x16x64_i8 v[124:127], v[174:177], v[198:201], v[124:127]
	v_mfma_i32_16x16x64_i8 v[120:123], v[166:169], v[206:209], v[120:123]
	v_mfma_i32_16x16x64_i8 v[116:119], v[174:177], v[206:209], v[116:119]
	v_mfma_i32_16x16x64_i8 v[112:115], v[166:169], v[214:217], v[112:115]
	v_mfma_i32_16x16x64_i8 v[108:111], v[174:177], v[214:217], v[108:111]
	v_mfma_i32_16x16x64_i8 v[104:107], v[166:169], v[226:229], v[104:107]
	v_mfma_i32_16x16x64_i8 v[100:103], v[174:177], v[226:229], v[100:103]
	v_mfma_i32_16x16x64_i8 v[96:99], v[178:181], v[194:197], v[96:99]
	v_mfma_i32_16x16x64_i8 v[92:95], v[186:189], v[194:197], v[92:95]
	v_mfma_i32_16x16x64_i8 v[88:91], v[178:181], v[202:205], v[88:91]
	v_mfma_i32_16x16x64_i8 v[84:87], v[186:189], v[202:205], v[84:87]
	v_mfma_i32_16x16x64_i8 v[80:83], v[178:181], v[210:213], v[80:83]
	v_mfma_i32_16x16x64_i8 v[76:79], v[186:189], v[210:213], v[76:79]
	v_mfma_i32_16x16x64_i8 v[72:75], v[178:181], v[218:221], v[72:75]
	v_mfma_i32_16x16x64_i8 v[68:71], v[186:189], v[218:221], v[68:71]
	v_mfma_i32_16x16x64_i8 v[96:99], v[182:185], v[198:201], v[96:99]
	v_mfma_i32_16x16x64_i8 v[92:95], v[190:193], v[198:201], v[92:95]
	v_mfma_i32_16x16x64_i8 v[88:91], v[182:185], v[206:209], v[88:91]
	v_mfma_i32_16x16x64_i8 v[84:87], v[190:193], v[206:209], v[84:87]
	v_mfma_i32_16x16x64_i8 v[80:83], v[182:185], v[214:217], v[80:83]
	v_mfma_i32_16x16x64_i8 v[76:79], v[190:193], v[214:217], v[76:79]
	v_mfma_i32_16x16x64_i8 v[72:75], v[182:185], v[226:229], v[72:75]
	v_mfma_i32_16x16x64_i8 v[68:71], v[190:193], v[226:229], v[68:71]
	s_setprio 0
	s_barrier
; #define PG8_STAGE(bufoff, gbase, voff) do { _Pragma("unroll") for (int _i = 0; _i < 2; ++_i) \
;         __builtin_amdgcn_global_load_lds((const unsigned*)((const char*)(gbase) + (voff)[_i]), (LAS unsigned*)(lds + (bufoff) + ldsw + _i * 8192), 16, 0, 0); } while (0)
; #define PG8_LDA(dst, b, h) do { _Pragma("unroll") for (int m = 0; m < 4; ++m) _Pragma("unroll") for (int k = 0; k < 2; ++k) dst[m][k] = *(const LAS bf16x8*)(lds + PG8_SA(b, h) + aoff + m * 2048 + k * 1024); } while (0)
; #define PG8_WAIT_V(n) asm volatile("s_waitcnt vmcnt(" #n ")" ::: "memory")
; #define PG8_WAIT_L(n) asm volatile("s_waitcnt lgkmcnt(" #n ")" ::: "memory")
; #define PG8_BAR __builtin_amdgcn_s_barrier()
; #define PG8_SCHED __builtin_amdgcn_sched_barrier(0)
;     ...
;             PG8_LDA(At, 1, 1); PG8_STAGE(PG8_SB(1, 0), b3, voffB); PG8_STAGE(PG8_SB(1, 1), b3 + hstepB, voffB); PG8_STAGE(PG8_SA(1, 0), a3, voffA);
;             PG8_WAIT_V(8); PG8_WAIT_L(0); PG8_BAR; PG8_MMA(1, 0, At, B0); PG8_MMA(1, 1, At, B1); PG8_BAR; PG8_SCHED;
	s_add_i32 s59, s59, s57
	s_add_i32 m0, s59, 0xffffff80
	ds_read_b128 v[194:197], v160 offset:49152
	ds_read_b128 v[198:201], v160 offset:50176
	ds_read_b128 v[202:205], v160 offset:51200
	ds_read_b128 v[206:209], v160 offset:52224
	ds_read_b128 v[210:213], v160 offset:53248
	ds_read_b128 v[214:217], v160 offset:54272
	ds_read_b128 v[218:221], v160 offset:55296
	ds_read_b128 v[226:229], v160 offset:56320
	global_load_lds_dwordx4 v[234:235], off offset:128
	s_add_i32 m0, s59, 0x1f80
	s_add_i32 s59, s75, s57
	global_load_lds_dwordx4 v[236:237], off offset:128
	s_add_i32 m0, s59, 0xffffff80
	s_nop 0
	global_load_lds_dwordx4 v[238:239], off offset:128
	s_add_i32 m0, s59, 0x1f80
	s_nop 0
	global_load_lds_dwordx4 v[232:233], off offset:128
	s_add_i32 m0, s64, 0xffffff80
	s_nop 0
	global_load_lds_dwordx4 v[240:241], off offset:128
	s_add_i32 m0, s65, 0xffffff80
	s_nop 0
	global_load_lds_dwordx4 v[242:243], off offset:128
	s_waitcnt vmcnt(8)
	s_waitcnt lgkmcnt(0)
	s_barrier
	s_setprio 1
	v_mfma_i32_16x16x64_i8 v[64:67], v[162:165], v[194:197], v[64:67]
	v_mfma_i32_16x16x64_i8 v[60:63], v[170:173], v[194:197], v[60:63]
	v_mfma_i32_16x16x64_i8 v[56:59], v[162:165], v[202:205], v[56:59]
	v_mfma_i32_16x16x64_i8 v[52:55], v[170:173], v[202:205], v[52:55]
	v_mfma_i32_16x16x64_i8 v[48:51], v[162:165], v[210:213], v[48:51]
	v_mfma_i32_16x16x64_i8 v[44:47], v[170:173], v[210:213], v[44:47]
	v_mfma_i32_16x16x64_i8 v[40:43], v[162:165], v[218:221], v[40:43]
	v_mfma_i32_16x16x64_i8 v[36:39], v[170:173], v[218:221], v[36:39]
	v_mfma_i32_16x16x64_i8 v[64:67], v[166:169], v[198:201], v[64:67]
	v_mfma_i32_16x16x64_i8 v[60:63], v[174:177], v[198:201], v[60:63]
	v_mfma_i32_16x16x64_i8 v[56:59], v[166:169], v[206:209], v[56:59]
	v_mfma_i32_16x16x64_i8 v[52:55], v[174:177], v[206:209], v[52:55]
	v_mfma_i32_16x16x64_i8 v[48:51], v[166:169], v[214:217], v[48:51]
	v_mfma_i32_16x16x64_i8 v[44:47], v[174:177], v[214:217], v[44:47]
	v_mfma_i32_16x16x64_i8 v[40:43], v[166:169], v[226:229], v[40:43]
	v_mfma_i32_16x16x64_i8 v[36:39], v[174:177], v[226:229], v[36:39]
	v_mfma_i32_16x16x64_i8 v[32:35], v[178:181], v[194:197], v[32:35]
	v_mfma_i32_16x16x64_i8 v[28:31], v[186:189], v[194:197], v[28:31]
	v_mfma_i32_16x16x64_i8 v[24:27], v[178:181], v[202:205], v[24:27]
	v_mfma_i32_16x16x64_i8 v[20:23], v[186:189], v[202:205], v[20:23]
	v_mfma_i32_16x16x64_i8 v[16:19], v[178:181], v[210:213], v[16:19]
	v_mfma_i32_16x16x64_i8 v[12:15], v[186:189], v[210:213], v[12:15]
	v_mfma_i32_16x16x64_i8 v[8:11], v[178:181], v[218:221], v[8:11]
	v_mfma_i32_16x16x64_i8 v[4:7], v[186:189], v[218:221], v[4:7]
	v_mfma_i32_16x16x64_i8 v[32:35], v[182:185], v[198:201], v[32:35]
	v_mfma_i32_16x16x64_i8 v[28:31], v[190:193], v[198:201], v[28:31]
	v_mfma_i32_16x16x64_i8 v[24:27], v[182:185], v[206:209], v[24:27]
	v_mfma_i32_16x16x64_i8 v[20:23], v[190:193], v[206:209], v[20:23]
	v_mfma_i32_16x16x64_i8 v[16:19], v[182:185], v[214:217], v[16:19]
	v_mfma_i32_16x16x64_i8 v[12:15], v[190:193], v[214:217], v[12:15]
	v_mfma_i32_16x16x64_i8 v[8:11], v[182:185], v[226:229], v[8:11]
	v_mfma_i32_16x16x64_i8 v[4:7], v[190:193], v[226:229], v[4:7]
	s_setprio 0
	s_barrier
	s_add_i32 s58, s58, 2
	s_add_u32 s38, s38, 0x100
	s_addc_u32 s39, s39, 0
	s_cmp_gt_u32 s58, 29
	s_cbranch_scc0 .LBB0_912
	s_and_b64 vcc, exec, s[50:51]
	s_cbranch_vccz .LBB0_915
	s_barrier

; #define PG8_STAGE(bufoff, gbase, voff) do { _Pragma("unroll") for (int _i = 0; _i < 2; ++_i) \
;         __builtin_amdgcn_global_load_lds((const unsigned*)((const char*)(gbase) + (voff)[_i]), (LAS unsigned*)(lds + (bufoff) + ldsw + _i * 8192), 16, 0, 0); } while (0)
; #define PG8_LDA(dst, b, h) do { _Pragma("unroll") for (int m = 0; m < 4; ++m) _Pragma("unroll") for (int k = 0; k < 2; ++k) dst[m][k] = *(const LAS bf16x8*)(lds + PG8_SA(b, h) + aoff + m * 2048 + k * 1024); } while (0)
; #define PG8_LDB(dst, b, h) do { _Pragma("unroll") for (int n = 0; n < 2; ++n) _Pragma("unroll") for (int k = 0; k < 2; ++k) dst[n][k] = *(const LAS bf16x8*)(lds + PG8_SB(b, h) + boff + n * 2048 + k * 1024); } while (0)
; #define PG8_WAIT_V(n) asm volatile("s_waitcnt vmcnt(" #n ")" ::: "memory")
; #define PG8_WAIT_L(n) asm volatile("s_waitcnt lgkmcnt(" #n ")" ::: "memory")
; #define PG8_BAR __builtin_amdgcn_s_barrier()
; #define PG8_SCHED __builtin_amdgcn_sched_barrier(0)
;     ...
;         for (int t = 0; t < nt; t += 2) {
;             const bool last = (t == nt - 2);
;             const char* a1 = cA + (size_t)(t + 1) * kstep;
;             const char* a2 = last ? nA : cA + (size_t)(t + 2) * kstep; const char* b2 = last ? nB : cB + (size_t)(t + 2) * kstep;
;             const char* a3 = a2 + kstep; const char* b3 = b2 + kstep;
;             if constexpr (SP2) {
;             PG8_LDB(B0, 0, 0); PG8_LDB(B1, 0, 1); PG8_SCHED; PG8_LDA(At, 0, 0); PG8_STAGE(PG8_SA(1, 1), a1 + hstepA, voffA);
;             PG8_WAIT_V(8); PG8_WAIT_L(0); PG8_BAR; PG8_MMA(0, 0, At, B0); PG8_MMA(0, 1, At, B1); PG8_BAR; PG8_SCHED;
;             PG8_LDA(At, 0, 1); PG8_STAGE(PG8_SB(0, 0), b2, voffB); PG8_STAGE(PG8_SB(0, 1), b2 + hstepB, voffB); PG8_STAGE(PG8_SA(0, 0), a2, voffA);
;             PG8_WAIT_V(8); PG8_WAIT_L(0); PG8_BAR; PG8_MMA(1, 0, At, B0); PG8_MMA(1, 1, At, B1); PG8_BAR; PG8_SCHED;
.LBB0_1046:
	v_lshl_add_u64 v[168:169], v[152:153], 0, s[24:25]
	s_cmpk_eq_i32 s24, 0xf00
	v_lshl_add_u64 v[168:169], v[168:169], 0, s[20:21]
	v_lshl_add_u64 v[184:185], v[158:159], 0, s[24:25]
	s_cselect_b64 vcc, -1, 0
	v_cndmask_b32_e32 v233, v169, v149, vcc
	v_cndmask_b32_e32 v232, v168, v148, vcc
	ds_read_b128 v[168:171], v164
	ds_read_b128 v[172:175], v164 offset:1024
	ds_read_b128 v[176:179], v164 offset:2048
	ds_read_b128 v[180:183], v164 offset:3072
	v_cndmask_b32_e32 v235, v185, v151, vcc
	v_cndmask_b32_e32 v234, v184, v150, vcc
	ds_read_b128 v[184:187], v165
	ds_read_b128 v[188:191], v165 offset:1024
	ds_read_b128 v[192:195], v165 offset:2048
	ds_read_b128 v[196:199], v165 offset:3072
	s_mov_b32 m0, s44
	v_lshl_add_u64 v[236:237], v[156:157], 0, s[24:25]
	ds_read_b128 v[200:203], v166
	ds_read_b128 v[204:207], v166 offset:1024
	ds_read_b128 v[208:211], v166 offset:2048
	ds_read_b128 v[212:215], v166 offset:3072
	ds_read_b128 v[216:219], v166 offset:4096
	ds_read_b128 v[220:223], v166 offset:5120
	ds_read_b128 v[224:227], v166 offset:6144
	ds_read_b128 v[228:231], v166 offset:7168
	global_load_lds_dwordx4 v[236:237], off
	v_lshl_add_u64 v[236:237], v[154:155], 0, s[24:25]
	s_mov_b32 m0, s45
	s_nop 0
	global_load_lds_dwordx4 v[236:237], off
	s_waitcnt vmcnt(8)
	s_waitcnt lgkmcnt(0)
	s_barrier
	s_setprio 1
	v_mfma_i32_16x16x64_i8 v[124:127], v[168:171], v[200:203], v[124:127]
	v_mfma_i32_16x16x64_i8 v[120:123], v[176:179], v[200:203], v[120:123]
	v_mfma_i32_16x16x64_i8 v[116:119], v[168:171], v[208:211], v[116:119]
	v_mfma_i32_16x16x64_i8 v[112:115], v[176:179], v[208:211], v[112:115]
	v_mfma_i32_16x16x64_i8 v[108:111], v[168:171], v[216:219], v[108:111]
	v_mfma_i32_16x16x64_i8 v[104:107], v[176:179], v[216:219], v[104:107]
	v_mfma_i32_16x16x64_i8 v[100:103], v[168:171], v[224:227], v[100:103]
	v_mfma_i32_16x16x64_i8 v[96:99], v[176:179], v[224:227], v[96:99]
	v_mfma_i32_16x16x64_i8 v[124:127], v[172:175], v[204:207], v[124:127]
	v_mfma_i32_16x16x64_i8 v[120:123], v[180:183], v[204:207], v[120:123]
	v_mfma_i32_16x16x64_i8 v[116:119], v[172:175], v[212:215], v[116:119]
	v_mfma_i32_16x16x64_i8 v[112:115], v[180:183], v[212:215], v[112:115]
	v_mfma_i32_16x16x64_i8 v[108:111], v[172:175], v[220:223], v[108:111]
	v_mfma_i32_16x16x64_i8 v[104:107], v[180:183], v[220:223], v[104:107]
	v_mfma_i32_16x16x64_i8 v[100:103], v[172:175], v[228:231], v[100:103]
	v_mfma_i32_16x16x64_i8 v[96:99], v[180:183], v[228:231], v[96:99]
	v_mfma_i32_16x16x64_i8 v[92:95], v[184:187], v[200:203], v[92:95]
	v_mfma_i32_16x16x64_i8 v[88:91], v[192:195], v[200:203], v[88:91]
	v_mfma_i32_16x16x64_i8 v[84:87], v[184:187], v[208:211], v[84:87]
	v_mfma_i32_16x16x64_i8 v[80:83], v[192:195], v[208:211], v[80:83]
	v_mfma_i32_16x16x64_i8 v[76:79], v[184:187], v[216:219], v[76:79]
	v_mfma_i32_16x16x64_i8 v[72:75], v[192:195], v[216:219], v[72:75]
	v_mfma_i32_16x16x64_i8 v[68:71], v[184:187], v[224:227], v[68:71]
	v_mfma_i32_16x16x64_i8 v[64:67], v[192:195], v[224:227], v[64:67]
	v_mfma_i32_16x16x64_i8 v[92:95], v[188:191], v[204:207], v[92:95]
	v_mfma_i32_16x16x64_i8 v[88:91], v[196:199], v[204:207], v[88:91]
	v_mfma_i32_16x16x64_i8 v[84:87], v[188:191], v[212:215], v[84:87]
	v_mfma_i32_16x16x64_i8 v[80:83], v[196:199], v[212:215], v[80:83]
	v_mfma_i32_16x16x64_i8 v[76:79], v[188:191], v[220:223], v[76:79]
	v_mfma_i32_16x16x64_i8 v[72:75], v[196:199], v[220:223], v[72:75]
	v_mfma_i32_16x16x64_i8 v[68:71], v[188:191], v[228:231], v[68:71]
	v_mfma_i32_16x16x64_i8 v[64:67], v[196:199], v[228:231], v[64:67]
	s_setprio 0
	s_barrier
	s_mov_b32 m0, s46
	v_lshl_add_u64 v[236:237], v[234:235], 0, v[136:137]
	ds_read_b128 v[200:203], v166 offset:16384
	ds_read_b128 v[204:207], v166 offset:17408
	ds_read_b128 v[208:211], v166 offset:18432
	ds_read_b128 v[212:215], v166 offset:19456
	ds_read_b128 v[216:219], v166 offset:20480
	ds_read_b128 v[220:223], v166 offset:21504
	ds_read_b128 v[224:227], v166 offset:22528
	ds_read_b128 v[228:231], v166 offset:23552
	global_load_lds_dwordx4 v[236:237], off
	v_lshl_add_u64 v[238:239], v[234:235], 0, v[132:133]
	s_add_i32 m0, s46, 0x2000
	v_lshl_add_u64 v[234:235], v[234:235], 0, v[130:131]
	s_add_i32 s39, s43, s2
	global_load_lds_dwordx4 v[238:239], off
	v_lshl_add_u64 v[240:241], v[234:235], 0, v[136:137]
	s_mov_b32 m0, s39
	v_lshl_add_u64 v[234:235], v[234:235], 0, v[132:133]
	global_load_lds_dwordx4 v[240:241], off
	s_add_i32 m0, s39, 0x2000
	v_lshl_add_u64 v[242:243], v[232:233], 0, v[138:139]
	global_load_lds_dwordx4 v[234:235], off
	s_mov_b32 m0, s26
	v_lshl_add_u64 v[244:245], v[232:233], 0, v[134:135]
	global_load_lds_dwordx4 v[242:243], off
	s_mov_b32 m0, s27
	s_nop 0
	global_load_lds_dwordx4 v[244:245], off
	s_waitcnt vmcnt(8)
	s_waitcnt lgkmcnt(0)
	s_barrier
; #define PG8_STAGE(bufoff, gbase, voff) do { _Pragma("unroll") for (int _i = 0; _i < 2; ++_i) \
;         __builtin_amdgcn_global_load_lds((const unsigned*)((const char*)(gbase) + (voff)[_i]), (LAS unsigned*)(lds + (bufoff) + ldsw + _i * 8192), 16, 0, 0); } while (0)
; #define PG8_LDA(dst, b, h) do { _Pragma("unroll") for (int m = 0; m < 4; ++m) _Pragma("unroll") for (int k = 0; k < 2; ++k) dst[m][k] = *(const LAS bf16x8*)(lds + PG8_SA(b, h) + aoff + m * 2048 + k * 1024); } while (0)
; #define PG8_LDB(dst, b, h) do { _Pragma("unroll") for (int n = 0; n < 2; ++n) _Pragma("unroll") for (int k = 0; k < 2; ++k) dst[n][k] = *(const LAS bf16x8*)(lds + PG8_SB(b, h) + boff + n * 2048 + k * 1024); } while (0)
; #define PG8_WAIT_V(n) asm volatile("s_waitcnt vmcnt(" #n ")" ::: "memory")
; #define PG8_WAIT_L(n) asm volatile("s_waitcnt lgkmcnt(" #n ")" ::: "memory")
; #define PG8_BAR __builtin_amdgcn_s_barrier()
; #define PG8_SCHED __builtin_amdgcn_sched_barrier(0)
;     ...
;             PG8_WAIT_V(8); PG8_WAIT_L(0); PG8_BAR; PG8_MMA(1, 0, At, B0); PG8_MMA(1, 1, At, B1); PG8_BAR; PG8_SCHED;
;             PG8_LDB(B0, 1, 0); PG8_LDB(B1, 1, 1); PG8_SCHED; PG8_LDA(At, 1, 0); PG8_STAGE(PG8_SA(0, 1), a2 + hstepA, voffA);
;             PG8_WAIT_V(8); PG8_WAIT_L(0); PG8_BAR; PG8_MMA(0, 0, At, B0); PG8_MMA(0, 1, At, B1); PG8_BAR; PG8_SCHED;
;             PG8_LDA(At, 1, 1); PG8_STAGE(PG8_SB(1, 0), b3, voffB); PG8_STAGE(PG8_SB(1, 1), b3 + hstepB, voffB); PG8_STAGE(PG8_SA(1, 0), a3, voffA);
	s_setprio 1
	v_mfma_i32_16x16x64_i8 v[60:63], v[168:171], v[200:203], v[60:63]
	v_mfma_i32_16x16x64_i8 v[56:59], v[176:179], v[200:203], v[56:59]
	v_mfma_i32_16x16x64_i8 v[52:55], v[168:171], v[208:211], v[52:55]
	v_mfma_i32_16x16x64_i8 v[48:51], v[176:179], v[208:211], v[48:51]
	v_mfma_i32_16x16x64_i8 v[44:47], v[168:171], v[216:219], v[44:47]
	v_mfma_i32_16x16x64_i8 v[40:43], v[176:179], v[216:219], v[40:43]
	v_mfma_i32_16x16x64_i8 v[36:39], v[168:171], v[224:227], v[36:39]
	v_mfma_i32_16x16x64_i8 v[32:35], v[176:179], v[224:227], v[32:35]
	v_mfma_i32_16x16x64_i8 v[60:63], v[172:175], v[204:207], v[60:63]
	v_mfma_i32_16x16x64_i8 v[56:59], v[180:183], v[204:207], v[56:59]
	v_mfma_i32_16x16x64_i8 v[52:55], v[172:175], v[212:215], v[52:55]
	v_mfma_i32_16x16x64_i8 v[48:51], v[180:183], v[212:215], v[48:51]
	v_mfma_i32_16x16x64_i8 v[44:47], v[172:175], v[220:223], v[44:47]
	v_mfma_i32_16x16x64_i8 v[40:43], v[180:183], v[220:223], v[40:43]
	v_mfma_i32_16x16x64_i8 v[36:39], v[172:175], v[228:231], v[36:39]
	v_mfma_i32_16x16x64_i8 v[32:35], v[180:183], v[228:231], v[32:35]
	v_mfma_i32_16x16x64_i8 v[28:31], v[184:187], v[200:203], v[28:31]
	v_mfma_i32_16x16x64_i8 v[24:27], v[192:195], v[200:203], v[24:27]
	v_mfma_i32_16x16x64_i8 v[20:23], v[184:187], v[208:211], v[20:23]
	v_mfma_i32_16x16x64_i8 v[16:19], v[192:195], v[208:211], v[16:19]
	v_mfma_i32_16x16x64_i8 v[12:15], v[184:187], v[216:219], v[12:15]
	v_mfma_i32_16x16x64_i8 v[8:11], v[192:195], v[216:219], v[8:11]
	v_mfma_i32_16x16x64_i8 v[4:7], v[184:187], v[224:227], v[4:7]
	v_mfma_i32_16x16x64_i8 v[0:3], v[192:195], v[224:227], v[0:3]
	v_mfma_i32_16x16x64_i8 v[28:31], v[188:191], v[204:207], v[28:31]
	v_mfma_i32_16x16x64_i8 v[24:27], v[196:199], v[204:207], v[24:27]
	v_mfma_i32_16x16x64_i8 v[20:23], v[188:191], v[212:215], v[20:23]
	v_mfma_i32_16x16x64_i8 v[16:19], v[196:199], v[212:215], v[16:19]
	v_mfma_i32_16x16x64_i8 v[12:15], v[188:191], v[220:223], v[12:15]
	v_mfma_i32_16x16x64_i8 v[8:11], v[196:199], v[220:223], v[8:11]
	v_mfma_i32_16x16x64_i8 v[4:7], v[188:191], v[228:231], v[4:7]
	v_mfma_i32_16x16x64_i8 v[0:3], v[196:199], v[228:231], v[0:3]
	s_setprio 0
	s_barrier
	s_add_i32 s39, 0, 0x18000
	s_add_i32 s51, 0, 0x1c000
	ds_read_b128 v[168:171], v248
	ds_read_b128 v[172:175], v248 offset:1024
	ds_read_b128 v[176:179], v248 offset:2048
	ds_read_b128 v[180:183], v248 offset:3072
	ds_read_b128 v[184:187], v249
	ds_read_b128 v[188:191], v249 offset:1024
	ds_read_b128 v[192:195], v249 offset:2048
	ds_read_b128 v[196:199], v249 offset:3072
	v_lshl_add_u64 v[232:233], v[232:233], 0, v[128:129]
	s_mov_b32 m0, s28
	v_lshl_add_u64 v[246:247], v[232:233], 0, v[138:139]
	ds_read_b128 v[200:203], v166 offset:32768
	ds_read_b128 v[204:207], v166 offset:33792
	ds_read_b128 v[208:211], v166 offset:34816
	ds_read_b128 v[212:215], v166 offset:35840
	ds_read_b128 v[216:219], v166 offset:36864
	ds_read_b128 v[220:223], v166 offset:37888
	ds_read_b128 v[224:227], v166 offset:38912
	ds_read_b128 v[228:231], v166 offset:39936
	global_load_lds_dwordx4 v[246:247], off
	v_lshl_add_u64 v[232:233], v[232:233], 0, v[134:135]
	s_mov_b32 m0, s29
	s_nop 0
	global_load_lds_dwordx4 v[232:233], off
	s_waitcnt vmcnt(8)
	s_waitcnt lgkmcnt(0)
	s_barrier
	s_setprio 1
	v_mfma_i32_16x16x64_i8 v[124:127], v[168:171], v[200:203], v[124:127]
	v_mfma_i32_16x16x64_i8 v[120:123], v[176:179], v[200:203], v[120:123]
	v_mfma_i32_16x16x64_i8 v[116:119], v[168:171], v[208:211], v[116:119]
	v_mfma_i32_16x16x64_i8 v[112:115], v[176:179], v[208:211], v[112:115]
	v_mfma_i32_16x16x64_i8 v[108:111], v[168:171], v[216:219], v[108:111]
	v_mfma_i32_16x16x64_i8 v[104:107], v[176:179], v[216:219], v[104:107]
	v_mfma_i32_16x16x64_i8 v[100:103], v[168:171], v[224:227], v[100:103]
	v_mfma_i32_16x16x64_i8 v[96:99], v[176:179], v[224:227], v[96:99]
	v_mfma_i32_16x16x64_i8 v[124:127], v[172:175], v[204:207], v[124:127]
	v_mfma_i32_16x16x64_i8 v[120:123], v[180:183], v[204:207], v[120:123]
	v_mfma_i32_16x16x64_i8 v[116:119], v[172:175], v[212:215], v[116:119]
	v_mfma_i32_16x16x64_i8 v[112:115], v[180:183], v[212:215], v[112:115]
	v_mfma_i32_16x16x64_i8 v[108:111], v[172:175], v[220:223], v[108:111]
	v_mfma_i32_16x16x64_i8 v[104:107], v[180:183], v[220:223], v[104:107]
	v_mfma_i32_16x16x64_i8 v[100:103], v[172:175], v[228:231], v[100:103]
	v_mfma_i32_16x16x64_i8 v[96:99], v[180:183], v[228:231], v[96:99]
	v_mfma_i32_16x16x64_i8 v[92:95], v[184:187], v[200:203], v[92:95]
	v_mfma_i32_16x16x64_i8 v[88:91], v[192:195], v[200:203], v[88:91]
	v_mfma_i32_16x16x64_i8 v[84:87], v[184:187], v[208:211], v[84:87]
	v_mfma_i32_16x16x64_i8 v[80:83], v[192:195], v[208:211], v[80:83]
	v_mfma_i32_16x16x64_i8 v[76:79], v[184:187], v[216:219], v[76:79]
	v_mfma_i32_16x16x64_i8 v[72:75], v[192:195], v[216:219], v[72:75]
	v_mfma_i32_16x16x64_i8 v[68:71], v[184:187], v[224:227], v[68:71]
	v_mfma_i32_16x16x64_i8 v[64:67], v[192:195], v[224:227], v[64:67]
	v_mfma_i32_16x16x64_i8 v[92:95], v[188:191], v[204:207], v[92:95]
	v_mfma_i32_16x16x64_i8 v[88:91], v[196:199], v[204:207], v[88:91]
	v_mfma_i32_16x16x64_i8 v[84:87], v[188:191], v[212:215], v[84:87]
	v_mfma_i32_16x16x64_i8 v[80:83], v[196:199], v[212:215], v[80:83]
	v_mfma_i32_16x16x64_i8 v[76:79], v[188:191], v[220:223], v[76:79]
	v_mfma_i32_16x16x64_i8 v[72:75], v[196:199], v[220:223], v[72:75]
	v_mfma_i32_16x16x64_i8 v[68:71], v[188:191], v[228:231], v[68:71]
	v_mfma_i32_16x16x64_i8 v[64:67], v[196:199], v[228:231], v[64:67]
	s_setprio 0
	s_barrier
; #define PG8_STAGE(bufoff, gbase, voff) do { _Pragma("unroll") for (int _i = 0; _i < 2; ++_i) \
;         __builtin_amdgcn_global_load_lds((const unsigned*)((const char*)(gbase) + (voff)[_i]), (LAS unsigned*)(lds + (bufoff) + ldsw + _i * 8192), 16, 0, 0); } while (0)
; #define PG8_LDA(dst, b, h) do { _Pragma("unroll") for (int m = 0; m < 4; ++m) _Pragma("unroll") for (int k = 0; k < 2; ++k) dst[m][k] = *(const LAS bf16x8*)(lds + PG8_SA(b, h) + aoff + m * 2048 + k * 1024); } while (0)
; #define PG8_WAIT_V(n) asm volatile("s_waitcnt vmcnt(" #n ")" ::: "memory")
; #define PG8_WAIT_L(n) asm volatile("s_waitcnt lgkmcnt(" #n ")" ::: "memory")
; #define PG8_BAR __builtin_amdgcn_s_barrier()
; #define PG8_SCHED __builtin_amdgcn_sched_barrier(0)
;     ...
;             PG8_LDA(At, 1, 1); PG8_STAGE(PG8_SB(1, 0), b3, voffB); PG8_STAGE(PG8_SB(1, 1), b3 + hstepB, voffB); PG8_STAGE(PG8_SA(1, 0), a3, voffA);
;             PG8_WAIT_V(8); PG8_WAIT_L(0); PG8_BAR; PG8_MMA(1, 0, At, B0); PG8_MMA(1, 1, At, B1); PG8_BAR; PG8_SCHED;
	s_add_i32 s39, s39, s2
	s_add_i32 m0, s39, 0xffffff80
	ds_read_b128 v[200:203], v166 offset:49152
	ds_read_b128 v[204:207], v166 offset:50176
	ds_read_b128 v[208:211], v166 offset:51200
	ds_read_b128 v[212:215], v166 offset:52224
	ds_read_b128 v[216:219], v166 offset:53248
	ds_read_b128 v[220:223], v166 offset:54272
	ds_read_b128 v[224:227], v166 offset:55296
	ds_read_b128 v[228:231], v166 offset:56320
	global_load_lds_dwordx4 v[236:237], off offset:128
	s_add_i32 m0, s39, 0x1f80
	s_add_i32 s39, s51, s2
	global_load_lds_dwordx4 v[238:239], off offset:128
	s_add_i32 m0, s39, 0xffffff80
	s_nop 0
	global_load_lds_dwordx4 v[240:241], off offset:128
	s_add_i32 m0, s39, 0x1f80
	s_nop 0
	global_load_lds_dwordx4 v[234:235], off offset:128
	s_add_i32 m0, s40, 0xffffff80
	s_nop 0
	global_load_lds_dwordx4 v[242:243], off offset:128
	s_add_i32 m0, s41, 0xffffff80
	s_nop 0
	global_load_lds_dwordx4 v[244:245], off offset:128
	s_waitcnt vmcnt(8)
	s_waitcnt lgkmcnt(0)
	s_barrier
	s_setprio 1
	v_mfma_i32_16x16x64_i8 v[60:63], v[168:171], v[200:203], v[60:63]
	v_mfma_i32_16x16x64_i8 v[56:59], v[176:179], v[200:203], v[56:59]
	v_mfma_i32_16x16x64_i8 v[52:55], v[168:171], v[208:211], v[52:55]
	v_mfma_i32_16x16x64_i8 v[48:51], v[176:179], v[208:211], v[48:51]
	v_mfma_i32_16x16x64_i8 v[44:47], v[168:171], v[216:219], v[44:47]
	v_mfma_i32_16x16x64_i8 v[40:43], v[176:179], v[216:219], v[40:43]
	v_mfma_i32_16x16x64_i8 v[36:39], v[168:171], v[224:227], v[36:39]
	v_mfma_i32_16x16x64_i8 v[32:35], v[176:179], v[224:227], v[32:35]
	v_mfma_i32_16x16x64_i8 v[60:63], v[172:175], v[204:207], v[60:63]
	v_mfma_i32_16x16x64_i8 v[56:59], v[180:183], v[204:207], v[56:59]
	v_mfma_i32_16x16x64_i8 v[52:55], v[172:175], v[212:215], v[52:55]
	v_mfma_i32_16x16x64_i8 v[48:51], v[180:183], v[212:215], v[48:51]
	v_mfma_i32_16x16x64_i8 v[44:47], v[172:175], v[220:223], v[44:47]
	v_mfma_i32_16x16x64_i8 v[40:43], v[180:183], v[220:223], v[40:43]
	v_mfma_i32_16x16x64_i8 v[36:39], v[172:175], v[228:231], v[36:39]
	v_mfma_i32_16x16x64_i8 v[32:35], v[180:183], v[228:231], v[32:35]
	v_mfma_i32_16x16x64_i8 v[28:31], v[184:187], v[200:203], v[28:31]
	v_mfma_i32_16x16x64_i8 v[24:27], v[192:195], v[200:203], v[24:27]
	v_mfma_i32_16x16x64_i8 v[20:23], v[184:187], v[208:211], v[20:23]
	v_mfma_i32_16x16x64_i8 v[16:19], v[192:195], v[208:211], v[16:19]
	v_mfma_i32_16x16x64_i8 v[12:15], v[184:187], v[216:219], v[12:15]
	v_mfma_i32_16x16x64_i8 v[8:11], v[192:195], v[216:219], v[8:11]
	v_mfma_i32_16x16x64_i8 v[4:7], v[184:187], v[224:227], v[4:7]
	v_mfma_i32_16x16x64_i8 v[0:3], v[192:195], v[224:227], v[0:3]
	v_mfma_i32_16x16x64_i8 v[28:31], v[188:191], v[204:207], v[28:31]
	v_mfma_i32_16x16x64_i8 v[24:27], v[196:199], v[204:207], v[24:27]
	v_mfma_i32_16x16x64_i8 v[20:23], v[188:191], v[212:215], v[20:23]
	v_mfma_i32_16x16x64_i8 v[16:19], v[196:199], v[212:215], v[16:19]
	v_mfma_i32_16x16x64_i8 v[12:15], v[188:191], v[220:223], v[12:15]
	v_mfma_i32_16x16x64_i8 v[8:11], v[196:199], v[220:223], v[8:11]
	v_mfma_i32_16x16x64_i8 v[4:7], v[188:191], v[228:231], v[4:7]
	v_mfma_i32_16x16x64_i8 v[0:3], v[196:199], v[228:231], v[0:3]
	s_setprio 0
	s_barrier
	s_add_i32 s38, s38, 2
	s_add_u32 s24, s24, 0x100
	s_addc_u32 s25, s25, 0
	s_cmp_gt_u32 s38, 29
	s_cbranch_scc0 .LBB0_1046
	s_and_b64 vcc, exec, s[18:19]
	s_cbranch_vccz .LBB0_1049
	s_barrier

; #define PG8_STAGE(bufoff, gbase, voff) do { _Pragma("unroll") for (int _i = 0; _i < 2; ++_i) \
;         __builtin_amdgcn_global_load_lds((const unsigned*)((const char*)(gbase) + (voff)[_i]), (LAS unsigned*)(lds + (bufoff) + ldsw + _i * 8192), 16, 0, 0); } while (0)
; #define PG8_LDA(dst, b, h) do { _Pragma("unroll") for (int m = 0; m < 4; ++m) _Pragma("unroll") for (int k = 0; k < 2; ++k) dst[m][k] = *(const LAS bf16x8*)(lds + PG8_SA(b, h) + aoff + m * 2048 + k * 1024); } while (0)
; #define PG8_LDB(dst, b, h) do { _Pragma("unroll") for (int n = 0; n < 2; ++n) _Pragma("unroll") for (int k = 0; k < 2; ++k) dst[n][k] = *(const LAS bf16x8*)(lds + PG8_SB(b, h) + boff + n * 2048 + k * 1024); } while (0)
; #define PG8_WAIT_V(n) asm volatile("s_waitcnt vmcnt(" #n ")" ::: "memory")
; #define PG8_WAIT_L(n) asm volatile("s_waitcnt lgkmcnt(" #n ")" ::: "memory")
; #define PG8_BAR __builtin_amdgcn_s_barrier()
; #define PG8_SCHED __builtin_amdgcn_sched_barrier(0)
;     ...
;         for (int t = 0; t < nt; t += 2) {
;             const bool last = (t == nt - 2);
;             const char* a1 = cA + (size_t)(t + 1) * kstep;
;             const char* a2 = last ? nA : cA + (size_t)(t + 2) * kstep; const char* b2 = last ? nB : cB + (size_t)(t + 2) * kstep;
;             const char* a3 = a2 + kstep; const char* b3 = b2 + kstep;
;             if constexpr (SP2) {
;             PG8_LDB(B0, 0, 0); PG8_LDB(B1, 0, 1); PG8_SCHED; PG8_LDA(At, 0, 0); PG8_STAGE(PG8_SA(1, 1), a1 + hstepA, voffA);
;             PG8_WAIT_V(8); PG8_WAIT_L(0); PG8_BAR; PG8_MMA(0, 0, At, B0); PG8_MMA(0, 1, At, B1); PG8_BAR; PG8_SCHED;
;             PG8_LDA(At, 0, 1); PG8_STAGE(PG8_SB(0, 0), b2, voffB); PG8_STAGE(PG8_SB(0, 1), b2 + hstepB, voffB); PG8_STAGE(PG8_SA(0, 0), a2, voffA);
;             PG8_WAIT_V(8); PG8_WAIT_L(0); PG8_BAR; PG8_MMA(1, 0, At, B0); PG8_MMA(1, 1, At, B1); PG8_BAR; PG8_SCHED;
; __global__ void __launch_bounds__(NWAVES * 64, 2) fwd(Args args) {
;     ...
;               pg8::Gemm g{(bf16_t*)(ws + WS_N2ALL), (bf16_t*)(ws + WS_WUPB), MTOT, DFF - NUP8, D, D, D, 0, 0}; pg8::StaticOrder S; S.init(MTOT, DFF - NUP8, G, bx);
;               pg8::EpiBf16<1> E{(bf16_t*)(ws + WS_HALL) + NUP8, DFF, 1.0f};
;               pg8::gemm_phase<pg8::EpiBf16<1>, pg8::StaticOrder, true, true>(lds + RING_OFF, g, S, E, tid); }
.LBB0_1066:
	v_lshl_add_u64 v[168:169], v[152:153], 0, s[18:19]
	s_cmpk_eq_i32 s18, 0x1f00
	v_lshl_add_u64 v[168:169], v[168:169], 0, s[16:17]
	v_lshl_add_u64 v[184:185], v[158:159], 0, s[18:19]
	s_cselect_b64 vcc, -1, 0
	v_cndmask_b32_e32 v233, v169, v149, vcc
	v_cndmask_b32_e32 v232, v168, v148, vcc
	ds_read_b128 v[168:171], v164
	ds_read_b128 v[172:175], v164 offset:1024
	ds_read_b128 v[176:179], v164 offset:2048
	ds_read_b128 v[180:183], v164 offset:3072
	v_cndmask_b32_e32 v235, v185, v151, vcc
	v_cndmask_b32_e32 v234, v184, v150, vcc
	ds_read_b128 v[184:187], v165
	ds_read_b128 v[188:191], v165 offset:1024
	ds_read_b128 v[192:195], v165 offset:2048
	ds_read_b128 v[196:199], v165 offset:3072
	s_mov_b32 m0, s35
	v_lshl_add_u64 v[236:237], v[156:157], 0, s[18:19]
	ds_read_b128 v[200:203], v166
	ds_read_b128 v[204:207], v166 offset:1024
	ds_read_b128 v[208:211], v166 offset:2048
	ds_read_b128 v[212:215], v166 offset:3072
	ds_read_b128 v[216:219], v166 offset:4096
	ds_read_b128 v[220:223], v166 offset:5120
	ds_read_b128 v[224:227], v166 offset:6144
	ds_read_b128 v[228:231], v166 offset:7168
	global_load_lds_dwordx4 v[236:237], off
	v_lshl_add_u64 v[236:237], v[154:155], 0, s[18:19]
	s_mov_b32 m0, s40
	s_nop 0
	global_load_lds_dwordx4 v[236:237], off
	s_waitcnt vmcnt(8)
	s_waitcnt lgkmcnt(0)
	s_barrier
	s_setprio 1
	v_mfma_f32_16x16x32_bf16 v[124:127], v[168:171], v[200:203], v[124:127]
	v_mfma_f32_16x16x32_bf16 v[120:123], v[176:179], v[200:203], v[120:123]
	v_mfma_f32_16x16x32_bf16 v[108:111], v[168:171], v[208:211], v[108:111]
	v_mfma_f32_16x16x32_bf16 v[104:107], v[176:179], v[208:211], v[104:107]
	v_mfma_f32_16x16x32_bf16 v[92:95], v[168:171], v[216:219], v[92:95]
	v_mfma_f32_16x16x32_bf16 v[88:91], v[176:179], v[216:219], v[88:91]
	v_mfma_f32_16x16x32_bf16 v[76:79], v[168:171], v[224:227], v[76:79]
	v_mfma_f32_16x16x32_bf16 v[72:75], v[176:179], v[224:227], v[72:75]
	v_mfma_f32_16x16x32_bf16 v[124:127], v[172:175], v[204:207], v[124:127]
	v_mfma_f32_16x16x32_bf16 v[120:123], v[180:183], v[204:207], v[120:123]
	v_mfma_f32_16x16x32_bf16 v[108:111], v[172:175], v[212:215], v[108:111]
	v_mfma_f32_16x16x32_bf16 v[104:107], v[180:183], v[212:215], v[104:107]
	v_mfma_f32_16x16x32_bf16 v[92:95], v[172:175], v[220:223], v[92:95]
	v_mfma_f32_16x16x32_bf16 v[88:91], v[180:183], v[220:223], v[88:91]
	v_mfma_f32_16x16x32_bf16 v[76:79], v[172:175], v[228:231], v[76:79]
	v_mfma_f32_16x16x32_bf16 v[72:75], v[180:183], v[228:231], v[72:75]
	v_mfma_f32_16x16x32_bf16 v[116:119], v[184:187], v[200:203], v[116:119]
	v_mfma_f32_16x16x32_bf16 v[112:115], v[192:195], v[200:203], v[112:115]
	v_mfma_f32_16x16x32_bf16 v[100:103], v[184:187], v[208:211], v[100:103]
	v_mfma_f32_16x16x32_bf16 v[96:99], v[192:195], v[208:211], v[96:99]
	v_mfma_f32_16x16x32_bf16 v[84:87], v[184:187], v[216:219], v[84:87]
	v_mfma_f32_16x16x32_bf16 v[80:83], v[192:195], v[216:219], v[80:83]
	v_mfma_f32_16x16x32_bf16 v[68:71], v[184:187], v[224:227], v[68:71]
	v_mfma_f32_16x16x32_bf16 v[64:67], v[192:195], v[224:227], v[64:67]
	v_mfma_f32_16x16x32_bf16 v[116:119], v[188:191], v[204:207], v[116:119]
	v_mfma_f32_16x16x32_bf16 v[112:115], v[196:199], v[204:207], v[112:115]
	v_mfma_f32_16x16x32_bf16 v[100:103], v[188:191], v[212:215], v[100:103]
	v_mfma_f32_16x16x32_bf16 v[96:99], v[196:199], v[212:215], v[96:99]
	v_mfma_f32_16x16x32_bf16 v[84:87], v[188:191], v[220:223], v[84:87]
	v_mfma_f32_16x16x32_bf16 v[80:83], v[196:199], v[220:223], v[80:83]
	v_mfma_f32_16x16x32_bf16 v[68:71], v[188:191], v[228:231], v[68:71]
	v_mfma_f32_16x16x32_bf16 v[64:67], v[196:199], v[228:231], v[64:67]
	s_setprio 0
	s_barrier
	s_mov_b32 m0, s41
	v_lshl_add_u64 v[236:237], v[234:235], 0, v[136:137]
	ds_read_b128 v[200:203], v166 offset:16384
	ds_read_b128 v[204:207], v166 offset:17408
	ds_read_b128 v[208:211], v166 offset:18432
	ds_read_b128 v[212:215], v166 offset:19456
	ds_read_b128 v[216:219], v166 offset:20480
	ds_read_b128 v[220:223], v166 offset:21504
	ds_read_b128 v[224:227], v166 offset:22528
	ds_read_b128 v[228:231], v166 offset:23552
	global_load_lds_dwordx4 v[236:237], off
	v_lshl_add_u64 v[238:239], v[234:235], 0, v[132:133]
	s_add_i32 m0, s41, 0x2000
	v_lshl_add_u64 v[234:235], v[234:235], 0, v[130:131]
	s_add_i32 s39, s34, s2
	global_load_lds_dwordx4 v[238:239], off
	v_lshl_add_u64 v[240:241], v[234:235], 0, v[136:137]
	s_mov_b32 m0, s39
	v_lshl_add_u64 v[234:235], v[234:235], 0, v[132:133]
	global_load_lds_dwordx4 v[240:241], off
	s_add_i32 m0, s39, 0x2000
	v_lshl_add_u64 v[242:243], v[232:233], 0, v[138:139]
	global_load_lds_dwordx4 v[234:235], off
	s_mov_b32 m0, s21
	v_lshl_add_u64 v[244:245], v[232:233], 0, v[134:135]
	global_load_lds_dwordx4 v[242:243], off
	s_mov_b32 m0, s22
	s_nop 0
	global_load_lds_dwordx4 v[244:245], off
	s_waitcnt vmcnt(8)
	s_waitcnt lgkmcnt(0)
	s_barrier
; #define PG8_STAGE(bufoff, gbase, voff) do { _Pragma("unroll") for (int _i = 0; _i < 2; ++_i) \
;         __builtin_amdgcn_global_load_lds((const unsigned*)((const char*)(gbase) + (voff)[_i]), (LAS unsigned*)(lds + (bufoff) + ldsw + _i * 8192), 16, 0, 0); } while (0)
; #define PG8_LDA(dst, b, h) do { _Pragma("unroll") for (int m = 0; m < 4; ++m) _Pragma("unroll") for (int k = 0; k < 2; ++k) dst[m][k] = *(const LAS bf16x8*)(lds + PG8_SA(b, h) + aoff + m * 2048 + k * 1024); } while (0)
; #define PG8_LDB(dst, b, h) do { _Pragma("unroll") for (int n = 0; n < 2; ++n) _Pragma("unroll") for (int k = 0; k < 2; ++k) dst[n][k] = *(const LAS bf16x8*)(lds + PG8_SB(b, h) + boff + n * 2048 + k * 1024); } while (0)
; #define PG8_WAIT_V(n) asm volatile("s_waitcnt vmcnt(" #n ")" ::: "memory")
; #define PG8_WAIT_L(n) asm volatile("s_waitcnt lgkmcnt(" #n ")" ::: "memory")
; #define PG8_BAR __builtin_amdgcn_s_barrier()
; #define PG8_SCHED __builtin_amdgcn_sched_barrier(0)
;     ...
;             PG8_WAIT_V(8); PG8_WAIT_L(0); PG8_BAR; PG8_MMA(1, 0, At, B0); PG8_MMA(1, 1, At, B1); PG8_BAR; PG8_SCHED;
;             PG8_LDB(B0, 1, 0); PG8_LDB(B1, 1, 1); PG8_SCHED; PG8_LDA(At, 1, 0); PG8_STAGE(PG8_SA(0, 1), a2 + hstepA, voffA);
;             PG8_WAIT_V(8); PG8_WAIT_L(0); PG8_BAR; PG8_MMA(0, 0, At, B0); PG8_MMA(0, 1, At, B1); PG8_BAR; PG8_SCHED;
;             PG8_LDA(At, 1, 1); PG8_STAGE(PG8_SB(1, 0), b3, voffB); PG8_STAGE(PG8_SB(1, 1), b3 + hstepB, voffB); PG8_STAGE(PG8_SA(1, 0), a3, voffA);
	s_setprio 1
	v_mfma_f32_16x16x32_bf16 v[60:63], v[168:171], v[200:203], v[60:63]
	v_mfma_f32_16x16x32_bf16 v[56:59], v[176:179], v[200:203], v[56:59]
	v_mfma_f32_16x16x32_bf16 v[44:47], v[168:171], v[208:211], v[44:47]
	v_mfma_f32_16x16x32_bf16 v[40:43], v[176:179], v[208:211], v[40:43]
	v_mfma_f32_16x16x32_bf16 v[28:31], v[168:171], v[216:219], v[28:31]
	v_mfma_f32_16x16x32_bf16 v[24:27], v[176:179], v[216:219], v[24:27]
	v_mfma_f32_16x16x32_bf16 v[12:15], v[168:171], v[224:227], v[12:15]
	v_mfma_f32_16x16x32_bf16 v[8:11], v[176:179], v[224:227], v[8:11]
	v_mfma_f32_16x16x32_bf16 v[60:63], v[172:175], v[204:207], v[60:63]
	v_mfma_f32_16x16x32_bf16 v[56:59], v[180:183], v[204:207], v[56:59]
	v_mfma_f32_16x16x32_bf16 v[44:47], v[172:175], v[212:215], v[44:47]
	v_mfma_f32_16x16x32_bf16 v[40:43], v[180:183], v[212:215], v[40:43]
	v_mfma_f32_16x16x32_bf16 v[28:31], v[172:175], v[220:223], v[28:31]
	v_mfma_f32_16x16x32_bf16 v[24:27], v[180:183], v[220:223], v[24:27]
	v_mfma_f32_16x16x32_bf16 v[12:15], v[172:175], v[228:231], v[12:15]
	v_mfma_f32_16x16x32_bf16 v[8:11], v[180:183], v[228:231], v[8:11]
	v_mfma_f32_16x16x32_bf16 v[52:55], v[184:187], v[200:203], v[52:55]
	v_mfma_f32_16x16x32_bf16 v[48:51], v[192:195], v[200:203], v[48:51]
	v_mfma_f32_16x16x32_bf16 v[36:39], v[184:187], v[208:211], v[36:39]
	v_mfma_f32_16x16x32_bf16 v[32:35], v[192:195], v[208:211], v[32:35]
	v_mfma_f32_16x16x32_bf16 v[20:23], v[184:187], v[216:219], v[20:23]
	v_mfma_f32_16x16x32_bf16 v[16:19], v[192:195], v[216:219], v[16:19]
	v_mfma_f32_16x16x32_bf16 v[4:7], v[184:187], v[224:227], v[4:7]
	v_mfma_f32_16x16x32_bf16 v[0:3], v[192:195], v[224:227], v[0:3]
	v_mfma_f32_16x16x32_bf16 v[52:55], v[188:191], v[204:207], v[52:55]
	v_mfma_f32_16x16x32_bf16 v[48:51], v[196:199], v[204:207], v[48:51]
	v_mfma_f32_16x16x32_bf16 v[36:39], v[188:191], v[212:215], v[36:39]
	v_mfma_f32_16x16x32_bf16 v[32:35], v[196:199], v[212:215], v[32:35]
	v_mfma_f32_16x16x32_bf16 v[20:23], v[188:191], v[220:223], v[20:23]
	v_mfma_f32_16x16x32_bf16 v[16:19], v[196:199], v[220:223], v[16:19]
	v_mfma_f32_16x16x32_bf16 v[4:7], v[188:191], v[228:231], v[4:7]
	v_mfma_f32_16x16x32_bf16 v[0:3], v[196:199], v[228:231], v[0:3]
	s_setprio 0
	s_barrier
	s_add_i32 s39, 0, 0x18000
	s_add_i32 s46, 0, 0x1c000
	ds_read_b128 v[168:171], v248
	ds_read_b128 v[172:175], v248 offset:1024
	ds_read_b128 v[176:179], v248 offset:2048
	ds_read_b128 v[180:183], v248 offset:3072
	ds_read_b128 v[184:187], v249
	ds_read_b128 v[188:191], v249 offset:1024
	ds_read_b128 v[192:195], v249 offset:2048
	ds_read_b128 v[196:199], v249 offset:3072
	v_lshl_add_u64 v[232:233], v[232:233], 0, v[128:129]
	s_mov_b32 m0, s23
	v_lshl_add_u64 v[246:247], v[232:233], 0, v[138:139]
	ds_read_b128 v[200:203], v166 offset:32768
	ds_read_b128 v[204:207], v166 offset:33792
	ds_read_b128 v[208:211], v166 offset:34816
	ds_read_b128 v[212:215], v166 offset:35840
	ds_read_b128 v[216:219], v166 offset:36864
	ds_read_b128 v[220:223], v166 offset:37888
	ds_read_b128 v[224:227], v166 offset:38912
	ds_read_b128 v[228:231], v166 offset:39936
	global_load_lds_dwordx4 v[246:247], off
	v_lshl_add_u64 v[232:233], v[232:233], 0, v[134:135]
	s_mov_b32 m0, s24
	s_nop 0
	global_load_lds_dwordx4 v[232:233], off
	s_waitcnt vmcnt(8)
	s_waitcnt lgkmcnt(0)
	s_barrier
	s_setprio 1
	v_mfma_f32_16x16x32_bf16 v[124:127], v[168:171], v[200:203], v[124:127]
	v_mfma_f32_16x16x32_bf16 v[120:123], v[176:179], v[200:203], v[120:123]
	v_mfma_f32_16x16x32_bf16 v[108:111], v[168:171], v[208:211], v[108:111]
	v_mfma_f32_16x16x32_bf16 v[104:107], v[176:179], v[208:211], v[104:107]
	v_mfma_f32_16x16x32_bf16 v[92:95], v[168:171], v[216:219], v[92:95]
	v_mfma_f32_16x16x32_bf16 v[88:91], v[176:179], v[216:219], v[88:91]
	v_mfma_f32_16x16x32_bf16 v[76:79], v[168:171], v[224:227], v[76:79]
	v_mfma_f32_16x16x32_bf16 v[72:75], v[176:179], v[224:227], v[72:75]
	v_mfma_f32_16x16x32_bf16 v[124:127], v[172:175], v[204:207], v[124:127]
	v_mfma_f32_16x16x32_bf16 v[120:123], v[180:183], v[204:207], v[120:123]
	v_mfma_f32_16x16x32_bf16 v[108:111], v[172:175], v[212:215], v[108:111]
	v_mfma_f32_16x16x32_bf16 v[104:107], v[180:183], v[212:215], v[104:107]
	v_mfma_f32_16x16x32_bf16 v[92:95], v[172:175], v[220:223], v[92:95]
	v_mfma_f32_16x16x32_bf16 v[88:91], v[180:183], v[220:223], v[88:91]
	v_mfma_f32_16x16x32_bf16 v[76:79], v[172:175], v[228:231], v[76:79]
	v_mfma_f32_16x16x32_bf16 v[72:75], v[180:183], v[228:231], v[72:75]
	v_mfma_f32_16x16x32_bf16 v[116:119], v[184:187], v[200:203], v[116:119]
	v_mfma_f32_16x16x32_bf16 v[112:115], v[192:195], v[200:203], v[112:115]
	v_mfma_f32_16x16x32_bf16 v[100:103], v[184:187], v[208:211], v[100:103]
	v_mfma_f32_16x16x32_bf16 v[96:99], v[192:195], v[208:211], v[96:99]
	v_mfma_f32_16x16x32_bf16 v[84:87], v[184:187], v[216:219], v[84:87]
	v_mfma_f32_16x16x32_bf16 v[80:83], v[192:195], v[216:219], v[80:83]
	v_mfma_f32_16x16x32_bf16 v[68:71], v[184:187], v[224:227], v[68:71]
	v_mfma_f32_16x16x32_bf16 v[64:67], v[192:195], v[224:227], v[64:67]
	v_mfma_f32_16x16x32_bf16 v[116:119], v[188:191], v[204:207], v[116:119]
	v_mfma_f32_16x16x32_bf16 v[112:115], v[196:199], v[204:207], v[112:115]
	v_mfma_f32_16x16x32_bf16 v[100:103], v[188:191], v[212:215], v[100:103]
	v_mfma_f32_16x16x32_bf16 v[96:99], v[196:199], v[212:215], v[96:99]
	v_mfma_f32_16x16x32_bf16 v[84:87], v[188:191], v[220:223], v[84:87]
	v_mfma_f32_16x16x32_bf16 v[80:83], v[196:199], v[220:223], v[80:83]
	v_mfma_f32_16x16x32_bf16 v[68:71], v[188:191], v[228:231], v[68:71]
	v_mfma_f32_16x16x32_bf16 v[64:67], v[196:199], v[228:231], v[64:67]
	s_setprio 0
	s_barrier
; #define PG8_STAGE(bufoff, gbase, voff) do { _Pragma("unroll") for (int _i = 0; _i < 2; ++_i) \
;         __builtin_amdgcn_global_load_lds((const unsigned*)((const char*)(gbase) + (voff)[_i]), (LAS unsigned*)(lds + (bufoff) + ldsw + _i * 8192), 16, 0, 0); } while (0)
; #define PG8_LDA(dst, b, h) do { _Pragma("unroll") for (int m = 0; m < 4; ++m) _Pragma("unroll") for (int k = 0; k < 2; ++k) dst[m][k] = *(const LAS bf16x8*)(lds + PG8_SA(b, h) + aoff + m * 2048 + k * 1024); } while (0)
; #define PG8_WAIT_V(n) asm volatile("s_waitcnt vmcnt(" #n ")" ::: "memory")
; #define PG8_WAIT_L(n) asm volatile("s_waitcnt lgkmcnt(" #n ")" ::: "memory")
; #define PG8_BAR __builtin_amdgcn_s_barrier()
; #define PG8_SCHED __builtin_amdgcn_sched_barrier(0)
;     ...
;             PG8_LDA(At, 1, 1); PG8_STAGE(PG8_SB(1, 0), b3, voffB); PG8_STAGE(PG8_SB(1, 1), b3 + hstepB, voffB); PG8_STAGE(PG8_SA(1, 0), a3, voffA);
;             PG8_WAIT_V(8); PG8_WAIT_L(0); PG8_BAR; PG8_MMA(1, 0, At, B0); PG8_MMA(1, 1, At, B1); PG8_BAR; PG8_SCHED;
	s_add_i32 s39, s39, s2
	s_add_i32 m0, s39, 0xffffff80
	ds_read_b128 v[200:203], v166 offset:49152
	ds_read_b128 v[204:207], v166 offset:50176
	ds_read_b128 v[208:211], v166 offset:51200
	ds_read_b128 v[212:215], v166 offset:52224
	ds_read_b128 v[216:219], v166 offset:53248
	ds_read_b128 v[220:223], v166 offset:54272
	ds_read_b128 v[224:227], v166 offset:55296
	ds_read_b128 v[228:231], v166 offset:56320
	global_load_lds_dwordx4 v[236:237], off offset:128
	s_add_i32 m0, s39, 0x1f80
	s_add_i32 s39, s46, s2
	global_load_lds_dwordx4 v[238:239], off offset:128
	s_add_i32 m0, s39, 0xffffff80
	s_nop 0
	global_load_lds_dwordx4 v[240:241], off offset:128
	s_add_i32 m0, s39, 0x1f80
	s_nop 0
	global_load_lds_dwordx4 v[234:235], off offset:128
	s_add_i32 m0, s30, 0xffffff80
	s_nop 0
	global_load_lds_dwordx4 v[242:243], off offset:128
	s_add_i32 m0, s31, 0xffffff80
	s_nop 0
	global_load_lds_dwordx4 v[244:245], off offset:128
	s_waitcnt vmcnt(8)
	s_waitcnt lgkmcnt(0)
	s_barrier
	s_setprio 1
	v_mfma_f32_16x16x32_bf16 v[60:63], v[168:171], v[200:203], v[60:63]
	v_mfma_f32_16x16x32_bf16 v[56:59], v[176:179], v[200:203], v[56:59]
	v_mfma_f32_16x16x32_bf16 v[44:47], v[168:171], v[208:211], v[44:47]
	v_mfma_f32_16x16x32_bf16 v[40:43], v[176:179], v[208:211], v[40:43]
	v_mfma_f32_16x16x32_bf16 v[28:31], v[168:171], v[216:219], v[28:31]
	v_mfma_f32_16x16x32_bf16 v[24:27], v[176:179], v[216:219], v[24:27]
	v_mfma_f32_16x16x32_bf16 v[12:15], v[168:171], v[224:227], v[12:15]
	v_mfma_f32_16x16x32_bf16 v[8:11], v[176:179], v[224:227], v[8:11]
	v_mfma_f32_16x16x32_bf16 v[60:63], v[172:175], v[204:207], v[60:63]
	v_mfma_f32_16x16x32_bf16 v[56:59], v[180:183], v[204:207], v[56:59]
	v_mfma_f32_16x16x32_bf16 v[44:47], v[172:175], v[212:215], v[44:47]
	v_mfma_f32_16x16x32_bf16 v[40:43], v[180:183], v[212:215], v[40:43]
	v_mfma_f32_16x16x32_bf16 v[28:31], v[172:175], v[220:223], v[28:31]
	v_mfma_f32_16x16x32_bf16 v[24:27], v[180:183], v[220:223], v[24:27]
	v_mfma_f32_16x16x32_bf16 v[12:15], v[172:175], v[228:231], v[12:15]
	v_mfma_f32_16x16x32_bf16 v[8:11], v[180:183], v[228:231], v[8:11]
	v_mfma_f32_16x16x32_bf16 v[52:55], v[184:187], v[200:203], v[52:55]
	v_mfma_f32_16x16x32_bf16 v[48:51], v[192:195], v[200:203], v[48:51]
	v_mfma_f32_16x16x32_bf16 v[36:39], v[184:187], v[208:211], v[36:39]
	v_mfma_f32_16x16x32_bf16 v[32:35], v[192:195], v[208:211], v[32:35]
	v_mfma_f32_16x16x32_bf16 v[20:23], v[184:187], v[216:219], v[20:23]
	v_mfma_f32_16x16x32_bf16 v[16:19], v[192:195], v[216:219], v[16:19]
	v_mfma_f32_16x16x32_bf16 v[4:7], v[184:187], v[224:227], v[4:7]
	v_mfma_f32_16x16x32_bf16 v[0:3], v[192:195], v[224:227], v[0:3]
	v_mfma_f32_16x16x32_bf16 v[52:55], v[188:191], v[204:207], v[52:55]
	v_mfma_f32_16x16x32_bf16 v[48:51], v[196:199], v[204:207], v[48:51]
	v_mfma_f32_16x16x32_bf16 v[36:39], v[188:191], v[212:215], v[36:39]
	v_mfma_f32_16x16x32_bf16 v[32:35], v[196:199], v[212:215], v[32:35]
	v_mfma_f32_16x16x32_bf16 v[20:23], v[188:191], v[220:223], v[20:23]
	v_mfma_f32_16x16x32_bf16 v[16:19], v[196:199], v[220:223], v[16:19]
	v_mfma_f32_16x16x32_bf16 v[4:7], v[188:191], v[228:231], v[4:7]
	v_mfma_f32_16x16x32_bf16 v[0:3], v[196:199], v[228:231], v[0:3]
	s_setprio 0
	s_barrier
	s_add_i32 s38, s38, 2
	s_add_u32 s18, s18, 0x100
	s_addc_u32 s19, s19, 0
	s_cmp_gt_u32 s38, 61
	s_cbranch_scc0 .LBB0_1066
	s_and_b64 vcc, exec, s[14:15]
	s_cbranch_vccz .LBB0_1069
	s_barrier

; #define PG8_STAGE(bufoff, gbase, voff) do { _Pragma("unroll") for (int _i = 0; _i < 2; ++_i) \
;         __builtin_amdgcn_global_load_lds((const unsigned*)((const char*)(gbase) + (voff)[_i]), (LAS unsigned*)(lds + (bufoff) + ldsw + _i * 8192), 16, 0, 0); } while (0)
; #define PG8_LDA(dst, b, h) do { _Pragma("unroll") for (int m = 0; m < 4; ++m) _Pragma("unroll") for (int k = 0; k < 2; ++k) dst[m][k] = *(const LAS bf16x8*)(lds + PG8_SA(b, h) + aoff + m * 2048 + k * 1024); } while (0)
; #define PG8_LDB(dst, b, h) do { _Pragma("unroll") for (int n = 0; n < 2; ++n) _Pragma("unroll") for (int k = 0; k < 2; ++k) dst[n][k] = *(const LAS bf16x8*)(lds + PG8_SB(b, h) + boff + n * 2048 + k * 1024); } while (0)
; #define PG8_WAIT_V(n) asm volatile("s_waitcnt vmcnt(" #n ")" ::: "memory")
; #define PG8_WAIT_L(n) asm volatile("s_waitcnt lgkmcnt(" #n ")" ::: "memory")
; #define PG8_BAR __builtin_amdgcn_s_barrier()
; #define PG8_SCHED __builtin_amdgcn_sched_barrier(0)
;     ...
;         for (int t = 0; t < nt; t += 2) {
;             const bool last = (t == nt - 2);
;             const char* a1 = cA + (size_t)(t + 1) * kstep;
;             const char* a2 = last ? nA : cA + (size_t)(t + 2) * kstep; const char* b2 = last ? nB : cB + (size_t)(t + 2) * kstep;
;             const char* a3 = a2 + kstep; const char* b3 = b2 + kstep;
;             if constexpr (SP2) {
;             PG8_LDB(B0, 0, 0); PG8_LDB(B1, 0, 1); PG8_SCHED; PG8_LDA(At, 0, 0); PG8_STAGE(PG8_SA(1, 1), a1 + hstepA, voffA);
;             PG8_WAIT_V(8); PG8_WAIT_L(0); PG8_BAR; PG8_MMA(0, 0, At, B0); PG8_MMA(0, 1, At, B1); PG8_BAR; PG8_SCHED;
;             PG8_LDA(At, 0, 1); PG8_STAGE(PG8_SB(0, 0), b2, voffB); PG8_STAGE(PG8_SB(0, 1), b2 + hstepB, voffB); PG8_STAGE(PG8_SA(0, 0), a2, voffA);
;             PG8_WAIT_V(8); PG8_WAIT_L(0); PG8_BAR; PG8_MMA(1, 0, At, B0); PG8_MMA(1, 1, At, B1); PG8_BAR; PG8_SCHED;
; __global__ void __launch_bounds__(NWAVES * 64, 2) fwd(Args args) {
;     ...
;             pg8::Gemm g{(bf16_t*)(ws + WS_HALL), (bf16_t*)(ws + WS_WDN), MTOT, D, DFF, DFF, DFF, 0, 0}; pg8::StaticOrder S; S.init(MTOT, D, G, bx, 1);
;             pg8::EpiResBf<true> E{kp->out, MG, (size_t)MG * D * 2, (bf16_t*)(ws + WS_N2ALL), 0, 0, D, 1.0f};
;             pg8::gemm_phase<pg8::EpiResBf<true>, pg8::StaticOrder, true, true>(lds + RING_OFF, g, S, E, tid);
.LBB0_1148:
	v_lshl_add_u64 v[168:169], v[152:153], 0, s[18:19]
	s_cmpk_eq_i32 s18, 0x7f00
	v_lshl_add_u64 v[168:169], v[168:169], 0, s[16:17]
	v_lshl_add_u64 v[184:185], v[158:159], 0, s[18:19]
	s_cselect_b64 vcc, -1, 0
	v_cndmask_b32_e32 v233, v169, v149, vcc
	v_cndmask_b32_e32 v232, v168, v148, vcc
	ds_read_b128 v[168:171], v164
	ds_read_b128 v[172:175], v164 offset:1024
	ds_read_b128 v[176:179], v164 offset:2048
	ds_read_b128 v[180:183], v164 offset:3072
	v_cndmask_b32_e32 v235, v185, v151, vcc
	v_cndmask_b32_e32 v234, v184, v150, vcc
	ds_read_b128 v[184:187], v165
	ds_read_b128 v[188:191], v165 offset:1024
	ds_read_b128 v[192:195], v165 offset:2048
	ds_read_b128 v[196:199], v165 offset:3072
	v_lshl_add_u64 v[236:237], v[156:157], 0, s[18:19]
	s_add_i32 m0, s3, 0xc000
	ds_read_b128 v[200:203], v166
	ds_read_b128 v[204:207], v166 offset:1024
	ds_read_b128 v[208:211], v166 offset:2048
	ds_read_b128 v[212:215], v166 offset:3072
	ds_read_b128 v[216:219], v166 offset:4096
	ds_read_b128 v[220:223], v166 offset:5120
	ds_read_b128 v[224:227], v166 offset:6144
	ds_read_b128 v[228:231], v166 offset:7168
	global_load_lds_dwordx4 v[236:237], off
	v_lshl_add_u64 v[236:237], v[154:155], 0, s[18:19]
	s_add_i32 m0, s3, 0xe000
	s_nop 0
	global_load_lds_dwordx4 v[236:237], off
	s_waitcnt vmcnt(8)
	s_waitcnt lgkmcnt(0)
	s_barrier
	s_setprio 1
	v_mfma_f32_16x16x32_bf16 v[124:127], v[168:171], v[200:203], v[124:127]
	v_mfma_f32_16x16x32_bf16 v[120:123], v[176:179], v[200:203], v[120:123]
	v_mfma_f32_16x16x32_bf16 v[108:111], v[168:171], v[208:211], v[108:111]
	v_mfma_f32_16x16x32_bf16 v[104:107], v[176:179], v[208:211], v[104:107]
	v_mfma_f32_16x16x32_bf16 v[92:95], v[168:171], v[216:219], v[92:95]
	v_mfma_f32_16x16x32_bf16 v[88:91], v[176:179], v[216:219], v[88:91]
	v_mfma_f32_16x16x32_bf16 v[76:79], v[168:171], v[224:227], v[76:79]
	v_mfma_f32_16x16x32_bf16 v[72:75], v[176:179], v[224:227], v[72:75]
	v_mfma_f32_16x16x32_bf16 v[124:127], v[172:175], v[204:207], v[124:127]
	v_mfma_f32_16x16x32_bf16 v[120:123], v[180:183], v[204:207], v[120:123]
	v_mfma_f32_16x16x32_bf16 v[108:111], v[172:175], v[212:215], v[108:111]
	v_mfma_f32_16x16x32_bf16 v[104:107], v[180:183], v[212:215], v[104:107]
	v_mfma_f32_16x16x32_bf16 v[92:95], v[172:175], v[220:223], v[92:95]
	v_mfma_f32_16x16x32_bf16 v[88:91], v[180:183], v[220:223], v[88:91]
	v_mfma_f32_16x16x32_bf16 v[76:79], v[172:175], v[228:231], v[76:79]
	v_mfma_f32_16x16x32_bf16 v[72:75], v[180:183], v[228:231], v[72:75]
	v_mfma_f32_16x16x32_bf16 v[116:119], v[184:187], v[200:203], v[116:119]
	v_mfma_f32_16x16x32_bf16 v[112:115], v[192:195], v[200:203], v[112:115]
	v_mfma_f32_16x16x32_bf16 v[100:103], v[184:187], v[208:211], v[100:103]
	v_mfma_f32_16x16x32_bf16 v[96:99], v[192:195], v[208:211], v[96:99]
	v_mfma_f32_16x16x32_bf16 v[84:87], v[184:187], v[216:219], v[84:87]
	v_mfma_f32_16x16x32_bf16 v[80:83], v[192:195], v[216:219], v[80:83]
	v_mfma_f32_16x16x32_bf16 v[68:71], v[184:187], v[224:227], v[68:71]
	v_mfma_f32_16x16x32_bf16 v[64:67], v[192:195], v[224:227], v[64:67]
	v_mfma_f32_16x16x32_bf16 v[116:119], v[188:191], v[204:207], v[116:119]
	v_mfma_f32_16x16x32_bf16 v[112:115], v[196:199], v[204:207], v[112:115]
	v_mfma_f32_16x16x32_bf16 v[100:103], v[188:191], v[212:215], v[100:103]
	v_mfma_f32_16x16x32_bf16 v[96:99], v[196:199], v[212:215], v[96:99]
	v_mfma_f32_16x16x32_bf16 v[84:87], v[188:191], v[220:223], v[84:87]
	v_mfma_f32_16x16x32_bf16 v[80:83], v[196:199], v[220:223], v[80:83]
	v_mfma_f32_16x16x32_bf16 v[68:71], v[188:191], v[228:231], v[68:71]
	v_mfma_f32_16x16x32_bf16 v[64:67], v[196:199], v[228:231], v[64:67]
	s_setprio 0
	s_barrier
	s_add_i32 s21, s43, s2
	v_lshl_add_u64 v[236:237], v[234:235], 0, v[130:131]
	s_mov_b32 m0, s21
	ds_read_b128 v[200:203], v166 offset:16384
	ds_read_b128 v[204:207], v166 offset:17408
	ds_read_b128 v[208:211], v166 offset:18432
	ds_read_b128 v[212:215], v166 offset:19456
	ds_read_b128 v[216:219], v166 offset:20480
	ds_read_b128 v[220:223], v166 offset:21504
	ds_read_b128 v[224:227], v166 offset:22528
	ds_read_b128 v[228:231], v166 offset:23552
	global_load_lds_dwordx4 v[236:237], off
	v_lshl_add_u64 v[238:239], v[234:235], 0, v[134:135]
	s_add_i32 m0, s21, 0x2000
	v_lshl_add_u64 v[234:235], v[234:235], 0, v[138:139]
	s_add_i32 s21, s46, s2
	global_load_lds_dwordx4 v[238:239], off
	v_lshl_add_u64 v[240:241], v[234:235], 0, v[130:131]
	s_mov_b32 m0, s21
	v_lshl_add_u64 v[234:235], v[234:235], 0, v[134:135]
	global_load_lds_dwordx4 v[240:241], off
	s_add_i32 m0, s21, 0x2000
	v_lshl_add_u64 v[242:243], v[232:233], 0, v[128:129]
	global_load_lds_dwordx4 v[234:235], off
	s_mov_b32 m0, s3
	v_lshl_add_u64 v[244:245], v[232:233], 0, v[132:133]
	global_load_lds_dwordx4 v[242:243], off
	s_mov_b32 m0, s22
	s_nop 0
	global_load_lds_dwordx4 v[244:245], off
	s_waitcnt vmcnt(8)
	s_waitcnt lgkmcnt(0)
	s_barrier
; #define PG8_STAGE(bufoff, gbase, voff) do { _Pragma("unroll") for (int _i = 0; _i < 2; ++_i) \
;         __builtin_amdgcn_global_load_lds((const unsigned*)((const char*)(gbase) + (voff)[_i]), (LAS unsigned*)(lds + (bufoff) + ldsw + _i * 8192), 16, 0, 0); } while (0)
; #define PG8_LDA(dst, b, h) do { _Pragma("unroll") for (int m = 0; m < 4; ++m) _Pragma("unroll") for (int k = 0; k < 2; ++k) dst[m][k] = *(const LAS bf16x8*)(lds + PG8_SA(b, h) + aoff + m * 2048 + k * 1024); } while (0)
; #define PG8_LDB(dst, b, h) do { _Pragma("unroll") for (int n = 0; n < 2; ++n) _Pragma("unroll") for (int k = 0; k < 2; ++k) dst[n][k] = *(const LAS bf16x8*)(lds + PG8_SB(b, h) + boff + n * 2048 + k * 1024); } while (0)
; #define PG8_WAIT_V(n) asm volatile("s_waitcnt vmcnt(" #n ")" ::: "memory")
; #define PG8_WAIT_L(n) asm volatile("s_waitcnt lgkmcnt(" #n ")" ::: "memory")
; #define PG8_BAR __builtin_amdgcn_s_barrier()
; #define PG8_SCHED __builtin_amdgcn_sched_barrier(0)
;     ...
;             PG8_WAIT_V(8); PG8_WAIT_L(0); PG8_BAR; PG8_MMA(1, 0, At, B0); PG8_MMA(1, 1, At, B1); PG8_BAR; PG8_SCHED;
;             PG8_LDB(B0, 1, 0); PG8_LDB(B1, 1, 1); PG8_SCHED; PG8_LDA(At, 1, 0); PG8_STAGE(PG8_SA(0, 1), a2 + hstepA, voffA);
;             PG8_WAIT_V(8); PG8_WAIT_L(0); PG8_BAR; PG8_MMA(0, 0, At, B0); PG8_MMA(0, 1, At, B1); PG8_BAR; PG8_SCHED;
;             PG8_LDA(At, 1, 1); PG8_STAGE(PG8_SB(1, 0), b3, voffB); PG8_STAGE(PG8_SB(1, 1), b3 + hstepB, voffB); PG8_STAGE(PG8_SA(1, 0), a3, voffA);
	s_setprio 1
	v_mfma_f32_16x16x32_bf16 v[60:63], v[168:171], v[200:203], v[60:63]
	v_mfma_f32_16x16x32_bf16 v[56:59], v[176:179], v[200:203], v[56:59]
	v_mfma_f32_16x16x32_bf16 v[44:47], v[168:171], v[208:211], v[44:47]
	v_mfma_f32_16x16x32_bf16 v[40:43], v[176:179], v[208:211], v[40:43]
	v_mfma_f32_16x16x32_bf16 v[28:31], v[168:171], v[216:219], v[28:31]
	v_mfma_f32_16x16x32_bf16 v[24:27], v[176:179], v[216:219], v[24:27]
	v_mfma_f32_16x16x32_bf16 v[12:15], v[168:171], v[224:227], v[12:15]
	v_mfma_f32_16x16x32_bf16 v[8:11], v[176:179], v[224:227], v[8:11]
	v_mfma_f32_16x16x32_bf16 v[60:63], v[172:175], v[204:207], v[60:63]
	v_mfma_f32_16x16x32_bf16 v[56:59], v[180:183], v[204:207], v[56:59]
	v_mfma_f32_16x16x32_bf16 v[44:47], v[172:175], v[212:215], v[44:47]
	v_mfma_f32_16x16x32_bf16 v[40:43], v[180:183], v[212:215], v[40:43]
	v_mfma_f32_16x16x32_bf16 v[28:31], v[172:175], v[220:223], v[28:31]
	v_mfma_f32_16x16x32_bf16 v[24:27], v[180:183], v[220:223], v[24:27]
	v_mfma_f32_16x16x32_bf16 v[12:15], v[172:175], v[228:231], v[12:15]
	v_mfma_f32_16x16x32_bf16 v[8:11], v[180:183], v[228:231], v[8:11]
	v_mfma_f32_16x16x32_bf16 v[52:55], v[184:187], v[200:203], v[52:55]
	v_mfma_f32_16x16x32_bf16 v[48:51], v[192:195], v[200:203], v[48:51]
	v_mfma_f32_16x16x32_bf16 v[36:39], v[184:187], v[208:211], v[36:39]
	v_mfma_f32_16x16x32_bf16 v[32:35], v[192:195], v[208:211], v[32:35]
	v_mfma_f32_16x16x32_bf16 v[20:23], v[184:187], v[216:219], v[20:23]
	v_mfma_f32_16x16x32_bf16 v[16:19], v[192:195], v[216:219], v[16:19]
	v_mfma_f32_16x16x32_bf16 v[4:7], v[184:187], v[224:227], v[4:7]
	v_mfma_f32_16x16x32_bf16 v[0:3], v[192:195], v[224:227], v[0:3]
	v_mfma_f32_16x16x32_bf16 v[52:55], v[188:191], v[204:207], v[52:55]
	v_mfma_f32_16x16x32_bf16 v[48:51], v[196:199], v[204:207], v[48:51]
	v_mfma_f32_16x16x32_bf16 v[36:39], v[188:191], v[212:215], v[36:39]
	v_mfma_f32_16x16x32_bf16 v[32:35], v[196:199], v[212:215], v[32:35]
	v_mfma_f32_16x16x32_bf16 v[20:23], v[188:191], v[220:223], v[20:23]
	v_mfma_f32_16x16x32_bf16 v[16:19], v[196:199], v[220:223], v[16:19]
	v_mfma_f32_16x16x32_bf16 v[4:7], v[188:191], v[228:231], v[4:7]
	v_mfma_f32_16x16x32_bf16 v[0:3], v[196:199], v[228:231], v[0:3]
	s_setprio 0
	s_barrier
	s_add_i32 s21, 0, 0x18000
	s_add_i32 s40, 0, 0x1c000
	ds_read_b128 v[168:171], v248
	ds_read_b128 v[172:175], v248 offset:1024
	ds_read_b128 v[176:179], v248 offset:2048
	ds_read_b128 v[180:183], v248 offset:3072
	ds_read_b128 v[184:187], v249
	ds_read_b128 v[188:191], v249 offset:1024
	ds_read_b128 v[192:195], v249 offset:2048
	ds_read_b128 v[196:199], v249 offset:3072
	v_lshl_add_u64 v[232:233], v[232:233], 0, v[136:137]
	s_mov_b32 m0, s23
	v_lshl_add_u64 v[246:247], v[232:233], 0, v[128:129]
	ds_read_b128 v[200:203], v166 offset:32768
	ds_read_b128 v[204:207], v166 offset:33792
	ds_read_b128 v[208:211], v166 offset:34816
	ds_read_b128 v[212:215], v166 offset:35840
	ds_read_b128 v[216:219], v166 offset:36864
	ds_read_b128 v[220:223], v166 offset:37888
	ds_read_b128 v[224:227], v166 offset:38912
	ds_read_b128 v[228:231], v166 offset:39936
	global_load_lds_dwordx4 v[246:247], off
	v_lshl_add_u64 v[232:233], v[232:233], 0, v[132:133]
	s_mov_b32 m0, s24
	s_nop 0
	global_load_lds_dwordx4 v[232:233], off
	s_waitcnt vmcnt(8)
	s_waitcnt lgkmcnt(0)
	s_barrier
	s_setprio 1
	v_mfma_f32_16x16x32_bf16 v[124:127], v[168:171], v[200:203], v[124:127]
	v_mfma_f32_16x16x32_bf16 v[120:123], v[176:179], v[200:203], v[120:123]
	v_mfma_f32_16x16x32_bf16 v[108:111], v[168:171], v[208:211], v[108:111]
	v_mfma_f32_16x16x32_bf16 v[104:107], v[176:179], v[208:211], v[104:107]
	v_mfma_f32_16x16x32_bf16 v[92:95], v[168:171], v[216:219], v[92:95]
	v_mfma_f32_16x16x32_bf16 v[88:91], v[176:179], v[216:219], v[88:91]
	v_mfma_f32_16x16x32_bf16 v[76:79], v[168:171], v[224:227], v[76:79]
	v_mfma_f32_16x16x32_bf16 v[72:75], v[176:179], v[224:227], v[72:75]
	v_mfma_f32_16x16x32_bf16 v[124:127], v[172:175], v[204:207], v[124:127]
	v_mfma_f32_16x16x32_bf16 v[120:123], v[180:183], v[204:207], v[120:123]
	v_mfma_f32_16x16x32_bf16 v[108:111], v[172:175], v[212:215], v[108:111]
	v_mfma_f32_16x16x32_bf16 v[104:107], v[180:183], v[212:215], v[104:107]
	v_mfma_f32_16x16x32_bf16 v[92:95], v[172:175], v[220:223], v[92:95]
	v_mfma_f32_16x16x32_bf16 v[88:91], v[180:183], v[220:223], v[88:91]
	v_mfma_f32_16x16x32_bf16 v[76:79], v[172:175], v[228:231], v[76:79]
	v_mfma_f32_16x16x32_bf16 v[72:75], v[180:183], v[228:231], v[72:75]
	v_mfma_f32_16x16x32_bf16 v[116:119], v[184:187], v[200:203], v[116:119]
	v_mfma_f32_16x16x32_bf16 v[112:115], v[192:195], v[200:203], v[112:115]
	v_mfma_f32_16x16x32_bf16 v[100:103], v[184:187], v[208:211], v[100:103]
	v_mfma_f32_16x16x32_bf16 v[96:99], v[192:195], v[208:211], v[96:99]
	v_mfma_f32_16x16x32_bf16 v[84:87], v[184:187], v[216:219], v[84:87]
	v_mfma_f32_16x16x32_bf16 v[80:83], v[192:195], v[216:219], v[80:83]
	v_mfma_f32_16x16x32_bf16 v[68:71], v[184:187], v[224:227], v[68:71]
	v_mfma_f32_16x16x32_bf16 v[64:67], v[192:195], v[224:227], v[64:67]
	v_mfma_f32_16x16x32_bf16 v[116:119], v[188:191], v[204:207], v[116:119]
	v_mfma_f32_16x16x32_bf16 v[112:115], v[196:199], v[204:207], v[112:115]
	v_mfma_f32_16x16x32_bf16 v[100:103], v[188:191], v[212:215], v[100:103]
	v_mfma_f32_16x16x32_bf16 v[96:99], v[196:199], v[212:215], v[96:99]
	v_mfma_f32_16x16x32_bf16 v[84:87], v[188:191], v[220:223], v[84:87]
	v_mfma_f32_16x16x32_bf16 v[80:83], v[196:199], v[220:223], v[80:83]
	v_mfma_f32_16x16x32_bf16 v[68:71], v[188:191], v[228:231], v[68:71]
	v_mfma_f32_16x16x32_bf16 v[64:67], v[196:199], v[228:231], v[64:67]
	s_setprio 0
	s_barrier
; #define PG8_STAGE(bufoff, gbase, voff) do { _Pragma("unroll") for (int _i = 0; _i < 2; ++_i) \
;         __builtin_amdgcn_global_load_lds((const unsigned*)((const char*)(gbase) + (voff)[_i]), (LAS unsigned*)(lds + (bufoff) + ldsw + _i * 8192), 16, 0, 0); } while (0)
; #define PG8_LDA(dst, b, h) do { _Pragma("unroll") for (int m = 0; m < 4; ++m) _Pragma("unroll") for (int k = 0; k < 2; ++k) dst[m][k] = *(const LAS bf16x8*)(lds + PG8_SA(b, h) + aoff + m * 2048 + k * 1024); } while (0)
; #define PG8_WAIT_V(n) asm volatile("s_waitcnt vmcnt(" #n ")" ::: "memory")
; #define PG8_WAIT_L(n) asm volatile("s_waitcnt lgkmcnt(" #n ")" ::: "memory")
; #define PG8_BAR __builtin_amdgcn_s_barrier()
; #define PG8_SCHED __builtin_amdgcn_sched_barrier(0)
;     ...
;             PG8_LDA(At, 1, 1); PG8_STAGE(PG8_SB(1, 0), b3, voffB); PG8_STAGE(PG8_SB(1, 1), b3 + hstepB, voffB); PG8_STAGE(PG8_SA(1, 0), a3, voffA);
;             PG8_WAIT_V(8); PG8_WAIT_L(0); PG8_BAR; PG8_MMA(1, 0, At, B0); PG8_MMA(1, 1, At, B1); PG8_BAR; PG8_SCHED;
	s_add_i32 s21, s21, s2
	s_add_i32 m0, s21, 0xffffff80
	ds_read_b128 v[200:203], v166 offset:49152
	ds_read_b128 v[204:207], v166 offset:50176
	ds_read_b128 v[208:211], v166 offset:51200
	ds_read_b128 v[212:215], v166 offset:52224
	ds_read_b128 v[216:219], v166 offset:53248
	ds_read_b128 v[220:223], v166 offset:54272
	ds_read_b128 v[224:227], v166 offset:55296
	ds_read_b128 v[228:231], v166 offset:56320
	global_load_lds_dwordx4 v[236:237], off offset:128
	s_add_i32 m0, s21, 0x1f80
	s_add_i32 s21, s40, s2
	global_load_lds_dwordx4 v[238:239], off offset:128
	s_add_i32 m0, s21, 0xffffff80
	s_nop 0
	global_load_lds_dwordx4 v[240:241], off offset:128
	s_add_i32 m0, s21, 0x1f80
	s_nop 0
	global_load_lds_dwordx4 v[234:235], off offset:128
	s_add_i32 m0, s30, 0xffffff80
	s_nop 0
	global_load_lds_dwordx4 v[242:243], off offset:128
	s_add_i32 m0, s31, 0xffffff80
	s_nop 0
	global_load_lds_dwordx4 v[244:245], off offset:128
	s_waitcnt vmcnt(8)
	s_waitcnt lgkmcnt(0)
	s_barrier
	s_setprio 1
	v_mfma_f32_16x16x32_bf16 v[60:63], v[168:171], v[200:203], v[60:63]
	v_mfma_f32_16x16x32_bf16 v[56:59], v[176:179], v[200:203], v[56:59]
	v_mfma_f32_16x16x32_bf16 v[44:47], v[168:171], v[208:211], v[44:47]
	v_mfma_f32_16x16x32_bf16 v[40:43], v[176:179], v[208:211], v[40:43]
	v_mfma_f32_16x16x32_bf16 v[28:31], v[168:171], v[216:219], v[28:31]
	v_mfma_f32_16x16x32_bf16 v[24:27], v[176:179], v[216:219], v[24:27]
	v_mfma_f32_16x16x32_bf16 v[12:15], v[168:171], v[224:227], v[12:15]
	v_mfma_f32_16x16x32_bf16 v[8:11], v[176:179], v[224:227], v[8:11]
	v_mfma_f32_16x16x32_bf16 v[60:63], v[172:175], v[204:207], v[60:63]
	v_mfma_f32_16x16x32_bf16 v[56:59], v[180:183], v[204:207], v[56:59]
	v_mfma_f32_16x16x32_bf16 v[44:47], v[172:175], v[212:215], v[44:47]
	v_mfma_f32_16x16x32_bf16 v[40:43], v[180:183], v[212:215], v[40:43]
	v_mfma_f32_16x16x32_bf16 v[28:31], v[172:175], v[220:223], v[28:31]
	v_mfma_f32_16x16x32_bf16 v[24:27], v[180:183], v[220:223], v[24:27]
	v_mfma_f32_16x16x32_bf16 v[12:15], v[172:175], v[228:231], v[12:15]
	v_mfma_f32_16x16x32_bf16 v[8:11], v[180:183], v[228:231], v[8:11]
	v_mfma_f32_16x16x32_bf16 v[52:55], v[184:187], v[200:203], v[52:55]
	v_mfma_f32_16x16x32_bf16 v[48:51], v[192:195], v[200:203], v[48:51]
	v_mfma_f32_16x16x32_bf16 v[36:39], v[184:187], v[208:211], v[36:39]
	v_mfma_f32_16x16x32_bf16 v[32:35], v[192:195], v[208:211], v[32:35]
	v_mfma_f32_16x16x32_bf16 v[20:23], v[184:187], v[216:219], v[20:23]
	v_mfma_f32_16x16x32_bf16 v[16:19], v[192:195], v[216:219], v[16:19]
	v_mfma_f32_16x16x32_bf16 v[4:7], v[184:187], v[224:227], v[4:7]
	v_mfma_f32_16x16x32_bf16 v[0:3], v[192:195], v[224:227], v[0:3]
	v_mfma_f32_16x16x32_bf16 v[52:55], v[188:191], v[204:207], v[52:55]
	v_mfma_f32_16x16x32_bf16 v[48:51], v[196:199], v[204:207], v[48:51]
	v_mfma_f32_16x16x32_bf16 v[36:39], v[188:191], v[212:215], v[36:39]
	v_mfma_f32_16x16x32_bf16 v[32:35], v[196:199], v[212:215], v[32:35]
	v_mfma_f32_16x16x32_bf16 v[20:23], v[188:191], v[220:223], v[20:23]
	v_mfma_f32_16x16x32_bf16 v[16:19], v[196:199], v[220:223], v[16:19]
	v_mfma_f32_16x16x32_bf16 v[4:7], v[188:191], v[228:231], v[4:7]
	v_mfma_f32_16x16x32_bf16 v[0:3], v[196:199], v[228:231], v[0:3]
	s_setprio 0
	s_barrier
	s_add_i32 s20, s20, 2
	s_add_u32 s18, s18, 0x100
	s_addc_u32 s19, s19, 0
	s_cmpk_gt_u32 s20, 0xfd
	s_cbranch_scc0 .LBB0_1148
	s_and_b64 vcc, exec, s[14:15]
	s_cbranch_vccz .LBB0_1151
	s_barrier
